# nt hint also on one-shot loads of phases 20, 23, 24, 25 (final norm, context rounds, layer-1 weight conversion)
# speedup vs baseline: 1.0051x; 1.0007x over previous
; __device__ __forceinline__ void norm_pair_load(NormPair& P, unsigned char* ws, const float* x, const float* ctx, bool first, int l, int which, int sel, int k, int lane) {
;   const float* MODS = (const float*)(ws + WS_MODS); const bf16_t* HB = (const bf16_t*)(ws + WS_HB);
;   const int i = 2 * k;
;   int b, pos; if (sel == 0) { b = i / RB; pos = i - b * RB; } else if (sel == 1) { b = i >> 11; pos = NCTX + (i & 2047); } else { b = i >> 8; pos = i & 255; }
;   const int row = b * RB + pos; P.row = row;
;     ...
;   if (first) { const float* hr = hrow_ptr(ctx, x, row);
; #pragma unroll
;     for (int j = 0; j < 4; ++j) { P.v0[j] = *(const f32x4*)(hr + lane * 4 + 256 * j); P.v1[j] = *(const f32x4*)(hr + DMODEL + lane * 4 + 256 * j); } }
;   else { const bf16_t* hr = HB + (size_t)row * 1024;
; #pragma unroll
;     for (int j = 0; j < 4; ++j) { const u32x2 w = *(const u32x2*)(hr + lane * 4 + 256 * j), w2 = *(const u32x2*)(hr + 1024 + lane * 4 + 256 * j);
;       P.v0[j] = (f32x4){bflo(w.x), bfhi(w.x), bflo(w.y), bfhi(w.y)}; P.v1[j] = (f32x4){bflo(w2.x), bfhi(w2.x), bflo(w2.y), bfhi(w2.y)}; } }
; }
; __device__ __forceinline__ void norm_rows(unsigned char* ws, const float* x, const float* ctx, bool first, int l, int which, int sel, int w0, int wstride, int lane) {
;   const int ppb = (sel == 0 ? RB : sel == 1 ? NLAT : NCTX) >> 1, wpb = wstride >> 4, b = w0 / wpb, wi = w0 - b * wpb, kb = b * ppb, n = (ppb - wi + wpb - 1) / wpb;
;   if (b >= 16 || n <= 0) return;
;   f32x4 sh[4], g[4]; const float* md_cur = nullptr;
;   NormPair A, B; norm_pair_load(A, ws, x, ctx, first, l, which, sel, kb + wi, lane);
;   for (int j = 0; j < n; j += 2) {
;     if (j + 1 < n) norm_pair_load(B, ws, x, ctx, first, l, which, sel, kb + wi + wpb * (j + 1), lane);
;     norm_pair_store(A, sh, g, md_cur, ws, lane);
;     if (j + 1 >= n) break;
;     if (j + 2 < n) norm_pair_load(A, ws, x, ctx, first, l, which, sel, kb + wi + wpb * (j + 2), lane);
;     norm_pair_store(B, sh, g, md_cur, ws, lane);
;   }
; }
; template <int ph> __device__ __forceinline__ void run_phase(const MArgs& a, unsigned char* lds, int tid, int lane, int wave, int G, int bx, int vcu) {
;     ...
;       const int gw2 = (bx - nctx) * NWAVES + wave, NGW2 = (G - nctx) * NWAVES;
;       { XcdBarrier b2; b2.bar = (unsigned*)(ws + WS_CTL) + 4096; b2.x = 0; b2.st = (volatile LAS unsigned*)(L + MISC_OFF) + 8; xcd_wait(b2); }
.LBB0_1077:
	s_or_b64 exec, exec, s[0:1]
	s_lshl_b32 s1, s33, 3
	s_addk_i32 s1, 0xfe00
	s_waitcnt lgkmcnt(0)
	s_ashr_i32 s8, s1, 4
	s_abs_i32 s4, s8
	v_cvt_f32_u32_e32 v1, s4
	s_lshl_b32 s3, s2, 3
	s_add_i32 s0, s3, s93
	s_ashr_i32 s6, s1, 31
	v_rcp_iflag_f32_e32 v1, v1
	s_sub_i32 s1, 0, s4
	s_add_i32 s5, s0, 0xfffffe00
	s_ashr_i32 s0, s5, 31
	v_mul_f32_e32 v1, 0x4f7ffffe, v1
	v_cvt_u32_f32_e32 v1, v1
	s_xor_b32 s9, s0, s6
	s_abs_i32 s0, s5
	s_waitcnt vmcnt(0)
	v_readfirstlane_b32 s7, v1
	s_mul_i32 s1, s1, s7
	s_mul_hi_u32 s1, s7, s1
	s_add_i32 s7, s7, s1
	s_mul_hi_u32 s1, s0, s7
	s_mul_i32 s10, s1, s4
	s_sub_i32 s0, s0, s10
	s_add_i32 s10, s1, 1
	s_sub_i32 s11, s0, s4
	s_cmp_ge_u32 s0, s4
	s_cselect_b32 s1, s10, s1
	s_cselect_b32 s0, s11, s0
	s_add_i32 s10, s1, 1
	s_cmp_ge_u32 s0, s4
	s_cselect_b32 s0, s10, s1
	s_xor_b32 s10, s0, s9
	s_sub_i32 s0, s10, s9
	s_mul_i32 s1, s0, s8
	s_sub_i32 s1, s5, s1
	s_sub_i32 s5, s8, s1
	s_addk_i32 s5, 0x3ff
	s_ashr_i32 s11, s5, 31
	s_abs_i32 s5, s5
	s_mul_hi_u32 s7, s5, s7
	s_xor_b32 s6, s11, s6
	s_mul_i32 s11, s7, s4
	s_sub_i32 s5, s5, s11
	s_add_i32 s11, s7, 1
	s_sub_i32 s12, s5, s4
	s_cmp_ge_u32 s5, s4
	s_cselect_b32 s7, s11, s7
	s_cselect_b32 s5, s12, s5
	s_add_i32 s11, s7, 1
	s_cmp_ge_u32 s5, s4
	s_cselect_b32 s4, s11, s7
	s_xor_b32 s4, s4, s6
	s_sub_i32 s16, s4, s6
	s_cmp_gt_i32 s0, 15
	s_cselect_b64 s[4:5], -1, 0
	s_cmp_lt_i32 s16, 1
	s_cselect_b64 s[6:7], -1, 0
	s_or_b64 s[4:5], s[4:5], s[6:7]
	s_and_b64 vcc, exec, s[4:5]
	s_barrier
	s_cbranch_vccnz .LBB0_1090
	s_lshl_b32 s0, s0, 10
	s_add_i32 s4, s1, s0
	s_add_u32 s0, s26, 0x4f00000
	s_addc_u32 s1, s27, 0
	s_lshl_b32 s5, s4, 1
	s_ashr_i32 s4, s4, 10
	s_and_b32 s5, s5, 0x7fe
	s_mul_i32 s6, s4, 0x900
	s_add_i32 s5, s5, s6
	s_add_i32 s6, s5, 0x100
	s_mul_hi_i32 s5, s4, 0x6000
	s_mulk_i32 s4, 0x6000
	s_add_u32 s4, s26, s4
	s_addc_u32 s5, s27, s5
	s_add_u32 s4, s4, 0x103000
	s_addc_u32 s5, s5, 0
	s_ashr_i32 s7, s6, 31
	s_lshl_b64 s[12:13], s[6:7], 11
	s_add_u32 s12, s0, s12
	s_addc_u32 s13, s1, s13
	v_lshlrev_b32_e32 v34, 3, v254
	global_load_dwordx2 v[2:3], v34, s[12:13] nt
	global_load_dwordx2 v[4:5], v34, s[12:13] offset:2048 nt
	global_load_dwordx2 v[6:7], v34, s[12:13] offset:512 nt
	global_load_dwordx2 v[8:9], v34, s[12:13] offset:2560 nt
	global_load_dwordx2 v[10:11], v34, s[12:13] offset:1024 nt
	global_load_dwordx2 v[12:13], v34, s[12:13] offset:3072 nt
	global_load_dwordx2 v[14:15], v34, s[12:13] offset:1536 nt
	global_load_dwordx2 v[16:17], v34, s[12:13] offset:3584 nt
	v_mbcnt_lo_u32_b32 v1, -1, 0
	v_mbcnt_hi_u32_b32 v1, -1, v1
	v_and_b32_e32 v20, 64, v1
	v_mov_b32_e32 v35, 0
	v_xor_b32_e32 v21, 1, v1
	v_add_u32_e32 v20, 64, v20
	s_add_u32 s7, s26, 0x103000
	v_xor_b32_e32 v22, 2, v1
	v_cmp_lt_i32_e32 vcc, v21, v20
	s_addc_u32 s17, s27, 0
	v_lshl_add_u64 v[40:41], s[0:1], 0, v[34:35]
	s_sub_i32 s0, s9, s10
	v_xor_b32_e32 v23, 4, v1
	v_cndmask_b32_e32 v21, v1, v21, vcc
	v_cmp_lt_i32_e32 vcc, v22, v20
	s_add_i32 s1, s0, 2
	v_lshl_add_u64 v[18:19], s[26:27], 0, v[34:35]
	v_xor_b32_e32 v24, 8, v1
	v_cndmask_b32_e32 v22, v1, v22, vcc
	v_cmp_lt_i32_e32 vcc, v23, v20
	s_mov_b64 s[12:13], 0x9700000
	s_mul_i32 s1, s8, s1
	s_add_i32 s0, s0, 1
	v_xor_b32_e32 v25, 16, v1
	v_cndmask_b32_e32 v23, v1, v23, vcc
	v_cmp_lt_i32_e32 vcc, v24, v20
	v_lshl_add_u64 v[38:39], v[18:19], 0, s[12:13]
	s_add_i32 s11, s93, s1
	s_lshl_b32 s12, s10, 10
	s_lshl_b32 s19, s8, 1
	s_lshl_b32 s28, s1, 1
	s_lshl_b32 s1, s10, 11
	s_lshl_b32 s10, s2, 4
	s_lshl_b32 s29, s8, 2
	s_mul_i32 s8, s8, s0
	v_xor_b32_e32 v26, 32, v1
	v_cndmask_b32_e32 v24, v1, v24, vcc
	v_cmp_lt_i32_e32 vcc, v25, v20
	s_add_i32 s1, s1, s10
	s_lshl_b32 s10, s93, 1
	s_add_i32 s0, s93, s8
	v_cndmask_b32_e32 v25, v1, v25, vcc
	v_cmp_lt_i32_e32 vcc, v26, v20
	s_add_i32 s11, s11, s12
	s_lshl_b32 s13, s9, 10
	s_add_i32 s1, s1, s10
	s_lshl_b32 s9, s9, 11
	s_add_i32 s0, s0, s12
	v_cndmask_b32_e32 v20, v1, v26, vcc
	s_sub_i32 s11, s11, s13
	s_sub_i32 s1, s1, s9
	s_sub_i32 s0, s0, s13
	s_mov_b32 s18, 2
	v_lshlrev_b32_e32 v36, 2, v254
	v_lshlrev_b32_e32 v1, 2, v21
	v_lshlrev_b32_e32 v37, 2, v22
	v_lshlrev_b32_e32 v51, 2, v23
	v_lshlrev_b32_e32 v110, 2, v24
	v_lshlrev_b32_e32 v111, 2, v25
	v_lshlrev_b32_e32 v112, 2, v20
	s_add_i32 s34, s11, 0xfffffe00
	s_add_i32 s35, s1, 0xfffffc00
	s_add_i32 s36, s0, 0xfffffe00
	s_lshl_b32 s30, s8, 1
	s_mov_b64 s[0:1], 0
	v_mov_b32_e32 v76, s6
	s_mov_b32 s6, 0x3a800000
	s_mov_b32 s31, 0x800000
	v_mov_b32_e32 v50, 0x358637bd
	s_waitcnt vmcnt(7)
	v_lshlrev_b32_e32 v42, 16, v2
	v_and_b32_e32 v43, 0xffff0000, v2
	v_lshlrev_b32_e32 v44, 16, v3
	v_and_b32_e32 v45, 0xffff0000, v3
	s_waitcnt vmcnt(6)
	v_lshlrev_b32_e32 v46, 16, v4
	v_and_b32_e32 v47, 0xffff0000, v4
	v_lshlrev_b32_e32 v48, 16, v5
	v_and_b32_e32 v49, 0xffff0000, v5
	s_waitcnt vmcnt(5)
	v_lshlrev_b32_e32 v52, 16, v6
	v_and_b32_e32 v53, 0xffff0000, v6
	v_lshlrev_b32_e32 v54, 16, v7
	v_and_b32_e32 v55, 0xffff0000, v7
	s_waitcnt vmcnt(4)
	v_lshlrev_b32_e32 v56, 16, v8
	v_and_b32_e32 v57, 0xffff0000, v8
	v_lshlrev_b32_e32 v58, 16, v9
	v_and_b32_e32 v59, 0xffff0000, v9
	s_waitcnt vmcnt(3)
	v_lshlrev_b32_e32 v60, 16, v10
	v_and_b32_e32 v61, 0xffff0000, v10
	v_lshlrev_b32_e32 v62, 16, v11
	v_and_b32_e32 v63, 0xffff0000, v11
	s_waitcnt vmcnt(2)
	v_lshlrev_b32_e32 v64, 16, v12
	v_and_b32_e32 v65, 0xffff0000, v12
	v_lshlrev_b32_e32 v66, 16, v13
	v_and_b32_e32 v67, 0xffff0000, v13
	s_waitcnt vmcnt(1)
	v_lshlrev_b32_e32 v68, 16, v14
	v_and_b32_e32 v69, 0xffff0000, v14
	v_lshlrev_b32_e32 v70, 16, v15
	v_and_b32_e32 v71, 0xffff0000, v15
	s_waitcnt vmcnt(0)
	v_lshlrev_b32_e32 v72, 16, v16
	v_and_b32_e32 v73, 0xffff0000, v16
	v_lshlrev_b32_e32 v74, 16, v17
	v_and_b32_e32 v75, 0xffff0000, v17
	s_branch .LBB0_1081

; __device__ __forceinline__ float bflo(unsigned u) { return __uint_as_float(u << 16); }
; __device__ __forceinline__ float bfhi(unsigned u) { return __uint_as_float(u & 0xffff0000u); }
; __device__ __forceinline__ void norm_pair_load(NormPair& P, unsigned char* ws, const float* x, const float* ctx, bool first, int l, int which, int sel, int k, int lane) {
;   const float* MODS = (const float*)(ws + WS_MODS); const bf16_t* HB = (const bf16_t*)(ws + WS_HB);
;   const int i = 2 * k;
;   int b, pos; if (sel == 0) { b = i / RB; pos = i - b * RB; } else if (sel == 1) { b = i >> 11; pos = NCTX + (i & 2047); } else { b = i >> 8; pos = i & 255; }
;   const int row = b * RB + pos; P.row = row;
;     ...
;   if (first) { const float* hr = hrow_ptr(ctx, x, row);
; #pragma unroll
;     for (int j = 0; j < 4; ++j) { P.v0[j] = *(const f32x4*)(hr + lane * 4 + 256 * j); P.v1[j] = *(const f32x4*)(hr + DMODEL + lane * 4 + 256 * j); } }
;   else { const bf16_t* hr = HB + (size_t)row * 1024;
; #pragma unroll
;     for (int j = 0; j < 4; ++j) { const u32x2 w = *(const u32x2*)(hr + lane * 4 + 256 * j), w2 = *(const u32x2*)(hr + 1024 + lane * 4 + 256 * j);
;       P.v0[j] = (f32x4){bflo(w.x), bfhi(w.x), bflo(w.y), bfhi(w.y)}; P.v1[j] = (f32x4){bflo(w2.x), bfhi(w2.x), bflo(w2.y), bfhi(w2.y)}; } }
; }
; __device__ __forceinline__ void norm_pair_store(const NormPair& P, f32x4 (&sh)[4], f32x4 (&g)[4], const float*& md_cur, unsigned char* ws, int lane) {
;   bf16_t* XN = (bf16_t*)(ws + WS_XN);
;     ...
; #pragma unroll
;     ...
;   float ss0 = 0.f, ss1 = 0.f;
; #pragma unroll
;   for (int j = 0; j < 4; ++j) { ss0 += (P.v0[j][0] * P.v0[j][0] + P.v0[j][1] * P.v0[j][1]) + (P.v0[j][2] * P.v0[j][2] + P.v0[j][3] * P.v0[j][3]); ss1 += (P.v1[j][0] * P.v1[j][0] + P.v1[j][1] * P.v1[j][1]) + (P.v1[j][2] * P.v1[j][2] + P.v1[j][3] * P.v1[j][3]); }
;   const float rs0 = rsqrtf(wave_sum64(ss0) * (1.f / 1024.f) + EPS_N), rs1 = rsqrtf(wave_sum64(ss1) * (1.f / 1024.f) + EPS_N);
.LBB0_1081:
	s_add_i32 s9, s18, -1
	s_cmp_lt_i32 s9, s16
	s_cselect_b64 s[14:15], -1, 0
	s_cmp_ge_i32 s9, s16
	s_cbranch_scc1 .LBB0_1083
	s_add_i32 s8, s3, s36
	s_add_i32 s9, s30, s35
	s_ashr_i32 s10, s8, 10
	s_and_b32 s8, s9, 0x7fe
	s_mul_i32 s9, s10, 0x900
	s_add_i32 s8, s8, s9
	s_addk_i32 s8, 0x100
	s_mul_hi_i32 s9, s10, 0x6000
	s_mulk_i32 s10, 0x6000
	s_add_u32 s10, s7, s10
	s_addc_u32 s11, s17, s9
	s_ashr_i32 s9, s8, 31
	s_lshl_b64 s[12:13], s[8:9], 11
	v_lshl_add_u64 v[78:79], v[40:41], 0, s[12:13]
	global_load_dwordx2 v[80:81], v[78:79], off nt
	global_load_dwordx2 v[84:85], v[78:79], off offset:2048 nt
	global_load_dwordx2 v[88:89], v[78:79], off offset:512 nt
	global_load_dwordx2 v[90:91], v[78:79], off offset:2560 nt
	global_load_dwordx2 v[96:97], v[78:79], off offset:1024 nt
	global_load_dwordx2 v[102:103], v[78:79], off offset:3072 nt
	global_load_dwordx2 v[104:105], v[78:79], off offset:1536 nt
	global_load_dwordx2 v[108:109], v[78:79], off offset:3584 nt
	s_waitcnt vmcnt(7)
	v_lshlrev_b32_e32 v78, 16, v80
	v_and_b32_e32 v79, 0xffff0000, v80
	v_lshlrev_b32_e32 v86, 16, v81
	v_and_b32_e32 v87, 0xffff0000, v81
	s_waitcnt vmcnt(6)
	v_lshlrev_b32_e32 v82, 16, v84
	v_and_b32_e32 v83, 0xffff0000, v84
	v_lshlrev_b32_e32 v92, 16, v85
	v_and_b32_e32 v93, 0xffff0000, v85
	s_waitcnt vmcnt(5)
	v_lshlrev_b32_e32 v80, 16, v88
	v_and_b32_e32 v81, 0xffff0000, v88
	v_lshlrev_b32_e32 v94, 16, v89
	v_and_b32_e32 v95, 0xffff0000, v89
	s_waitcnt vmcnt(4)
	v_lshlrev_b32_e32 v88, 16, v90
	v_and_b32_e32 v89, 0xffff0000, v90
	v_lshlrev_b32_e32 v98, 16, v91
	v_and_b32_e32 v99, 0xffff0000, v91
	s_waitcnt vmcnt(3)
	v_lshlrev_b32_e32 v84, 16, v96
	v_and_b32_e32 v85, 0xffff0000, v96
	v_lshlrev_b32_e32 v100, 16, v97
	v_and_b32_e32 v101, 0xffff0000, v97
	s_waitcnt vmcnt(2)
	v_lshlrev_b32_e32 v96, 16, v102
	v_and_b32_e32 v97, 0xffff0000, v102
	v_lshlrev_b32_e32 v102, 16, v103
	v_and_b32_e32 v103, 0xffff0000, v103
	s_waitcnt vmcnt(1)
	v_lshlrev_b32_e32 v90, 16, v104
	v_and_b32_e32 v91, 0xffff0000, v104
	v_lshlrev_b32_e32 v104, 16, v105
	v_and_b32_e32 v105, 0xffff0000, v105
	s_waitcnt vmcnt(0)
	v_lshlrev_b32_e32 v106, 16, v108
	v_and_b32_e32 v107, 0xffff0000, v108
	v_lshlrev_b32_e32 v108, 16, v109
	v_and_b32_e32 v109, 0xffff0000, v109
.LBB0_1083:
	s_cmp_eq_u64 s[4:5], s[0:1]
	s_cbranch_scc1 .LBB0_1085
	v_lshlrev_b32_e32 v34, 2, v36
	v_lshl_add_u64 v[2:3], s[4:5], 0, v[34:35]
	v_add_co_u32_e32 v10, vcc, 0x1000, v2
	s_nop 1
	v_addc_co_u32_e32 v11, vcc, 0, v3, vcc
	global_load_dwordx4 v[18:21], v[10:11], off nt
	global_load_dwordx4 v[22:25], v[10:11], off offset:1024 nt
	global_load_dwordx4 v[26:29], v[10:11], off offset:2048 nt
	global_load_dwordx4 v[2:5], v34, s[4:5] nt
	global_load_dwordx4 v[6:9], v34, s[4:5] offset:1024 nt
	global_load_dwordx4 v[30:33], v[10:11], off offset:3072 nt
	global_load_dwordx4 v[14:17], v34, s[4:5] offset:2048 nt
	s_nop 0
	global_load_dwordx4 v[10:13], v34, s[4:5] offset:3072 nt
	s_waitcnt vmcnt(7)
	v_pk_add_f32 v[20:21], v[20:21], 1.0 op_sel_hi:[1,0]
	v_pk_add_f32 v[18:19], v[18:19], 1.0 op_sel_hi:[1,0]
	s_waitcnt vmcnt(6)
	v_pk_add_f32 v[24:25], v[24:25], 1.0 op_sel_hi:[1,0]
	v_pk_add_f32 v[22:23], v[22:23], 1.0 op_sel_hi:[1,0]
	s_waitcnt vmcnt(5)
	v_pk_add_f32 v[28:29], v[28:29], 1.0 op_sel_hi:[1,0]
	v_pk_add_f32 v[26:27], v[26:27], 1.0 op_sel_hi:[1,0]
	s_waitcnt vmcnt(2)
	v_pk_add_f32 v[32:33], v[32:33], 1.0 op_sel_hi:[1,0]
	v_pk_add_f32 v[30:31], v[30:31], 1.0 op_sel_hi:[1,0]
.LBB0_1085:
	v_pk_mul_f32 v[114:115], v[44:45], v[44:45]
	v_pk_mul_f32 v[116:117], v[42:43], v[42:43]
	v_mul_f32_e32 v34, v60, v60
	v_pk_mov_b32 v[118:119], v[116:117], v[114:115] op_sel:[1,0]
	v_mov_b32_e32 v117, v115
	v_pk_add_f32 v[114:115], v[118:119], v[116:117]
	v_pk_mul_f32 v[116:117], v[48:49], v[48:49]
	v_pk_mul_f32 v[118:119], v[46:47], v[46:47]
	v_pk_add_f32 v[114:115], v[114:115], v[114:115] op_sel_hi:[0,1]
	v_pk_mov_b32 v[120:121], v[118:119], v[116:117] op_sel:[1,0]
	v_mov_b32_e32 v119, v117
	v_pk_add_f32 v[116:117], v[120:121], v[118:119]
	v_pk_mul_f32 v[118:119], v[54:55], v[54:55]
	v_pk_mul_f32 v[120:121], v[52:53], v[52:53]
	v_pk_add_f32 v[116:117], v[116:117], v[116:117] op_sel_hi:[0,1]
	v_pk_mov_b32 v[122:123], v[120:121], v[118:119] op_sel:[1,0]
	v_mov_b32_e32 v121, v119
	v_pk_add_f32 v[118:119], v[122:123], v[120:121]
	v_pk_mul_f32 v[120:121], v[58:59], v[58:59]
	v_pk_mul_f32 v[122:123], v[56:57], v[56:57]
	v_pk_add_f32 v[118:119], v[118:119], v[118:119] op_sel_hi:[0,1]
	v_pk_mov_b32 v[124:125], v[122:123], v[120:121] op_sel:[1,0]
	v_mov_b32_e32 v123, v121
	v_pk_add_f32 v[120:121], v[124:125], v[122:123]
	v_pk_fma_f32 v[122:123], v[60:61], v[60:61], v[34:35] op_sel_hi:[1,1,0]
	v_mul_f32_e32 v34, v62, v62
	v_pk_fma_f32 v[124:125], v[62:63], v[62:63], v[34:35] op_sel_hi:[1,1,0]
	v_mul_f32_e32 v34, v64, v64
	v_pk_fma_f32 v[126:127], v[64:65], v[64:65], v[34:35] op_sel_hi:[1,1,0]
	v_mul_f32_e32 v34, v66, v66
	v_pk_add_f32 v[120:121], v[120:121], v[120:121] op_sel_hi:[0,1]
	v_pk_fma_f32 v[128:129], v[66:67], v[66:67], v[34:35] op_sel_hi:[1,1,0]
	v_mul_f32_e32 v122, v68, v68
	v_mul_f32_e32 v124, v69, v69
	v_mul_f32_e32 v114, v70, v70
	v_mul_f32_e32 v118, v71, v71
	v_mul_f32_e32 v126, v72, v72
	v_mul_f32_e32 v128, v73, v73
	v_mul_f32_e32 v116, v74, v74
	v_mul_f32_e32 v120, v75, v75
	v_pk_add_f32 v[122:123], v[122:123], v[124:125]
	v_pk_add_f32 v[114:115], v[114:115], v[118:119]
	v_pk_add_f32 v[118:119], v[126:127], v[128:129]
	v_pk_add_f32 v[116:117], v[116:117], v[120:121]
	v_pk_add_f32 v[114:115], v[122:123], v[114:115]
	v_pk_add_f32 v[116:117], v[118:119], v[116:117]
	v_mov_b32_e32 v119, v114
	v_mov_b32_e32 v118, v116
	v_mov_b32_e32 v114, v117
	v_pk_add_f32 v[114:115], v[118:119], v[114:115]
	ds_bpermute_b32 v117, v1, v115
	ds_bpermute_b32 v116, v1, v114
	s_mov_b64 s[12:13], -1
	v_readfirstlane_b32 s9, v0
	v_readfirstlane_b32 s37, v0
	v_readfirstlane_b32 s38, v0
	s_waitcnt lgkmcnt(0)
; __device__ __forceinline__ unsigned pk2(float lo, float hi) { f32x2 v = {lo, hi}; bf16x2_t b = __builtin_convertvector(v, bf16x2_t); return __builtin_bit_cast(unsigned, b); }
; __device__ __forceinline__ void norm_pair_store(const NormPair& P, f32x4 (&sh)[4], f32x4 (&g)[4], const float*& md_cur, unsigned char* ws, int lane) {
;     ...
;   float ss0 = 0.f, ss1 = 0.f;
; #pragma unroll
;   for (int j = 0; j < 4; ++j) { ss0 += (P.v0[j][0] * P.v0[j][0] + P.v0[j][1] * P.v0[j][1]) + (P.v0[j][2] * P.v0[j][2] + P.v0[j][3] * P.v0[j][3]); ss1 += (P.v1[j][0] * P.v1[j][0] + P.v1[j][1] * P.v1[j][1]) + (P.v1[j][2] * P.v1[j][2] + P.v1[j][3] * P.v1[j][3]); }
;   const float rs0 = rsqrtf(wave_sum64(ss0) * (1.f / 1024.f) + EPS_N), rs1 = rsqrtf(wave_sum64(ss1) * (1.f / 1024.f) + EPS_N);
; #pragma unroll
;   for (int j = 0; j < 4; ++j) {
;     const f32x4 o0 = P.v0[j] * rs0 * g[j] + sh[j], o1 = P.v1[j] * rs1 * g[j] + sh[j]; u32x2 w, w2; w.x = pk2(o0[0], o0[1]); w.y = pk2(o0[2], o0[3]); w2.x = pk2(o1[0], o1[1]); w2.y = pk2(o1[2], o1[3]);
;     *(u32x2*)(XN + (size_t)P.row * 1024 + lane * 4 + 256 * j) = w; *(u32x2*)(XN + (size_t)(P.row + 1) * 1024 + lane * 4 + 256 * j) = w2; }
; __device__ __forceinline__ void norm_rows(unsigned char* ws, const float* x, const float* ctx, bool first, int l, int which, int sel, int w0, int wstride, int lane) {
;     ...
;     if (j + 2 < n) norm_pair_load(A, ws, x, ctx, first, l, which, sel, kb + wi + wpb * (j + 2), lane);
	v_pk_add_f32 v[114:115], v[114:115], v[116:117]
	ds_bpermute_b32 v117, v37, v115
	ds_bpermute_b32 v116, v37, v114
	v_readfirstlane_b32 s39, v0
	s_waitcnt lgkmcnt(0)
	v_pk_add_f32 v[114:115], v[114:115], v[116:117]
	ds_bpermute_b32 v117, v51, v115
	ds_bpermute_b32 v116, v51, v114
	s_waitcnt lgkmcnt(0)
	v_pk_add_f32 v[114:115], v[114:115], v[116:117]
	ds_bpermute_b32 v117, v110, v115
	ds_bpermute_b32 v116, v110, v114
	s_waitcnt lgkmcnt(0)
	v_pk_add_f32 v[114:115], v[114:115], v[116:117]
	ds_bpermute_b32 v117, v111, v115
	ds_bpermute_b32 v116, v111, v114
	s_waitcnt lgkmcnt(0)
	v_pk_add_f32 v[114:115], v[114:115], v[116:117]
	ds_bpermute_b32 v117, v112, v115
	ds_bpermute_b32 v116, v112, v114
	s_waitcnt lgkmcnt(0)
	v_pk_add_f32 v[114:115], v[114:115], v[116:117]
	s_nop 0
	v_pk_fma_f32 v[114:115], v[114:115], s[6:7], v[50:51] op_sel_hi:[1,0,0]
	s_nop 0
	v_mul_f32_e32 v34, 0x4b800000, v115
	v_cmp_gt_f32_e32 vcc, s31, v115
	v_mul_f32_e32 v77, 0x4b800000, v114
	v_cmp_gt_f32_e64 s[0:1], s31, v114
	v_cndmask_b32_e32 v34, v115, v34, vcc
	v_rsq_f32_e32 v34, v34
	v_cndmask_b32_e64 v77, v114, v77, s[0:1]
	v_rsq_f32_e32 v77, v77
	v_mul_f32_e32 v113, 0x45800000, v34
	v_cndmask_b32_e32 v34, v34, v113, vcc
	v_mul_f32_e32 v113, 0x45800000, v77
	v_cndmask_b32_e64 v114, v77, v113, s[0:1]
	v_pk_mul_f32 v[116:117], v[34:35], v[42:43] op_sel_hi:[0,1]
	v_pk_mul_f32 v[118:119], v[34:35], v[44:45] op_sel_hi:[0,1]
	v_pk_mul_f32 v[120:121], v[114:115], v[46:47] op_sel_hi:[0,1]
	v_pk_fma_f32 v[118:119], v[20:21], v[118:119], v[4:5]
	v_pk_fma_f32 v[116:117], v[18:19], v[116:117], v[2:3]
	v_pk_mul_f32 v[122:123], v[114:115], v[48:49] op_sel_hi:[0,1]
	v_pk_fma_f32 v[120:121], v[18:19], v[120:121], v[2:3]
	v_ashrrev_i32_e32 v77, 31, v76
	v_pk_fma_f32 v[122:123], v[20:21], v[122:123], v[4:5]
	v_cvt_pk_bf16_f32 v116, v116, v117
	v_cvt_pk_bf16_f32 v117, v118, v119
	v_cvt_pk_bf16_f32 v118, v120, v121
	v_lshlrev_b64 v[120:121], 11, v[76:77]
	v_cvt_pk_bf16_f32 v119, v122, v123
	v_lshl_add_u64 v[120:121], v[38:39], 0, v[120:121]
	global_store_dwordx2 v[120:121], v[116:117], off
	global_store_dwordx2 v[120:121], v[118:119], off offset:2048
	v_pk_mul_f32 v[116:117], v[34:35], v[52:53] op_sel_hi:[0,1]
	v_pk_mul_f32 v[118:119], v[34:35], v[54:55] op_sel_hi:[0,1]
	v_pk_mul_f32 v[122:123], v[114:115], v[56:57] op_sel_hi:[0,1]
	v_pk_mul_f32 v[124:125], v[114:115], v[58:59] op_sel_hi:[0,1]
	v_pk_fma_f32 v[118:119], v[24:25], v[118:119], v[8:9]
	v_pk_fma_f32 v[116:117], v[22:23], v[116:117], v[6:7]
	v_pk_fma_f32 v[124:125], v[24:25], v[124:125], v[8:9]
	v_pk_fma_f32 v[122:123], v[22:23], v[122:123], v[6:7]
	v_cvt_pk_bf16_f32 v116, v116, v117
	v_cvt_pk_bf16_f32 v117, v118, v119
	v_cvt_pk_bf16_f32 v118, v122, v123
	v_cvt_pk_bf16_f32 v119, v124, v125
	global_store_dwordx2 v[120:121], v[116:117], off offset:512
	global_store_dwordx2 v[120:121], v[118:119], off offset:2560
	v_pk_mul_f32 v[116:117], v[34:35], v[60:61] op_sel_hi:[0,1]
	v_pk_mul_f32 v[118:119], v[34:35], v[62:63] op_sel_hi:[0,1]
	v_pk_mul_f32 v[122:123], v[114:115], v[64:65] op_sel_hi:[0,1]
	v_pk_mul_f32 v[124:125], v[114:115], v[66:67] op_sel_hi:[0,1]
	s_waitcnt vmcnt(5)
	v_pk_fma_f32 v[118:119], v[28:29], v[118:119], v[16:17]
	v_pk_fma_f32 v[116:117], v[26:27], v[116:117], v[14:15]
	v_pk_fma_f32 v[124:125], v[28:29], v[124:125], v[16:17]
	v_pk_fma_f32 v[122:123], v[26:27], v[122:123], v[14:15]
	v_cvt_pk_bf16_f32 v116, v116, v117
	v_cvt_pk_bf16_f32 v117, v118, v119
	v_cvt_pk_bf16_f32 v118, v122, v123
	v_cvt_pk_bf16_f32 v119, v124, v125
	global_store_dwordx2 v[120:121], v[116:117], off offset:1024
	global_store_dwordx2 v[120:121], v[118:119], off offset:3072
	v_pk_mul_f32 v[116:117], v[34:35], v[68:69] op_sel_hi:[0,1]
	v_pk_mul_f32 v[118:119], v[34:35], v[70:71] op_sel_hi:[0,1]
	s_waitcnt vmcnt(6)
	v_pk_fma_f32 v[118:119], v[32:33], v[118:119], v[12:13]
	v_pk_fma_f32 v[116:117], v[30:31], v[116:117], v[10:11]
	v_pk_mul_f32 v[122:123], v[114:115], v[72:73] op_sel_hi:[0,1]
	v_pk_mul_f32 v[114:115], v[114:115], v[74:75] op_sel_hi:[0,1]
	v_pk_fma_f32 v[114:115], v[32:33], v[114:115], v[12:13]
	v_pk_fma_f32 v[122:123], v[30:31], v[122:123], v[10:11]
	v_cvt_pk_bf16_f32 v116, v116, v117
	v_cvt_pk_bf16_f32 v117, v118, v119
	s_andn2_b64 vcc, exec, s[14:15]
	v_cvt_pk_bf16_f32 v118, v122, v123
	v_cvt_pk_bf16_f32 v119, v114, v115
	global_store_dwordx2 v[120:121], v[116:117], off offset:1536
	global_store_dwordx2 v[120:121], v[118:119], off offset:3584
	s_cbranch_vccnz .LBB0_1080
	s_cmp_ge_i32 s18, s16
	s_cselect_b64 s[12:13], -1, 0
	s_and_b64 vcc, exec, s[12:13]
	s_mov_b64 s[14:15], s[4:5]
	s_cbranch_vccnz .LBB0_1088
	s_add_i32 s0, s3, s34
	s_add_i32 s1, s28, s35
	s_ashr_i32 s9, s0, 10
	s_and_b32 s0, s1, 0x7fe
	s_mul_i32 s1, s9, 0x900
	s_add_i32 s0, s0, s1
	s_addk_i32 s0, 0x100
	s_mul_hi_i32 s1, s9, 0x6000
	s_mulk_i32 s9, 0x6000
	s_add_u32 s14, s7, s9
	s_addc_u32 s15, s17, s1
	s_ashr_i32 s1, s0, 31
	s_lshl_b64 s[38:39], s[0:1], 11
	v_lshl_add_u64 v[42:43], v[40:41], 0, s[38:39]
	global_load_dwordx2 v[44:45], v[42:43], off nt
	global_load_dwordx2 v[48:49], v[42:43], off offset:2048 nt
	global_load_dwordx2 v[54:55], v[42:43], off offset:512 nt
	global_load_dwordx2 v[58:59], v[42:43], off offset:2560 nt
	global_load_dwordx2 v[62:63], v[42:43], off offset:1024 nt
	global_load_dwordx2 v[66:67], v[42:43], off offset:3072 nt
	global_load_dwordx2 v[70:71], v[42:43], off offset:1536 nt
	global_load_dwordx2 v[74:75], v[42:43], off offset:3584 nt
	v_mov_b32_e32 v76, s0
	s_waitcnt vmcnt(7)
	v_lshlrev_b32_e32 v42, 16, v44
	v_and_b32_e32 v43, 0xffff0000, v44
	v_lshlrev_b32_e32 v44, 16, v45
	v_and_b32_e32 v45, 0xffff0000, v45
	s_waitcnt vmcnt(6)
	v_lshlrev_b32_e32 v46, 16, v48
	v_and_b32_e32 v47, 0xffff0000, v48
	v_lshlrev_b32_e32 v48, 16, v49
	v_and_b32_e32 v49, 0xffff0000, v49
	s_waitcnt vmcnt(5)
	v_lshlrev_b32_e32 v52, 16, v54
	v_and_b32_e32 v53, 0xffff0000, v54
	v_lshlrev_b32_e32 v54, 16, v55
	v_and_b32_e32 v55, 0xffff0000, v55
	s_waitcnt vmcnt(4)
	v_lshlrev_b32_e32 v56, 16, v58
	v_and_b32_e32 v57, 0xffff0000, v58
	v_lshlrev_b32_e32 v58, 16, v59
	v_and_b32_e32 v59, 0xffff0000, v59
	s_waitcnt vmcnt(3)
	v_lshlrev_b32_e32 v60, 16, v62
	v_and_b32_e32 v61, 0xffff0000, v62
	v_lshlrev_b32_e32 v62, 16, v63
	v_and_b32_e32 v63, 0xffff0000, v63
	s_waitcnt vmcnt(2)
	v_lshlrev_b32_e32 v64, 16, v66
	v_and_b32_e32 v65, 0xffff0000, v66
	v_lshlrev_b32_e32 v66, 16, v67
	v_and_b32_e32 v67, 0xffff0000, v67
	s_waitcnt vmcnt(1)
	v_lshlrev_b32_e32 v68, 16, v70
	v_and_b32_e32 v69, 0xffff0000, v70
	v_lshlrev_b32_e32 v70, 16, v71
	v_and_b32_e32 v71, 0xffff0000, v71
	s_waitcnt vmcnt(0)
	v_lshlrev_b32_e32 v72, 16, v74
	v_and_b32_e32 v73, 0xffff0000, v74
	v_lshlrev_b32_e32 v74, 16, v75
	v_and_b32_e32 v75, 0xffff0000, v75
; __device__ __forceinline__ void norm_pair_store(const NormPair& P, f32x4 (&sh)[4], f32x4 (&g)[4], const float*& md_cur, unsigned char* ws, int lane) {
;     ...
; #pragma unroll
.LBB0_1088:
	s_cmp_eq_u64 s[10:11], s[4:5]
	s_cbranch_scc1 .LBB0_1079
	v_lshlrev_b32_e32 v34, 2, v36
	v_lshl_add_u64 v[2:3], s[10:11], 0, v[34:35]
	v_add_co_u32_e32 v2, vcc, 0x1000, v2
	s_mov_b64 s[4:5], s[10:11]
	s_nop 0
	v_addc_co_u32_e32 v3, vcc, 0, v3, vcc
	global_load_dwordx4 v[18:21], v[2:3], off nt
	global_load_dwordx4 v[22:25], v[2:3], off offset:1024 nt
	global_load_dwordx4 v[26:29], v[2:3], off offset:2048 nt
	global_load_dwordx4 v[30:33], v[2:3], off offset:3072 nt
	s_nop 0
	global_load_dwordx4 v[2:5], v34, s[10:11] nt
	global_load_dwordx4 v[6:9], v34, s[10:11] offset:1024 nt
	global_load_dwordx4 v[14:17], v34, s[10:11] offset:2048 nt
	global_load_dwordx4 v[10:13], v34, s[10:11] offset:3072 nt
	s_waitcnt vmcnt(7)
	v_pk_add_f32 v[20:21], v[20:21], 1.0 op_sel_hi:[1,0]
	v_pk_add_f32 v[18:19], v[18:19], 1.0 op_sel_hi:[1,0]
	s_waitcnt vmcnt(6)
	v_pk_add_f32 v[24:25], v[24:25], 1.0 op_sel_hi:[1,0]
	v_pk_add_f32 v[22:23], v[22:23], 1.0 op_sel_hi:[1,0]
	s_waitcnt vmcnt(5)
	v_pk_add_f32 v[28:29], v[28:29], 1.0 op_sel_hi:[1,0]
	v_pk_add_f32 v[26:27], v[26:27], 1.0 op_sel_hi:[1,0]
	s_waitcnt vmcnt(4)
	v_pk_add_f32 v[32:33], v[32:33], 1.0 op_sel_hi:[1,0]
	v_pk_add_f32 v[30:31], v[30:31], 1.0 op_sel_hi:[1,0]
	s_branch .LBB0_1079

; __device__ __forceinline__ void store8(bf16_t* p, const f32x4& a, const f32x4& b) { u32x4 w; w.x = pk2(a[0], a[1]); w.y = pk2(a[2], a[3]); w.z = pk2(b[0], b[1]); w.w = pk2(b[2], b[3]); *(u32x4*)p = w; }
;     __device__ __forceinline__ void operator()(const f32x4 (&acc)[2][2][4][2], const pg8::Unit& u, int wr, int wc, int fr, int fq, int buf) const {
;     ...
;             const float* hi_ = lat ? hin_l + ((size_t)bb * NLAT + (jt - 1) * 256) * DMODEL : hin_c + (size_t)bb * NCTX * DMODEL;
;             bf16_t* HB = (bf16_t*)(ws + WS_HB) + (size_t)u.pm * 256 * DMODEL; const bool first = hin_l != nullptr;
;             const float* gt = gate + (size_t)(lat ? bb : 16) * 6144;
; #pragma unroll
;             for (int bj = 0; bj < 2; ++bj) {
;                 const int c0 = u.pn * 256 + bj * 128 + wc * 32 + 8 * fq; const f32x4 g0 = *(const f32x4*)(gt + c0), g1 = *(const f32x4*)(gt + c0 + 4);
;                 if (first) { f32x4 h0[8], h1[8];
; #pragma unroll
;                     for (int q = 0; q < 8; ++q) { const size_t off = (size_t)((q >> 2) * 128 + (q & 3) * 16 + rloc0) * DMODEL + c0; h0[q] = *(const f32x4*)(hi_ + off); h1[q] = *(const f32x4*)(hi_ + off + 4); }
;                     __builtin_amdgcn_sched_barrier(0);
; #pragma unroll
;                     for (int q = 0; q < 8; ++q) { const size_t off = (size_t)((q >> 2) * 128 + (q & 3) * 16 + rloc0) * DMODEL + c0;
;                         store8(HB + off, h0[q] + g0 * acc[q >> 2][bj][q & 3][0], h1[q] + g1 * acc[q >> 2][bj][q & 3][1]); }
.LBB0_1098:
	s_lshl_b32 s3, s35, 5
	s_lshl_b32 s0, s18, 20
	s_add_u32 s0, s56, s0
	s_addc_u32 s1, s57, 0
	s_add_u32 s4, s26, s17
	s_addc_u32 s5, s27, 0
	s_add_u32 s4, s4, 0x4f00000
	s_addc_u32 s5, s5, 0
	s_cmp_lg_u64 s[52:53], 0
	s_cselect_b64 s[6:7], -1, 0
	s_add_u32 s8, s26, 0x162000
	s_addc_u32 s9, s27, 0
	s_lshl_b32 s10, s16, 8
	s_or_b32 s3, s3, s10
	s_mov_b64 s[10:11], 0
	v_lshl_add_u32 v150, v142, 3, s3
	v_ashrrev_i32_e32 v151, 31, v150
	v_lshl_add_u64 v[134:135], v[150:151], 2, s[8:9]
	global_load_dwordx4 v[130:133], v[134:135], off offset:16 nt
	s_nop 0
	global_load_dwordx4 v[134:137], v[134:135], off nt
	v_add_u32_e32 v138, s28, v1
	v_ashrrev_i32_e32 v139, 31, v138
	s_cmp_eq_u64 s[52:53], 0
	v_lshlrev_b64 v[148:149], 12, v[138:139]
	v_add_u32_e32 v144, 16, v138
	v_add_u32_e32 v142, 32, v138
	v_add_u32_e32 v140, 48, v138
	v_lshl_add_u64 v[152:153], v[150:151], 1, s[4:5]
	v_lshlrev_b64 v[146:147], 11, v[138:139]
	s_cbranch_scc1 .LBB0_1114
	v_add_u32_e32 v218, 0x80, v138
	v_add_u32_e32 v220, 0x90, v138
	v_add_u32_e32 v222, 0xa0, v138
	v_add_u32_e32 v224, 0xb0, v138
	v_ashrrev_i32_e32 v145, 31, v144
	v_ashrrev_i32_e32 v143, 31, v142
	v_ashrrev_i32_e32 v141, 31, v140
	v_ashrrev_i32_e32 v219, 31, v218
	v_ashrrev_i32_e32 v221, 31, v220
	v_ashrrev_i32_e32 v223, 31, v222
	v_ashrrev_i32_e32 v225, 31, v224
	v_lshl_add_u64 v[210:211], v[150:151], 2, s[0:1]
	v_lshlrev_b64 v[162:163], 12, v[144:145]
	v_lshlrev_b64 v[170:171], 12, v[142:143]
	v_lshlrev_b64 v[178:179], 12, v[140:141]
	v_lshlrev_b64 v[186:187], 12, v[218:219]
	v_lshlrev_b64 v[194:195], 12, v[220:221]
	v_lshlrev_b64 v[202:203], 12, v[222:223]
	v_lshlrev_b64 v[212:213], 12, v[224:225]
	v_lshl_add_u64 v[158:159], v[210:211], 0, v[148:149]
	v_lshl_add_u64 v[166:167], v[210:211], 0, v[162:163]
	v_lshl_add_u64 v[174:175], v[210:211], 0, v[170:171]
	v_lshl_add_u64 v[182:183], v[210:211], 0, v[178:179]
	v_lshl_add_u64 v[190:191], v[210:211], 0, v[186:187]
	v_lshl_add_u64 v[198:199], v[210:211], 0, v[194:195]
	v_lshl_add_u64 v[206:207], v[210:211], 0, v[202:203]
	v_lshl_add_u64 v[214:215], v[210:211], 0, v[212:213]
	global_load_dwordx4 v[154:157], v[158:159], off offset:16 nt
	s_nop 0
	global_load_dwordx4 v[158:161], v[158:159], off nt
	s_nop 0
	global_load_dwordx4 v[162:165], v[166:167], off offset:16 nt
	s_nop 0
	global_load_dwordx4 v[166:169], v[166:167], off nt
	s_nop 0
	global_load_dwordx4 v[170:173], v[174:175], off offset:16 nt
	s_nop 0
	global_load_dwordx4 v[174:177], v[174:175], off nt
	s_nop 0
	global_load_dwordx4 v[178:181], v[182:183], off offset:16 nt
	s_nop 0
	global_load_dwordx4 v[182:185], v[182:183], off nt
	s_nop 0
	global_load_dwordx4 v[186:189], v[190:191], off offset:16 nt
	s_nop 0
	global_load_dwordx4 v[190:193], v[190:191], off nt
	s_nop 0
	global_load_dwordx4 v[194:197], v[198:199], off offset:16 nt
	s_nop 0
	global_load_dwordx4 v[198:201], v[198:199], off nt
	s_nop 0
	global_load_dwordx4 v[202:205], v[206:207], off offset:16 nt
	s_nop 0
	global_load_dwordx4 v[206:209], v[206:207], off nt
	s_nop 0
	global_load_dwordx4 v[210:213], v[214:215], off offset:16 nt
	s_nop 0
	global_load_dwordx4 v[214:217], v[214:215], off nt
	s_waitcnt vmcnt(0)
	v_pk_fma_f32 v[160:161], v[128:129], v[136:137], v[160:161]
	v_pk_fma_f32 v[158:159], v[126:127], v[134:135], v[158:159]
	v_pk_fma_f32 v[228:229], v[124:125], v[132:133], v[156:157]
	v_pk_fma_f32 v[156:157], v[122:123], v[130:131], v[154:155]
	v_lshl_add_u64 v[226:227], v[152:153], 0, v[146:147]
	v_cvt_pk_bf16_f32 v154, v158, v159
	v_cvt_pk_bf16_f32 v155, v160, v161
	v_cvt_pk_bf16_f32 v156, v156, v157
	v_cvt_pk_bf16_f32 v157, v228, v229
	global_store_dwordx4 v[226:227], v[154:157], off
	v_pk_fma_f32 v[160:161], v[116:117], v[132:133], v[164:165]
	v_pk_fma_f32 v[162:163], v[114:115], v[130:131], v[162:163]
	v_lshlrev_b64 v[154:155], 11, v[144:145]
	v_lshl_add_u64 v[158:159], v[152:153], 0, v[154:155]
	v_pk_fma_f32 v[156:157], v[120:121], v[136:137], v[168:169]
	v_pk_fma_f32 v[154:155], v[118:119], v[134:135], v[166:167]
	s_nop 0
	v_cvt_pk_bf16_f32 v154, v154, v155
	v_cvt_pk_bf16_f32 v155, v156, v157
	v_cvt_pk_bf16_f32 v156, v162, v163
	v_cvt_pk_bf16_f32 v157, v160, v161
	global_store_dwordx4 v[158:159], v[154:157], off
	v_pk_fma_f32 v[160:161], v[108:109], v[132:133], v[172:173]
	v_pk_fma_f32 v[162:163], v[106:107], v[130:131], v[170:171]
	v_lshlrev_b64 v[154:155], 11, v[142:143]
	v_lshl_add_u64 v[158:159], v[152:153], 0, v[154:155]
	v_pk_fma_f32 v[156:157], v[112:113], v[136:137], v[176:177]
	v_pk_fma_f32 v[154:155], v[110:111], v[134:135], v[174:175]
	s_nop 0
	v_cvt_pk_bf16_f32 v154, v154, v155
	v_cvt_pk_bf16_f32 v155, v156, v157
	v_cvt_pk_bf16_f32 v156, v162, v163
	v_cvt_pk_bf16_f32 v157, v160, v161
	global_store_dwordx4 v[158:159], v[154:157], off
	v_pk_fma_f32 v[160:161], v[100:101], v[132:133], v[180:181]
	v_pk_fma_f32 v[162:163], v[98:99], v[130:131], v[178:179]
	v_lshlrev_b64 v[154:155], 11, v[140:141]
	v_lshl_add_u64 v[158:159], v[152:153], 0, v[154:155]
	v_pk_fma_f32 v[156:157], v[104:105], v[136:137], v[184:185]
	v_pk_fma_f32 v[154:155], v[102:103], v[134:135], v[182:183]
	s_nop 0
	v_cvt_pk_bf16_f32 v154, v154, v155
	v_cvt_pk_bf16_f32 v155, v156, v157
	v_cvt_pk_bf16_f32 v156, v162, v163
	v_cvt_pk_bf16_f32 v157, v160, v161
	global_store_dwordx4 v[158:159], v[154:157], off
	v_pk_fma_f32 v[160:161], v[92:93], v[132:133], v[188:189]
	v_pk_fma_f32 v[162:163], v[90:91], v[130:131], v[186:187]
	v_lshlrev_b64 v[154:155], 11, v[218:219]
	v_lshl_add_u64 v[158:159], v[152:153], 0, v[154:155]
	v_pk_fma_f32 v[156:157], v[96:97], v[136:137], v[192:193]
	v_pk_fma_f32 v[154:155], v[94:95], v[134:135], v[190:191]
	s_nop 0
; __device__ __forceinline__ float bflo(unsigned u) { return __uint_as_float(u << 16); }
; __device__ __forceinline__ float bfhi(unsigned u) { return __uint_as_float(u & 0xffff0000u); }
; __device__ __forceinline__ void store8(bf16_t* p, const f32x4& a, const f32x4& b) { u32x4 w; w.x = pk2(a[0], a[1]); w.y = pk2(a[2], a[3]); w.z = pk2(b[0], b[1]); w.w = pk2(b[2], b[3]); *(u32x4*)p = w; }
;     __device__ __forceinline__ void operator()(const f32x4 (&acc)[2][2][4][2], const pg8::Unit& u, int wr, int wc, int fr, int fq, int buf) const {
;     ...
;                     for (int q = 0; q < 8; ++q) { const size_t off = (size_t)((q >> 2) * 128 + (q & 3) * 16 + rloc0) * DMODEL + c0;
;                         store8(HB + off, h0[q] + g0 * acc[q >> 2][bj][q & 3][0], h1[q] + g1 * acc[q >> 2][bj][q & 3][1]); }
;                 } else { u32x4 hw[8];
; #pragma unroll
;                     for (int q = 0; q < 8; ++q) { const size_t off = (size_t)((q >> 2) * 128 + (q & 3) * 16 + rloc0) * DMODEL + c0; hw[q] = *(const u32x4*)(HB + off); }
;                     __builtin_amdgcn_sched_barrier(0);
; #pragma unroll
;                     for (int q = 0; q < 8; ++q) { const size_t off = (size_t)((q >> 2) * 128 + (q & 3) * 16 + rloc0) * DMODEL + c0;
;                         const f32x4 h0 = (f32x4){bflo(hw[q].x), bfhi(hw[q].x), bflo(hw[q].y), bfhi(hw[q].y)}, h1 = (f32x4){bflo(hw[q].z), bfhi(hw[q].z), bflo(hw[q].w), bfhi(hw[q].w)};
;                         store8(HB + off, h0 + g0 * acc[q >> 2][bj][q & 3][0], h1 + g1 * acc[q >> 2][bj][q & 3][1]); }
	v_cvt_pk_bf16_f32 v154, v154, v155
	v_cvt_pk_bf16_f32 v155, v156, v157
	v_cvt_pk_bf16_f32 v156, v162, v163
	v_cvt_pk_bf16_f32 v157, v160, v161
	global_store_dwordx4 v[158:159], v[154:157], off
	v_pk_fma_f32 v[160:161], v[84:85], v[132:133], v[196:197]
	v_pk_fma_f32 v[162:163], v[82:83], v[130:131], v[194:195]
	v_lshlrev_b64 v[154:155], 11, v[220:221]
	v_lshl_add_u64 v[158:159], v[152:153], 0, v[154:155]
	v_pk_fma_f32 v[156:157], v[88:89], v[136:137], v[200:201]
	v_pk_fma_f32 v[154:155], v[86:87], v[134:135], v[198:199]
	s_nop 0
	v_cvt_pk_bf16_f32 v154, v154, v155
	v_cvt_pk_bf16_f32 v155, v156, v157
	v_cvt_pk_bf16_f32 v156, v162, v163
	v_cvt_pk_bf16_f32 v157, v160, v161
	global_store_dwordx4 v[158:159], v[154:157], off
	v_pk_fma_f32 v[160:161], v[76:77], v[132:133], v[204:205]
	v_pk_fma_f32 v[162:163], v[74:75], v[130:131], v[202:203]
	v_lshlrev_b64 v[154:155], 11, v[222:223]
	v_lshl_add_u64 v[158:159], v[152:153], 0, v[154:155]
	v_pk_fma_f32 v[156:157], v[80:81], v[136:137], v[208:209]
	v_pk_fma_f32 v[154:155], v[78:79], v[134:135], v[206:207]
	s_nop 0
	v_cvt_pk_bf16_f32 v154, v154, v155
	v_cvt_pk_bf16_f32 v155, v156, v157
	v_cvt_pk_bf16_f32 v156, v162, v163
	v_cvt_pk_bf16_f32 v157, v160, v161
	global_store_dwordx4 v[158:159], v[154:157], off
	v_pk_fma_f32 v[160:161], v[68:69], v[132:133], v[212:213]
	v_pk_fma_f32 v[162:163], v[66:67], v[130:131], v[210:211]
	v_lshlrev_b64 v[154:155], 11, v[224:225]
	v_lshl_add_u64 v[158:159], v[152:153], 0, v[154:155]
	v_pk_fma_f32 v[156:157], v[72:73], v[136:137], v[216:217]
	v_pk_fma_f32 v[154:155], v[70:71], v[134:135], v[214:215]
	s_nop 0
	v_cvt_pk_bf16_f32 v154, v154, v155
	v_cvt_pk_bf16_f32 v155, v156, v157
	v_cvt_pk_bf16_f32 v156, v162, v163
	v_cvt_pk_bf16_f32 v157, v160, v161
	global_store_dwordx4 v[158:159], v[154:157], off
	s_andn2_b64 vcc, exec, s[10:11]
	s_cbranch_vccnz .LBB0_1101
.LBB0_1100:
	v_add_u32_e32 v170, 0x80, v138
	v_add_u32_e32 v178, 0xa0, v138
	v_ashrrev_i32_e32 v171, 31, v170
	v_ashrrev_i32_e32 v179, 31, v178
	v_lshlrev_b64 v[170:171], 11, v[170:171]
	v_lshlrev_b64 v[178:179], 11, v[178:179]
	v_ashrrev_i32_e32 v143, 31, v142
	v_lshl_add_u64 v[194:195], v[152:153], 0, v[170:171]
	v_add_u32_e32 v170, 0x90, v138
	v_lshl_add_u64 v[198:199], v[152:153], 0, v[178:179]
	v_add_u32_e32 v178, 0xb0, v138
	v_ashrrev_i32_e32 v145, 31, v144
	v_lshlrev_b64 v[162:163], 11, v[142:143]
	v_ashrrev_i32_e32 v141, 31, v140
	v_ashrrev_i32_e32 v171, 31, v170
	v_ashrrev_i32_e32 v179, 31, v178
	v_lshl_add_u64 v[186:187], v[152:153], 0, v[146:147]
	v_lshlrev_b64 v[154:155], 11, v[144:145]
	v_lshl_add_u64 v[190:191], v[152:153], 0, v[162:163]
	v_lshlrev_b64 v[162:163], 11, v[140:141]
	v_lshlrev_b64 v[170:171], 11, v[170:171]
	v_lshlrev_b64 v[178:179], 11, v[178:179]
	v_lshl_add_u64 v[188:189], v[152:153], 0, v[154:155]
	global_load_dwordx4 v[154:157], v[186:187], off nt
	global_load_dwordx4 v[158:161], v[188:189], off nt
	v_lshl_add_u64 v[192:193], v[152:153], 0, v[162:163]
	global_load_dwordx4 v[162:165], v[190:191], off nt
	global_load_dwordx4 v[166:169], v[192:193], off nt
	v_lshl_add_u64 v[196:197], v[152:153], 0, v[170:171]
	global_load_dwordx4 v[170:173], v[194:195], off nt
	global_load_dwordx4 v[174:177], v[196:197], off nt
	v_lshl_add_u64 v[152:153], v[152:153], 0, v[178:179]
	global_load_dwordx4 v[178:181], v[198:199], off nt
	global_load_dwordx4 v[182:185], v[152:153], off nt
	s_waitcnt vmcnt(0)
	v_lshlrev_b32_e32 v200, 16, v154
	v_and_b32_e32 v201, 0xffff0000, v154
	v_lshlrev_b32_e32 v154, 16, v155
	v_and_b32_e32 v155, 0xffff0000, v155
	v_lshlrev_b32_e32 v202, 16, v156
	v_and_b32_e32 v203, 0xffff0000, v156
	v_lshlrev_b32_e32 v156, 16, v157
	v_and_b32_e32 v157, 0xffff0000, v157
	v_pk_fma_f32 v[128:129], v[128:129], v[136:137], v[154:155]
	v_pk_fma_f32 v[126:127], v[126:127], v[134:135], v[200:201]
	v_pk_fma_f32 v[154:155], v[124:125], v[132:133], v[156:157]
	v_pk_fma_f32 v[124:125], v[122:123], v[130:131], v[202:203]
	v_cvt_pk_bf16_f32 v122, v126, v127
	v_cvt_pk_bf16_f32 v123, v128, v129
	v_cvt_pk_bf16_f32 v124, v124, v125
	v_cvt_pk_bf16_f32 v125, v154, v155
	global_store_dwordx4 v[186:187], v[122:125], off
	v_lshlrev_b32_e32 v126, 16, v160
	v_and_b32_e32 v127, 0xffff0000, v160
	v_lshlrev_b32_e32 v122, 16, v158
	v_and_b32_e32 v123, 0xffff0000, v158
	v_lshlrev_b32_e32 v124, 16, v159
	v_and_b32_e32 v125, 0xffff0000, v159
	v_lshlrev_b32_e32 v128, 16, v161
	v_and_b32_e32 v129, 0xffff0000, v161
	v_pk_fma_f32 v[120:121], v[120:121], v[136:137], v[124:125]
	v_pk_fma_f32 v[118:119], v[118:119], v[134:135], v[122:123]
	v_pk_fma_f32 v[122:123], v[116:117], v[132:133], v[128:129]
	v_pk_fma_f32 v[116:117], v[114:115], v[130:131], v[126:127]
	v_cvt_pk_bf16_f32 v114, v118, v119
	v_cvt_pk_bf16_f32 v115, v120, v121
	v_cvt_pk_bf16_f32 v116, v116, v117
	v_cvt_pk_bf16_f32 v117, v122, v123
	global_store_dwordx4 v[188:189], v[114:117], off
	v_lshlrev_b32_e32 v118, 16, v164
	v_and_b32_e32 v119, 0xffff0000, v164
	v_lshlrev_b32_e32 v114, 16, v162
	v_and_b32_e32 v115, 0xffff0000, v162
	v_lshlrev_b32_e32 v116, 16, v163
	v_and_b32_e32 v117, 0xffff0000, v163
	v_lshlrev_b32_e32 v120, 16, v165
	v_and_b32_e32 v121, 0xffff0000, v165
	v_pk_fma_f32 v[112:113], v[112:113], v[136:137], v[116:117]
	v_pk_fma_f32 v[110:111], v[110:111], v[134:135], v[114:115]
	v_pk_fma_f32 v[114:115], v[108:109], v[132:133], v[120:121]
	v_pk_fma_f32 v[108:109], v[106:107], v[130:131], v[118:119]
	v_cvt_pk_bf16_f32 v106, v110, v111
	v_cvt_pk_bf16_f32 v107, v112, v113
	v_cvt_pk_bf16_f32 v108, v108, v109
	v_cvt_pk_bf16_f32 v109, v114, v115
	global_store_dwordx4 v[190:191], v[106:109], off
	v_lshlrev_b32_e32 v110, 16, v168
	v_and_b32_e32 v111, 0xffff0000, v168
; __device__ __forceinline__ float bflo(unsigned u) { return __uint_as_float(u << 16); }
; __device__ __forceinline__ float bfhi(unsigned u) { return __uint_as_float(u & 0xffff0000u); }
; __device__ __forceinline__ void store8(bf16_t* p, const f32x4& a, const f32x4& b) { u32x4 w; w.x = pk2(a[0], a[1]); w.y = pk2(a[2], a[3]); w.z = pk2(b[0], b[1]); w.w = pk2(b[2], b[3]); *(u32x4*)p = w; }
;     __device__ __forceinline__ void operator()(const f32x4 (&acc)[2][2][4][2], const pg8::Unit& u, int wr, int wc, int fr, int fq, int buf) const {
;     ...
;             for (int bj = 0; bj < 2; ++bj) {
;                 const int c0 = u.pn * 256 + bj * 128 + wc * 32 + 8 * fq; const f32x4 g0 = *(const f32x4*)(gt + c0), g1 = *(const f32x4*)(gt + c0 + 4);
;                 if (first) { f32x4 h0[8], h1[8];
; #pragma unroll
;                     for (int q = 0; q < 8; ++q) { const size_t off = (size_t)((q >> 2) * 128 + (q & 3) * 16 + rloc0) * DMODEL + c0; h0[q] = *(const f32x4*)(hi_ + off); h1[q] = *(const f32x4*)(hi_ + off + 4); }
;                     __builtin_amdgcn_sched_barrier(0);
; #pragma unroll
;                     for (int q = 0; q < 8; ++q) { const size_t off = (size_t)((q >> 2) * 128 + (q & 3) * 16 + rloc0) * DMODEL + c0;
;                         store8(HB + off, h0[q] + g0 * acc[q >> 2][bj][q & 3][0], h1[q] + g1 * acc[q >> 2][bj][q & 3][1]); }
;                 } else { u32x4 hw[8];
; #pragma unroll
;                     for (int q = 0; q < 8; ++q) { const size_t off = (size_t)((q >> 2) * 128 + (q & 3) * 16 + rloc0) * DMODEL + c0; hw[q] = *(const u32x4*)(HB + off); }
;                     __builtin_amdgcn_sched_barrier(0);
; #pragma unroll
;                     for (int q = 0; q < 8; ++q) { const size_t off = (size_t)((q >> 2) * 128 + (q & 3) * 16 + rloc0) * DMODEL + c0;
;                         const f32x4 h0 = (f32x4){bflo(hw[q].x), bfhi(hw[q].x), bflo(hw[q].y), bfhi(hw[q].y)}, h1 = (f32x4){bflo(hw[q].z), bfhi(hw[q].z), bflo(hw[q].w), bfhi(hw[q].w)};
;                         store8(HB + off, h0 + g0 * acc[q >> 2][bj][q & 3][0], h1 + g1 * acc[q >> 2][bj][q & 3][1]); }
	v_lshlrev_b32_e32 v106, 16, v166
	v_and_b32_e32 v107, 0xffff0000, v166
	v_lshlrev_b32_e32 v108, 16, v167
	v_and_b32_e32 v109, 0xffff0000, v167
	v_lshlrev_b32_e32 v112, 16, v169
	v_and_b32_e32 v113, 0xffff0000, v169
	v_pk_fma_f32 v[104:105], v[104:105], v[136:137], v[108:109]
	v_pk_fma_f32 v[102:103], v[102:103], v[134:135], v[106:107]
	v_pk_fma_f32 v[106:107], v[100:101], v[132:133], v[112:113]
	v_pk_fma_f32 v[100:101], v[98:99], v[130:131], v[110:111]
	v_cvt_pk_bf16_f32 v98, v102, v103
	v_cvt_pk_bf16_f32 v99, v104, v105
	v_cvt_pk_bf16_f32 v100, v100, v101
	v_cvt_pk_bf16_f32 v101, v106, v107
	global_store_dwordx4 v[192:193], v[98:101], off
	v_lshlrev_b32_e32 v102, 16, v172
	v_and_b32_e32 v103, 0xffff0000, v172
	v_lshlrev_b32_e32 v98, 16, v170
	v_and_b32_e32 v99, 0xffff0000, v170
	v_lshlrev_b32_e32 v100, 16, v171
	v_and_b32_e32 v101, 0xffff0000, v171
	v_lshlrev_b32_e32 v104, 16, v173
	v_and_b32_e32 v105, 0xffff0000, v173
	v_pk_fma_f32 v[96:97], v[96:97], v[136:137], v[100:101]
	v_pk_fma_f32 v[94:95], v[94:95], v[134:135], v[98:99]
	v_pk_fma_f32 v[98:99], v[92:93], v[132:133], v[104:105]
	v_pk_fma_f32 v[92:93], v[90:91], v[130:131], v[102:103]
	v_cvt_pk_bf16_f32 v90, v94, v95
	v_cvt_pk_bf16_f32 v91, v96, v97
	v_cvt_pk_bf16_f32 v92, v92, v93
	v_cvt_pk_bf16_f32 v93, v98, v99
	global_store_dwordx4 v[194:195], v[90:93], off
	v_lshlrev_b32_e32 v94, 16, v176
	v_and_b32_e32 v95, 0xffff0000, v176
	v_lshlrev_b32_e32 v90, 16, v174
	v_and_b32_e32 v91, 0xffff0000, v174
	v_lshlrev_b32_e32 v92, 16, v175
	v_and_b32_e32 v93, 0xffff0000, v175
	v_lshlrev_b32_e32 v96, 16, v177
	v_and_b32_e32 v97, 0xffff0000, v177
	v_pk_fma_f32 v[88:89], v[88:89], v[136:137], v[92:93]
	v_pk_fma_f32 v[86:87], v[86:87], v[134:135], v[90:91]
	v_pk_fma_f32 v[90:91], v[84:85], v[132:133], v[96:97]
	v_pk_fma_f32 v[84:85], v[82:83], v[130:131], v[94:95]
	v_cvt_pk_bf16_f32 v82, v86, v87
	v_cvt_pk_bf16_f32 v83, v88, v89
	v_cvt_pk_bf16_f32 v84, v84, v85
	v_cvt_pk_bf16_f32 v85, v90, v91
	global_store_dwordx4 v[196:197], v[82:85], off
	v_lshlrev_b32_e32 v86, 16, v180
	v_and_b32_e32 v87, 0xffff0000, v180
	v_lshlrev_b32_e32 v82, 16, v178
	v_and_b32_e32 v83, 0xffff0000, v178
	v_lshlrev_b32_e32 v84, 16, v179
	v_and_b32_e32 v85, 0xffff0000, v179
	v_lshlrev_b32_e32 v88, 16, v181
	v_and_b32_e32 v89, 0xffff0000, v181
	v_pk_fma_f32 v[80:81], v[80:81], v[136:137], v[84:85]
	v_pk_fma_f32 v[78:79], v[78:79], v[134:135], v[82:83]
	v_pk_fma_f32 v[82:83], v[76:77], v[132:133], v[88:89]
	v_pk_fma_f32 v[76:77], v[74:75], v[130:131], v[86:87]
	v_cvt_pk_bf16_f32 v74, v78, v79
	v_cvt_pk_bf16_f32 v75, v80, v81
	v_cvt_pk_bf16_f32 v76, v76, v77
	v_cvt_pk_bf16_f32 v77, v82, v83
	global_store_dwordx4 v[198:199], v[74:77], off
	v_lshlrev_b32_e32 v78, 16, v184
	v_and_b32_e32 v79, 0xffff0000, v184
	v_lshlrev_b32_e32 v74, 16, v182
	v_and_b32_e32 v75, 0xffff0000, v182
	v_lshlrev_b32_e32 v76, 16, v183
	v_and_b32_e32 v77, 0xffff0000, v183
	v_lshlrev_b32_e32 v80, 16, v185
	v_and_b32_e32 v81, 0xffff0000, v185
	v_pk_fma_f32 v[72:73], v[72:73], v[136:137], v[76:77]
	v_pk_fma_f32 v[70:71], v[70:71], v[134:135], v[74:75]
	v_pk_fma_f32 v[74:75], v[68:69], v[132:133], v[80:81]
	v_pk_fma_f32 v[68:69], v[66:67], v[130:131], v[78:79]
	v_cvt_pk_bf16_f32 v66, v70, v71
	v_cvt_pk_bf16_f32 v67, v72, v73
	v_cvt_pk_bf16_f32 v68, v68, v69
	v_cvt_pk_bf16_f32 v69, v74, v75
	global_store_dwordx4 v[152:153], v[66:69], off
.LBB0_1101:
	v_add_u32_e32 v76, 0x80, v150
	v_ashrrev_i32_e32 v77, 31, v76
	v_lshl_add_u64 v[74:75], v[76:77], 2, s[8:9]
	global_load_dwordx4 v[66:69], v[74:75], off offset:16 nt
	global_load_dwordx4 v[70:73], v[74:75], off nt
	s_andn2_b64 vcc, exec, s[6:7]
	v_lshl_add_u64 v[74:75], v[76:77], 1, s[4:5]
	s_cbranch_vccnz .LBB0_1115
	s_waitcnt vmcnt(0)
	v_lshl_add_u64 v[132:133], v[76:77], 2, s[0:1]
	v_lshl_add_u64 v[84:85], v[132:133], 0, v[148:149]
	v_ashrrev_i32_e32 v145, 31, v144
	global_load_dwordx4 v[76:79], v[84:85], off offset:16 nt
	global_load_dwordx4 v[80:83], v[84:85], off nt
	v_lshlrev_b64 v[84:85], 12, v[144:145]
	v_lshl_add_u64 v[92:93], v[132:133], 0, v[84:85]
	v_ashrrev_i32_e32 v143, 31, v142
	global_load_dwordx4 v[84:87], v[92:93], off offset:16 nt
	global_load_dwordx4 v[88:91], v[92:93], off nt
	v_lshlrev_b64 v[92:93], 12, v[142:143]
	v_lshl_add_u64 v[100:101], v[132:133], 0, v[92:93]
	v_ashrrev_i32_e32 v141, 31, v140
	global_load_dwordx4 v[92:95], v[100:101], off offset:16 nt
	global_load_dwordx4 v[96:99], v[100:101], off nt
	v_lshlrev_b64 v[100:101], 12, v[140:141]
	v_add_u32_e32 v136, 0x80, v138
	v_add_u32_e32 v152, 0x90, v138
	v_add_u32_e32 v154, 0xa0, v138
	v_add_u32_e32 v156, 0xb0, v138
	v_lshl_add_u64 v[108:109], v[132:133], 0, v[100:101]
	v_ashrrev_i32_e32 v137, 31, v136
	v_ashrrev_i32_e32 v153, 31, v152
	v_ashrrev_i32_e32 v155, 31, v154
	v_ashrrev_i32_e32 v157, 31, v156
	global_load_dwordx4 v[100:103], v[108:109], off offset:16 nt
	global_load_dwordx4 v[104:107], v[108:109], off nt
	v_lshlrev_b64 v[108:109], 12, v[136:137]
	v_lshlrev_b64 v[116:117], 12, v[152:153]
	v_lshlrev_b64 v[124:125], 12, v[154:155]
	v_lshlrev_b64 v[134:135], 12, v[156:157]
	v_lshl_add_u64 v[112:113], v[132:133], 0, v[108:109]
	v_lshl_add_u64 v[120:121], v[132:133], 0, v[116:117]
	v_lshl_add_u64 v[128:129], v[132:133], 0, v[124:125]
	v_lshl_add_u64 v[148:149], v[132:133], 0, v[134:135]
	global_load_dwordx4 v[108:111], v[112:113], off offset:16 nt
	s_nop 0
	global_load_dwordx4 v[112:115], v[112:113], off nt
	s_nop 0
	global_load_dwordx4 v[116:119], v[120:121], off offset:16 nt
	s_nop 0
	global_load_dwordx4 v[120:123], v[120:121], off nt
	s_nop 0
	global_load_dwordx4 v[124:127], v[128:129], off offset:16 nt
	s_nop 0
	global_load_dwordx4 v[128:131], v[128:129], off nt
	s_nop 0
	global_load_dwordx4 v[132:135], v[148:149], off offset:16 nt
	s_nop 0
	global_load_dwordx4 v[148:151], v[148:149], off nt
	s_waitcnt vmcnt(14)
; __device__ __forceinline__ void store8(bf16_t* p, const f32x4& a, const f32x4& b) { u32x4 w; w.x = pk2(a[0], a[1]); w.y = pk2(a[2], a[3]); w.z = pk2(b[0], b[1]); w.w = pk2(b[2], b[3]); *(u32x4*)p = w; }
;     __device__ __forceinline__ void operator()(const f32x4 (&acc)[2][2][4][2], const pg8::Unit& u, int wr, int wc, int fr, int fq, int buf) const {
;     ...
;                     for (int q = 0; q < 8; ++q) { const size_t off = (size_t)((q >> 2) * 128 + (q & 3) * 16 + rloc0) * DMODEL + c0;
;                         store8(HB + off, h0[q] + g0 * acc[q >> 2][bj][q & 3][0], h1[q] + g1 * acc[q >> 2][bj][q & 3][1]); }
	v_pk_fma_f32 v[82:83], v[64:65], v[72:73], v[82:83]
	v_pk_fma_f32 v[80:81], v[62:63], v[70:71], v[80:81]
	v_pk_fma_f32 v[160:161], v[60:61], v[68:69], v[78:79]
	v_pk_fma_f32 v[78:79], v[58:59], v[66:67], v[76:77]
	v_lshl_add_u64 v[158:159], v[74:75], 0, v[146:147]
	v_cvt_pk_bf16_f32 v76, v80, v81
	v_cvt_pk_bf16_f32 v77, v82, v83
	v_cvt_pk_bf16_f32 v78, v78, v79
	v_cvt_pk_bf16_f32 v79, v160, v161
	global_store_dwordx4 v[158:159], v[76:79], off
	s_waitcnt vmcnt(14)
	v_pk_fma_f32 v[82:83], v[52:53], v[68:69], v[86:87]
	v_pk_fma_f32 v[84:85], v[50:51], v[66:67], v[84:85]
	v_lshlrev_b64 v[76:77], 11, v[144:145]
	v_lshl_add_u64 v[80:81], v[74:75], 0, v[76:77]
	s_waitcnt vmcnt(13)
	v_pk_fma_f32 v[78:79], v[56:57], v[72:73], v[90:91]
	v_pk_fma_f32 v[76:77], v[54:55], v[70:71], v[88:89]
	s_nop 0
	v_cvt_pk_bf16_f32 v76, v76, v77
	v_cvt_pk_bf16_f32 v77, v78, v79
	v_cvt_pk_bf16_f32 v78, v84, v85
	v_cvt_pk_bf16_f32 v79, v82, v83
	global_store_dwordx4 v[80:81], v[76:79], off
	s_waitcnt vmcnt(13)
	v_pk_fma_f32 v[82:83], v[44:45], v[68:69], v[94:95]
	v_pk_fma_f32 v[84:85], v[42:43], v[66:67], v[92:93]
	v_lshlrev_b64 v[76:77], 11, v[142:143]
	v_lshl_add_u64 v[80:81], v[74:75], 0, v[76:77]
	s_waitcnt vmcnt(12)
	v_pk_fma_f32 v[78:79], v[48:49], v[72:73], v[98:99]
	v_pk_fma_f32 v[76:77], v[46:47], v[70:71], v[96:97]
	s_nop 0
	v_cvt_pk_bf16_f32 v76, v76, v77
	v_cvt_pk_bf16_f32 v77, v78, v79
	v_cvt_pk_bf16_f32 v78, v84, v85
	v_cvt_pk_bf16_f32 v79, v82, v83
	global_store_dwordx4 v[80:81], v[76:79], off
	s_waitcnt vmcnt(12)
	v_pk_fma_f32 v[82:83], v[36:37], v[68:69], v[102:103]
	v_pk_fma_f32 v[84:85], v[34:35], v[66:67], v[100:101]
	v_lshlrev_b64 v[76:77], 11, v[140:141]
	v_lshl_add_u64 v[80:81], v[74:75], 0, v[76:77]
	s_waitcnt vmcnt(11)
	v_pk_fma_f32 v[78:79], v[40:41], v[72:73], v[106:107]
	v_pk_fma_f32 v[76:77], v[38:39], v[70:71], v[104:105]
	s_nop 0
	v_cvt_pk_bf16_f32 v76, v76, v77
	v_cvt_pk_bf16_f32 v77, v78, v79
	v_cvt_pk_bf16_f32 v78, v84, v85
	v_cvt_pk_bf16_f32 v79, v82, v83
	global_store_dwordx4 v[80:81], v[76:79], off
	s_waitcnt vmcnt(11)
	v_pk_fma_f32 v[82:83], v[28:29], v[68:69], v[110:111]
	v_pk_fma_f32 v[84:85], v[26:27], v[66:67], v[108:109]
	v_lshlrev_b64 v[76:77], 11, v[136:137]
	v_lshl_add_u64 v[80:81], v[74:75], 0, v[76:77]
	s_waitcnt vmcnt(10)
	v_pk_fma_f32 v[78:79], v[32:33], v[72:73], v[114:115]
	v_pk_fma_f32 v[76:77], v[30:31], v[70:71], v[112:113]
	s_nop 0
	v_cvt_pk_bf16_f32 v76, v76, v77
	v_cvt_pk_bf16_f32 v77, v78, v79
	v_cvt_pk_bf16_f32 v78, v84, v85
	v_cvt_pk_bf16_f32 v79, v82, v83
	global_store_dwordx4 v[80:81], v[76:79], off
	s_waitcnt vmcnt(10)
	v_pk_fma_f32 v[82:83], v[20:21], v[68:69], v[118:119]
	v_pk_fma_f32 v[84:85], v[18:19], v[66:67], v[116:117]
	v_lshlrev_b64 v[76:77], 11, v[152:153]
	v_lshl_add_u64 v[80:81], v[74:75], 0, v[76:77]
	s_waitcnt vmcnt(9)
	v_pk_fma_f32 v[78:79], v[24:25], v[72:73], v[122:123]
	v_pk_fma_f32 v[76:77], v[22:23], v[70:71], v[120:121]
	s_nop 0
	v_cvt_pk_bf16_f32 v76, v76, v77
	v_cvt_pk_bf16_f32 v77, v78, v79
	v_cvt_pk_bf16_f32 v78, v84, v85
	v_cvt_pk_bf16_f32 v79, v82, v83
	global_store_dwordx4 v[80:81], v[76:79], off
	s_waitcnt vmcnt(9)
	v_pk_fma_f32 v[82:83], v[12:13], v[68:69], v[126:127]
	v_pk_fma_f32 v[84:85], v[10:11], v[66:67], v[124:125]
	v_lshlrev_b64 v[76:77], 11, v[154:155]
	v_lshl_add_u64 v[80:81], v[74:75], 0, v[76:77]
	s_waitcnt vmcnt(8)
	v_pk_fma_f32 v[78:79], v[16:17], v[72:73], v[130:131]
	v_pk_fma_f32 v[76:77], v[14:15], v[70:71], v[128:129]
	s_nop 0
	v_cvt_pk_bf16_f32 v76, v76, v77
	v_cvt_pk_bf16_f32 v77, v78, v79
	v_cvt_pk_bf16_f32 v78, v84, v85
	v_cvt_pk_bf16_f32 v79, v82, v83
	global_store_dwordx4 v[80:81], v[76:79], off
	s_waitcnt vmcnt(8)
	v_pk_fma_f32 v[82:83], v[4:5], v[68:69], v[134:135]
	v_pk_fma_f32 v[84:85], v[2:3], v[66:67], v[132:133]
	v_lshlrev_b64 v[76:77], 11, v[156:157]
	v_lshl_add_u64 v[80:81], v[74:75], 0, v[76:77]
	s_waitcnt vmcnt(7)
	v_pk_fma_f32 v[78:79], v[8:9], v[72:73], v[150:151]
	v_pk_fma_f32 v[76:77], v[6:7], v[70:71], v[148:149]
	s_nop 0
	v_cvt_pk_bf16_f32 v76, v76, v77
	v_cvt_pk_bf16_f32 v77, v78, v79
	v_cvt_pk_bf16_f32 v78, v84, v85
	v_cvt_pk_bf16_f32 v79, v82, v83
	global_store_dwordx4 v[80:81], v[76:79], off
	s_cbranch_execnz .LBB0_1104
; __device__ __forceinline__ float bflo(unsigned u) { return __uint_as_float(u << 16); }
; __device__ __forceinline__ float bfhi(unsigned u) { return __uint_as_float(u & 0xffff0000u); }
; __device__ __forceinline__ void store8(bf16_t* p, const f32x4& a, const f32x4& b) { u32x4 w; w.x = pk2(a[0], a[1]); w.y = pk2(a[2], a[3]); w.z = pk2(b[0], b[1]); w.w = pk2(b[2], b[3]); *(u32x4*)p = w; }
;     __device__ __forceinline__ void operator()(const f32x4 (&acc)[2][2][4][2], const pg8::Unit& u, int wr, int wc, int fr, int fq, int buf) const {
;     ...
;                 } else { u32x4 hw[8];
; #pragma unroll
;                     for (int q = 0; q < 8; ++q) { const size_t off = (size_t)((q >> 2) * 128 + (q & 3) * 16 + rloc0) * DMODEL + c0; hw[q] = *(const u32x4*)(HB + off); }
;                     __builtin_amdgcn_sched_barrier(0);
; #pragma unroll
;                     for (int q = 0; q < 8; ++q) { const size_t off = (size_t)((q >> 2) * 128 + (q & 3) * 16 + rloc0) * DMODEL + c0;
;                         const f32x4 h0 = (f32x4){bflo(hw[q].x), bfhi(hw[q].x), bflo(hw[q].y), bfhi(hw[q].y)}, h1 = (f32x4){bflo(hw[q].z), bfhi(hw[q].z), bflo(hw[q].w), bfhi(hw[q].w)};
;                         store8(HB + off, h0 + g0 * acc[q >> 2][bj][q & 3][0], h1 + g1 * acc[q >> 2][bj][q & 3][1]); }
.LBB0_1103:
	v_add_u32_e32 v92, 0x80, v138
	v_add_u32_e32 v100, 0xa0, v138
	v_ashrrev_i32_e32 v93, 31, v92
	v_ashrrev_i32_e32 v101, 31, v100
	v_lshlrev_b64 v[92:93], 11, v[92:93]
	v_lshlrev_b64 v[100:101], 11, v[100:101]
	v_ashrrev_i32_e32 v143, 31, v142
	v_lshl_add_u64 v[116:117], v[74:75], 0, v[92:93]
	v_add_u32_e32 v92, 0x90, v138
	v_lshl_add_u64 v[120:121], v[74:75], 0, v[100:101]
	v_add_u32_e32 v100, 0xb0, v138
	v_ashrrev_i32_e32 v145, 31, v144
	v_lshlrev_b64 v[84:85], 11, v[142:143]
	v_ashrrev_i32_e32 v141, 31, v140
	v_ashrrev_i32_e32 v93, 31, v92
	v_ashrrev_i32_e32 v101, 31, v100
	v_lshl_add_u64 v[108:109], v[74:75], 0, v[146:147]
	v_lshlrev_b64 v[76:77], 11, v[144:145]
	v_lshl_add_u64 v[112:113], v[74:75], 0, v[84:85]
	v_lshlrev_b64 v[84:85], 11, v[140:141]
	v_lshlrev_b64 v[92:93], 11, v[92:93]
	v_lshlrev_b64 v[100:101], 11, v[100:101]
	v_lshl_add_u64 v[110:111], v[74:75], 0, v[76:77]
	global_load_dwordx4 v[76:79], v[108:109], off nt
	global_load_dwordx4 v[80:83], v[110:111], off nt
	v_lshl_add_u64 v[114:115], v[74:75], 0, v[84:85]
	global_load_dwordx4 v[84:87], v[112:113], off nt
	global_load_dwordx4 v[88:91], v[114:115], off nt
	v_lshl_add_u64 v[118:119], v[74:75], 0, v[92:93]
	global_load_dwordx4 v[92:95], v[116:117], off nt
	global_load_dwordx4 v[96:99], v[118:119], off nt
	v_lshl_add_u64 v[74:75], v[74:75], 0, v[100:101]
	global_load_dwordx4 v[100:103], v[120:121], off nt
	global_load_dwordx4 v[104:107], v[74:75], off nt
	s_waitcnt vmcnt(0)
	v_lshlrev_b32_e32 v122, 16, v76
	v_and_b32_e32 v123, 0xffff0000, v76
	v_lshlrev_b32_e32 v76, 16, v77
	v_and_b32_e32 v77, 0xffff0000, v77
	v_lshlrev_b32_e32 v124, 16, v78
	v_and_b32_e32 v125, 0xffff0000, v78
	v_lshlrev_b32_e32 v78, 16, v79
	v_and_b32_e32 v79, 0xffff0000, v79
	v_pk_fma_f32 v[64:65], v[64:65], v[72:73], v[76:77]
	v_pk_fma_f32 v[62:63], v[62:63], v[70:71], v[122:123]
	v_pk_fma_f32 v[76:77], v[60:61], v[68:69], v[78:79]
	v_pk_fma_f32 v[60:61], v[58:59], v[66:67], v[124:125]
	v_cvt_pk_bf16_f32 v58, v62, v63
	v_cvt_pk_bf16_f32 v59, v64, v65
	v_cvt_pk_bf16_f32 v60, v60, v61
	v_cvt_pk_bf16_f32 v61, v76, v77
	global_store_dwordx4 v[108:109], v[58:61], off
	v_lshlrev_b32_e32 v62, 16, v82
	v_and_b32_e32 v63, 0xffff0000, v82
	v_lshlrev_b32_e32 v58, 16, v80
	v_and_b32_e32 v59, 0xffff0000, v80
	v_lshlrev_b32_e32 v60, 16, v81
	v_and_b32_e32 v61, 0xffff0000, v81
	v_lshlrev_b32_e32 v64, 16, v83
	v_and_b32_e32 v65, 0xffff0000, v83
	v_pk_fma_f32 v[56:57], v[56:57], v[72:73], v[60:61]
	v_pk_fma_f32 v[54:55], v[54:55], v[70:71], v[58:59]
	v_pk_fma_f32 v[58:59], v[52:53], v[68:69], v[64:65]
	v_pk_fma_f32 v[52:53], v[50:51], v[66:67], v[62:63]
	v_cvt_pk_bf16_f32 v50, v54, v55
	v_cvt_pk_bf16_f32 v51, v56, v57
	v_cvt_pk_bf16_f32 v52, v52, v53
	v_cvt_pk_bf16_f32 v53, v58, v59
	global_store_dwordx4 v[110:111], v[50:53], off
	v_lshlrev_b32_e32 v54, 16, v86
	v_and_b32_e32 v55, 0xffff0000, v86
	v_lshlrev_b32_e32 v50, 16, v84
	v_and_b32_e32 v51, 0xffff0000, v84
	v_lshlrev_b32_e32 v52, 16, v85
	v_and_b32_e32 v53, 0xffff0000, v85
	v_lshlrev_b32_e32 v56, 16, v87
	v_and_b32_e32 v57, 0xffff0000, v87
	v_pk_fma_f32 v[48:49], v[48:49], v[72:73], v[52:53]
	v_pk_fma_f32 v[46:47], v[46:47], v[70:71], v[50:51]
	v_pk_fma_f32 v[50:51], v[44:45], v[68:69], v[56:57]
	v_pk_fma_f32 v[44:45], v[42:43], v[66:67], v[54:55]
	v_cvt_pk_bf16_f32 v42, v46, v47
	v_cvt_pk_bf16_f32 v43, v48, v49
	v_cvt_pk_bf16_f32 v44, v44, v45
	v_cvt_pk_bf16_f32 v45, v50, v51
	global_store_dwordx4 v[112:113], v[42:45], off
	v_lshlrev_b32_e32 v46, 16, v90
	v_and_b32_e32 v47, 0xffff0000, v90
	v_lshlrev_b32_e32 v42, 16, v88
	v_and_b32_e32 v43, 0xffff0000, v88
	v_lshlrev_b32_e32 v44, 16, v89
	v_and_b32_e32 v45, 0xffff0000, v89
	v_lshlrev_b32_e32 v48, 16, v91
	v_and_b32_e32 v49, 0xffff0000, v91
	v_pk_fma_f32 v[40:41], v[40:41], v[72:73], v[44:45]
	v_pk_fma_f32 v[38:39], v[38:39], v[70:71], v[42:43]
	v_pk_fma_f32 v[42:43], v[36:37], v[68:69], v[48:49]
	v_pk_fma_f32 v[36:37], v[34:35], v[66:67], v[46:47]
	v_cvt_pk_bf16_f32 v34, v38, v39
	v_cvt_pk_bf16_f32 v35, v40, v41
	v_cvt_pk_bf16_f32 v36, v36, v37
	v_cvt_pk_bf16_f32 v37, v42, v43
	global_store_dwordx4 v[114:115], v[34:37], off
	v_lshlrev_b32_e32 v38, 16, v94
	v_and_b32_e32 v39, 0xffff0000, v94
	v_lshlrev_b32_e32 v34, 16, v92
	v_and_b32_e32 v35, 0xffff0000, v92
	v_lshlrev_b32_e32 v36, 16, v93
	v_and_b32_e32 v37, 0xffff0000, v93
	v_lshlrev_b32_e32 v40, 16, v95
	v_and_b32_e32 v41, 0xffff0000, v95
	v_pk_fma_f32 v[32:33], v[32:33], v[72:73], v[36:37]
	v_pk_fma_f32 v[30:31], v[30:31], v[70:71], v[34:35]
	v_pk_fma_f32 v[34:35], v[28:29], v[68:69], v[40:41]
	v_pk_fma_f32 v[28:29], v[26:27], v[66:67], v[38:39]
	v_cvt_pk_bf16_f32 v26, v30, v31
	v_cvt_pk_bf16_f32 v27, v32, v33
	v_cvt_pk_bf16_f32 v28, v28, v29
	v_cvt_pk_bf16_f32 v29, v34, v35
	global_store_dwordx4 v[116:117], v[26:29], off
	v_lshlrev_b32_e32 v30, 16, v98
	v_and_b32_e32 v31, 0xffff0000, v98
	v_lshlrev_b32_e32 v26, 16, v96
	v_and_b32_e32 v27, 0xffff0000, v96
	v_lshlrev_b32_e32 v28, 16, v97
	v_and_b32_e32 v29, 0xffff0000, v97
	v_lshlrev_b32_e32 v32, 16, v99
	v_and_b32_e32 v33, 0xffff0000, v99
	v_pk_fma_f32 v[24:25], v[24:25], v[72:73], v[28:29]
	v_pk_fma_f32 v[22:23], v[22:23], v[70:71], v[26:27]
	v_pk_fma_f32 v[26:27], v[20:21], v[68:69], v[32:33]
	v_pk_fma_f32 v[20:21], v[18:19], v[66:67], v[30:31]
	v_cvt_pk_bf16_f32 v18, v22, v23
	v_cvt_pk_bf16_f32 v19, v24, v25
	v_cvt_pk_bf16_f32 v20, v20, v21
	v_cvt_pk_bf16_f32 v21, v26, v27
	global_store_dwordx4 v[118:119], v[18:21], off
	v_lshlrev_b32_e32 v22, 16, v102
	v_and_b32_e32 v23, 0xffff0000, v102
	v_lshlrev_b32_e32 v18, 16, v100
	v_and_b32_e32 v19, 0xffff0000, v100
	v_lshlrev_b32_e32 v20, 16, v101
	v_and_b32_e32 v21, 0xffff0000, v101
	v_lshlrev_b32_e32 v24, 16, v103
	v_and_b32_e32 v25, 0xffff0000, v103
	v_pk_fma_f32 v[16:17], v[16:17], v[72:73], v[20:21]
	v_pk_fma_f32 v[14:15], v[14:15], v[70:71], v[18:19]
	v_pk_fma_f32 v[18:19], v[12:13], v[68:69], v[24:25]
	v_pk_fma_f32 v[12:13], v[10:11], v[66:67], v[22:23]
	v_cvt_pk_bf16_f32 v10, v14, v15
	v_cvt_pk_bf16_f32 v11, v16, v17
	v_cvt_pk_bf16_f32 v12, v12, v13
	v_cvt_pk_bf16_f32 v13, v18, v19
	global_store_dwordx4 v[120:121], v[10:13], off
	v_lshlrev_b32_e32 v14, 16, v106
	v_and_b32_e32 v15, 0xffff0000, v106
	v_lshlrev_b32_e32 v10, 16, v104
	v_and_b32_e32 v11, 0xffff0000, v104
	v_lshlrev_b32_e32 v12, 16, v105
	v_and_b32_e32 v13, 0xffff0000, v105
	v_lshlrev_b32_e32 v16, 16, v107
	v_and_b32_e32 v17, 0xffff0000, v107
	v_pk_fma_f32 v[8:9], v[8:9], v[72:73], v[12:13]
	v_pk_fma_f32 v[6:7], v[6:7], v[70:71], v[10:11]
	v_pk_fma_f32 v[10:11], v[4:5], v[68:69], v[16:17]
	v_pk_fma_f32 v[4:5], v[2:3], v[66:67], v[14:15]
	v_cvt_pk_bf16_f32 v2, v6, v7
	v_cvt_pk_bf16_f32 v3, v8, v9
	v_cvt_pk_bf16_f32 v4, v4, v5
	v_cvt_pk_bf16_f32 v5, v10, v11
	global_store_dwordx4 v[74:75], v[2:5], off

; __device__ __forceinline__ float bflo(unsigned u) { return __uint_as_float(u << 16); }
; __device__ __forceinline__ void norm_pair_load(NormPair& P, unsigned char* ws, const float* x, const float* ctx, bool first, int l, int which, int sel, int k, int lane) {
;   const float* MODS = (const float*)(ws + WS_MODS); const bf16_t* HB = (const bf16_t*)(ws + WS_HB);
;   const int i = 2 * k;
;   int b, pos; if (sel == 0) { b = i / RB; pos = i - b * RB; } else if (sel == 1) { b = i >> 11; pos = NCTX + (i & 2047); } else { b = i >> 8; pos = i & 255; }
;   const int row = b * RB + pos; P.row = row;
;     ...
;   if (first) { const float* hr = hrow_ptr(ctx, x, row);
; #pragma unroll
;     for (int j = 0; j < 4; ++j) { P.v0[j] = *(const f32x4*)(hr + lane * 4 + 256 * j); P.v1[j] = *(const f32x4*)(hr + DMODEL + lane * 4 + 256 * j); } }
;   else { const bf16_t* hr = HB + (size_t)row * 1024;
; #pragma unroll
;     for (int j = 0; j < 4; ++j) { const u32x2 w = *(const u32x2*)(hr + lane * 4 + 256 * j), w2 = *(const u32x2*)(hr + 1024 + lane * 4 + 256 * j);
;       P.v0[j] = (f32x4){bflo(w.x), bfhi(w.x), bflo(w.y), bfhi(w.y)}; P.v1[j] = (f32x4){bflo(w2.x), bfhi(w2.x), bflo(w2.y), bfhi(w2.y)}; } }
; }
; __device__ __forceinline__ void norm_rows(unsigned char* ws, const float* x, const float* ctx, bool first, int l, int which, int sel, int w0, int wstride, int lane) {
;   const int ppb = (sel == 0 ? RB : sel == 1 ? NLAT : NCTX) >> 1, wpb = wstride >> 4, b = w0 / wpb, wi = w0 - b * wpb, kb = b * ppb, n = (ppb - wi + wpb - 1) / wpb;
;   if (b >= 16 || n <= 0) return;
;   f32x4 sh[4], g[4]; const float* md_cur = nullptr;
;   NormPair A, B; norm_pair_load(A, ws, x, ctx, first, l, which, sel, kb + wi, lane);
;   for (int j = 0; j < n; j += 2) {
;     if (j + 1 < n) norm_pair_load(B, ws, x, ctx, first, l, which, sel, kb + wi + wpb * (j + 1), lane);
;     norm_pair_store(A, sh, g, md_cur, ws, lane);
;     if (j + 1 >= n) break;
;     if (j + 2 < n) norm_pair_load(A, ws, x, ctx, first, l, which, sel, kb + wi + wpb * (j + 2), lane);
;     norm_pair_store(B, sh, g, md_cur, ws, lane);
;   }
; }
; template <int ph> __device__ __forceinline__ void run_phase(const MArgs& a, unsigned char* lds, int tid, int lane, int wave, int G, int bx, int vcu) {
;     ...
;   } else if (ph == 24 || ph == 26) {
;     norm_rows(ws, x, ctx, false, ph == 24 ? 0 : 1, ph == 24 ? 1 : 0, 2, gw, NGW, lane);
.LBB0_1172:
	s_cmp_gt_i32 s94, 24
	s_cselect_b64 s[0:1], -1, 0
	s_cmp_lt_i32 s95, 25
	s_cselect_b64 s[4:5], -1, 0
	s_or_b64 s[0:1], s[0:1], s[4:5]
	s_and_b64 vcc, exec, s[0:1]
	s_cbranch_vccnz .LBB0_1236
	s_waitcnt lgkmcnt(0)
	s_ashr_i32 s8, s33, 1
	s_abs_i32 s4, s8
	v_cvt_f32_u32_e32 v1, s4
	s_lshl_b32 s3, s92, 3
	s_add_i32 s1, s3, s93
	s_ashr_i32 s5, s33, 31
	v_rcp_iflag_f32_e32 v1, v1
	s_ashr_i32 s0, s1, 31
	s_sub_i32 s7, 0, s4
	s_xor_b32 s9, s0, s5
	v_mul_f32_e32 v1, 0x4f7ffffe, v1
	v_cvt_u32_f32_e32 v1, v1
	s_abs_i32 s6, s1
	v_readfirstlane_b32 s0, v1
	s_mul_i32 s7, s7, s0
	s_mul_hi_u32 s7, s0, s7
	s_add_i32 s7, s0, s7
	s_mul_hi_u32 s0, s6, s7
	s_mul_i32 s10, s0, s4
	s_sub_i32 s6, s6, s10
	s_add_i32 s11, s0, 1
	s_sub_i32 s10, s6, s4
	s_cmp_ge_u32 s6, s4
	s_cselect_b32 s0, s11, s0
	s_cselect_b32 s6, s10, s6
	s_add_i32 s10, s0, 1
	s_cmp_ge_u32 s6, s4
	s_cselect_b32 s0, s10, s0
	s_xor_b32 s10, s0, s9
	s_sub_i32 s0, s10, s9
	s_mul_i32 s6, s0, s8
	s_sub_i32 s1, s1, s6
	s_sub_i32 s6, s8, s1
	s_addk_i32 s6, 0x7f
	s_ashr_i32 s11, s6, 31
	s_abs_i32 s6, s6
	s_mul_hi_u32 s7, s6, s7
	s_xor_b32 s5, s11, s5
	s_mul_i32 s11, s7, s4
	s_sub_i32 s6, s6, s11
	s_add_i32 s11, s7, 1
	s_sub_i32 s12, s6, s4
	s_cmp_ge_u32 s6, s4
	s_cselect_b32 s7, s11, s7
	s_cselect_b32 s6, s12, s6
	s_add_i32 s11, s7, 1
	s_cmp_ge_u32 s6, s4
	s_cselect_b32 s4, s11, s7
	s_xor_b32 s4, s4, s5
	s_sub_i32 s14, s4, s5
	s_cmp_gt_i32 s0, 15
	s_cselect_b64 s[4:5], -1, 0
	s_cmp_lt_i32 s14, 1
	s_cselect_b64 s[6:7], -1, 0
	s_or_b64 s[4:5], s[4:5], s[6:7]
	s_and_b64 vcc, exec, s[4:5]
	s_cbranch_vccnz .LBB0_1186
	s_lshl_b32 s0, s0, 7
	s_add_i32 s4, s1, s0
	s_add_u32 s0, s26, 0x4f00000
	s_addc_u32 s1, s27, 0
	s_lshl_b32 s5, s4, 1
	s_lshr_b32 s4, s4, 7
	s_and_b32 s5, s5, 0xfe
	s_mulk_i32 s4, 0x900
	s_or_b32 s6, s4, s5
	s_add_u32 s4, s26, 0x163000
	s_addc_u32 s5, s27, 0
	s_ashr_i32 s7, s6, 31
	s_lshl_b64 s[12:13], s[6:7], 11
	s_add_u32 s12, s0, s12
	s_addc_u32 s13, s1, s13
	v_lshlrev_b32_e32 v34, 3, v254
	global_load_dwordx2 v[2:3], v34, s[12:13] nt
	global_load_dwordx2 v[4:5], v34, s[12:13] offset:2048 nt
	global_load_dwordx2 v[6:7], v34, s[12:13] offset:512 nt
	global_load_dwordx2 v[8:9], v34, s[12:13] offset:2560 nt
	global_load_dwordx2 v[10:11], v34, s[12:13] offset:1024 nt
	global_load_dwordx2 v[12:13], v34, s[12:13] offset:3072 nt
	global_load_dwordx2 v[14:15], v34, s[12:13] offset:1536 nt
	global_load_dwordx2 v[16:17], v34, s[12:13] offset:3584 nt
	v_mbcnt_lo_u32_b32 v1, -1, 0
	v_mbcnt_hi_u32_b32 v1, -1, v1
	v_and_b32_e32 v19, 64, v1
	v_xor_b32_e32 v21, 1, v1
	v_add_u32_e32 v19, 64, v19
	v_mov_b32_e32 v35, 0
	v_xor_b32_e32 v24, 2, v1
	v_cmp_lt_i32_e32 vcc, v21, v19
	s_mov_b64 s[12:13], 0x9700000
	v_lshl_add_u64 v[22:23], s[26:27], 0, v[34:35]
	v_xor_b32_e32 v25, 4, v1
	v_cndmask_b32_e32 v21, v1, v21, vcc
	v_cmp_lt_i32_e32 vcc, v24, v19
	v_xor_b32_e32 v26, 8, v1
	v_lshl_add_u64 v[36:37], v[22:23], 0, s[12:13]
	v_cndmask_b32_e32 v22, v1, v24, vcc
	v_cmp_lt_i32_e32 vcc, v25, v19
	v_xor_b32_e32 v27, 16, v1
	v_xor_b32_e32 v28, 32, v1
	v_cndmask_b32_e32 v23, v1, v25, vcc
	v_cmp_lt_i32_e32 vcc, v26, v19
	v_lshlrev_b32_e32 v20, 4, v254
	s_mov_b64 s[12:13], 0x164000
	v_cndmask_b32_e32 v24, v1, v26, vcc
	v_cmp_lt_i32_e32 vcc, v27, v19
	v_lshl_add_u64 v[48:49], s[0:1], 0, v[34:35]
	s_sub_i32 s0, s9, s10
	v_cndmask_b32_e32 v25, v1, v27, vcc
	v_cmp_lt_i32_e32 vcc, v28, v19
	s_add_i32 s1, s0, 2
	s_mul_i32 s1, s8, s1
	v_cndmask_b32_e32 v19, v1, v28, vcc
	v_lshlrev_b32_e32 v1, 2, v21
	v_mov_b32_e32 v21, v35
	v_lshl_add_u64 v[38:39], s[4:5], 0, v[20:21]
	s_add_i32 s0, s0, 1
	s_add_i32 s11, s93, s1
	s_lshl_b32 s15, s8, 1
	s_lshl_b32 s16, s1, 1
	s_lshl_b32 s1, s10, 8
	s_lshl_b32 s17, s8, 2
	s_mul_i32 s8, s8, s0
	s_add_i32 s0, s93, s8
	v_lshlrev_b32_e32 v18, 2, v254
	s_mov_b32 s7, 2
	v_lshlrev_b32_e32 v67, 2, v22
	v_lshlrev_b32_e32 v118, 2, v23
	v_lshlrev_b32_e32 v119, 2, v24
	v_lshlrev_b32_e32 v120, 2, v25
	v_lshlrev_b32_e32 v121, 2, v19
	s_lshl_b32 s18, s8, 1
	v_mov_b32_e32 v84, s6
	s_mov_b32 s6, 0x3a800000
	s_mov_b32 s19, 0x800000
	v_lshlrev_b32_e32 v34, 2, v18
	v_mov_b32_e32 v66, 0x358637bd
	s_waitcnt vmcnt(0)
	v_lshlrev_b32_e32 v50, 16, v2
	v_and_b32_e32 v51, 0xffff0000, v2
	v_lshlrev_b32_e32 v52, 16, v3
	v_and_b32_e32 v53, 0xffff0000, v3
	v_lshl_add_u64 v[2:3], s[26:27], 0, v[20:21]
	v_lshl_add_u64 v[40:41], v[2:3], 0, s[12:13]
	s_mov_b64 s[12:13], 0x1400
	v_lshl_add_u64 v[42:43], v[38:39], 0, s[12:13]
	s_mov_b64 s[12:13], 0x1800
	v_lshl_add_u64 v[44:45], v[38:39], 0, s[12:13]
	s_mov_b64 s[12:13], 0x1c00
	v_lshl_add_u64 v[46:47], v[38:39], 0, s[12:13]
	s_lshl_b32 s12, s10, 7
	s_lshl_b32 s10, s92, 4
	s_add_i32 s1, s1, s10
	s_lshl_b32 s10, s93, 1
	s_add_i32 s11, s11, s12
	s_lshl_b32 s13, s9, 7
	s_add_i32 s1, s1, s10
	s_lshl_b32 s9, s9, 8
	s_add_i32 s0, s0, s12
	v_lshlrev_b32_e32 v54, 16, v4
	v_and_b32_e32 v55, 0xffff0000, v4
	v_lshlrev_b32_e32 v56, 16, v5
	v_and_b32_e32 v57, 0xffff0000, v5
	v_lshlrev_b32_e32 v58, 16, v6
	v_and_b32_e32 v59, 0xffff0000, v6
	v_lshlrev_b32_e32 v60, 16, v7
	v_and_b32_e32 v61, 0xffff0000, v7
	v_lshlrev_b32_e32 v62, 16, v8
	v_and_b32_e32 v63, 0xffff0000, v8
	v_lshlrev_b32_e32 v64, 16, v9
	v_and_b32_e32 v65, 0xffff0000, v9
	v_lshlrev_b32_e32 v68, 16, v10
	v_and_b32_e32 v69, 0xffff0000, v10
	v_lshlrev_b32_e32 v70, 16, v11
	v_and_b32_e32 v71, 0xffff0000, v11
	v_lshlrev_b32_e32 v72, 16, v12
	v_and_b32_e32 v73, 0xffff0000, v12
	v_lshlrev_b32_e32 v74, 16, v13
	v_and_b32_e32 v75, 0xffff0000, v13
	v_lshlrev_b32_e32 v76, 16, v14
	v_and_b32_e32 v77, 0xffff0000, v14
	v_lshlrev_b32_e32 v78, 16, v15
	v_and_b32_e32 v79, 0xffff0000, v15
	v_lshlrev_b32_e32 v80, 16, v16
	v_and_b32_e32 v81, 0xffff0000, v16
	v_lshlrev_b32_e32 v82, 16, v17
	v_and_b32_e32 v83, 0xffff0000, v17
	s_sub_i32 s28, s11, s13
	s_sub_i32 s29, s1, s9
	s_sub_i32 s30, s0, s13
	s_mov_b64 s[0:1], 0
	s_branch .LBB0_1177

; __device__ __forceinline__ float bflo(unsigned u) { return __uint_as_float(u << 16); }
; __device__ __forceinline__ float bfhi(unsigned u) { return __uint_as_float(u & 0xffff0000u); }
; __device__ __forceinline__ void norm_pair_load(NormPair& P, unsigned char* ws, const float* x, const float* ctx, bool first, int l, int which, int sel, int k, int lane) {
;   const float* MODS = (const float*)(ws + WS_MODS); const bf16_t* HB = (const bf16_t*)(ws + WS_HB);
;   const int i = 2 * k;
;   int b, pos; if (sel == 0) { b = i / RB; pos = i - b * RB; } else if (sel == 1) { b = i >> 11; pos = NCTX + (i & 2047); } else { b = i >> 8; pos = i & 255; }
;   const int row = b * RB + pos; P.row = row;
;     ...
;   if (first) { const float* hr = hrow_ptr(ctx, x, row);
; #pragma unroll
;     for (int j = 0; j < 4; ++j) { P.v0[j] = *(const f32x4*)(hr + lane * 4 + 256 * j); P.v1[j] = *(const f32x4*)(hr + DMODEL + lane * 4 + 256 * j); } }
;   else { const bf16_t* hr = HB + (size_t)row * 1024;
; #pragma unroll
;     for (int j = 0; j < 4; ++j) { const u32x2 w = *(const u32x2*)(hr + lane * 4 + 256 * j), w2 = *(const u32x2*)(hr + 1024 + lane * 4 + 256 * j);
;       P.v0[j] = (f32x4){bflo(w.x), bfhi(w.x), bflo(w.y), bfhi(w.y)}; P.v1[j] = (f32x4){bflo(w2.x), bfhi(w2.x), bflo(w2.y), bfhi(w2.y)}; } }
; }
; __device__ __forceinline__ void norm_pair_store(const NormPair& P, f32x4 (&sh)[4], f32x4 (&g)[4], const float*& md_cur, unsigned char* ws, int lane) {
;   bf16_t* XN = (bf16_t*)(ws + WS_XN);
;     ...
; #pragma unroll
;     ...
;   float ss0 = 0.f, ss1 = 0.f;
; #pragma unroll
;   for (int j = 0; j < 4; ++j) { ss0 += (P.v0[j][0] * P.v0[j][0] + P.v0[j][1] * P.v0[j][1]) + (P.v0[j][2] * P.v0[j][2] + P.v0[j][3] * P.v0[j][3]); ss1 += (P.v1[j][0] * P.v1[j][0] + P.v1[j][1] * P.v1[j][1]) + (P.v1[j][2] * P.v1[j][2] + P.v1[j][3] * P.v1[j][3]); }
;   const float rs0 = rsqrtf(wave_sum64(ss0) * (1.f / 1024.f) + EPS_N), rs1 = rsqrtf(wave_sum64(ss1) * (1.f / 1024.f) + EPS_N);
.LBB0_1177:
	s_add_i32 s9, s7, -1
	s_cmp_lt_i32 s9, s14
	s_cselect_b64 s[12:13], -1, 0
	s_cmp_ge_i32 s9, s14
	s_cbranch_scc1 .LBB0_1179
	s_add_i32 s8, s3, s30
	s_add_i32 s9, s18, s29
	s_lshr_b32 s8, s8, 7
	s_and_b32 s9, s9, 0xfe
	s_mulk_i32 s8, 0x900
	s_or_b32 s8, s8, s9
	s_ashr_i32 s9, s8, 31
	s_lshl_b64 s[10:11], s[8:9], 11
	v_lshl_add_u64 v[86:87], v[48:49], 0, s[10:11]
	global_load_dwordx2 v[88:89], v[86:87], off nt
	global_load_dwordx2 v[92:93], v[86:87], off offset:2048 nt
	global_load_dwordx2 v[96:97], v[86:87], off offset:512 nt
	global_load_dwordx2 v[98:99], v[86:87], off offset:2560 nt
	global_load_dwordx2 v[104:105], v[86:87], off offset:1024 nt
	global_load_dwordx2 v[110:111], v[86:87], off offset:3072 nt
	global_load_dwordx2 v[112:113], v[86:87], off offset:1536 nt
	global_load_dwordx2 v[116:117], v[86:87], off offset:3584 nt
	s_waitcnt vmcnt(7)
	v_lshlrev_b32_e32 v86, 16, v88
	v_and_b32_e32 v87, 0xffff0000, v88
	v_lshlrev_b32_e32 v94, 16, v89
	v_and_b32_e32 v95, 0xffff0000, v89
	s_waitcnt vmcnt(6)
	v_lshlrev_b32_e32 v90, 16, v92
	v_and_b32_e32 v91, 0xffff0000, v92
	v_lshlrev_b32_e32 v100, 16, v93
	v_and_b32_e32 v101, 0xffff0000, v93
	s_waitcnt vmcnt(5)
	v_lshlrev_b32_e32 v88, 16, v96
	v_and_b32_e32 v89, 0xffff0000, v96
	v_lshlrev_b32_e32 v102, 16, v97
	v_and_b32_e32 v103, 0xffff0000, v97
	s_waitcnt vmcnt(4)
	v_lshlrev_b32_e32 v96, 16, v98
	v_and_b32_e32 v97, 0xffff0000, v98
	v_lshlrev_b32_e32 v106, 16, v99
	v_and_b32_e32 v107, 0xffff0000, v99
	s_waitcnt vmcnt(3)
	v_lshlrev_b32_e32 v92, 16, v104
	v_and_b32_e32 v93, 0xffff0000, v104
	v_lshlrev_b32_e32 v108, 16, v105
	v_and_b32_e32 v109, 0xffff0000, v105
	s_waitcnt vmcnt(2)
	v_lshlrev_b32_e32 v104, 16, v110
	v_and_b32_e32 v105, 0xffff0000, v110
	v_lshlrev_b32_e32 v110, 16, v111
	v_and_b32_e32 v111, 0xffff0000, v111
	s_waitcnt vmcnt(1)
	v_lshlrev_b32_e32 v98, 16, v112
	v_and_b32_e32 v99, 0xffff0000, v112
	v_lshlrev_b32_e32 v112, 16, v113
	v_and_b32_e32 v113, 0xffff0000, v113
	s_waitcnt vmcnt(0)
	v_lshlrev_b32_e32 v114, 16, v116
	v_and_b32_e32 v115, 0xffff0000, v116
	v_lshlrev_b32_e32 v116, 16, v117
	v_and_b32_e32 v117, 0xffff0000, v117
.LBB0_1179:
	s_cmp_eq_u64 s[4:5], s[0:1]
	s_cbranch_scc1 .LBB0_1181
	global_load_dwordx4 v[18:21], v[40:41], off nt
	global_load_dwordx4 v[22:25], v[42:43], off nt
	global_load_dwordx4 v[26:29], v[44:45], off nt
	global_load_dwordx4 v[2:5], v[38:39], off nt
	global_load_dwordx4 v[6:9], v[38:39], off offset:1024 nt
	global_load_dwordx4 v[30:33], v[46:47], off nt
	global_load_dwordx4 v[14:17], v[38:39], off offset:2048 nt
	global_load_dwordx4 v[10:13], v[38:39], off offset:3072 nt
	s_waitcnt vmcnt(7)
	v_pk_add_f32 v[20:21], v[20:21], 1.0 op_sel_hi:[1,0]
	v_pk_add_f32 v[18:19], v[18:19], 1.0 op_sel_hi:[1,0]
	s_waitcnt vmcnt(6)
	v_pk_add_f32 v[24:25], v[24:25], 1.0 op_sel_hi:[1,0]
	v_pk_add_f32 v[22:23], v[22:23], 1.0 op_sel_hi:[1,0]
	s_waitcnt vmcnt(5)
	v_pk_add_f32 v[28:29], v[28:29], 1.0 op_sel_hi:[1,0]
	v_pk_add_f32 v[26:27], v[26:27], 1.0 op_sel_hi:[1,0]
	s_waitcnt vmcnt(2)
	v_pk_add_f32 v[32:33], v[32:33], 1.0 op_sel_hi:[1,0]
	v_pk_add_f32 v[30:31], v[30:31], 1.0 op_sel_hi:[1,0]
.LBB0_1181:
	v_pk_mul_f32 v[122:123], v[52:53], v[52:53]
	v_pk_mul_f32 v[124:125], v[50:51], v[50:51]
	s_mov_b64 s[10:11], -1
	v_pk_mov_b32 v[126:127], v[124:125], v[122:123] op_sel:[1,0]
	v_mov_b32_e32 v125, v123
	v_pk_add_f32 v[122:123], v[126:127], v[124:125]
	v_pk_mul_f32 v[124:125], v[56:57], v[56:57]
	v_pk_mul_f32 v[126:127], v[54:55], v[54:55]
	v_pk_add_f32 v[122:123], v[122:123], v[122:123] op_sel_hi:[0,1]
	v_pk_mov_b32 v[128:129], v[126:127], v[124:125] op_sel:[1,0]
	v_mov_b32_e32 v127, v125
	v_pk_add_f32 v[124:125], v[128:129], v[126:127]
	v_pk_mul_f32 v[126:127], v[60:61], v[60:61]
	v_pk_mul_f32 v[128:129], v[58:59], v[58:59]
	v_mul_f32_e32 v122, v68, v68
	v_pk_mov_b32 v[130:131], v[128:129], v[126:127] op_sel:[1,0]
	v_mov_b32_e32 v129, v127
	v_pk_add_f32 v[126:127], v[130:131], v[128:129]
	v_pk_mul_f32 v[128:129], v[64:65], v[64:65]
	v_pk_mul_f32 v[130:131], v[62:63], v[62:63]
	v_pk_add_f32 v[124:125], v[124:125], v[124:125] op_sel_hi:[0,1]
	v_pk_mov_b32 v[132:133], v[130:131], v[128:129] op_sel:[1,0]
	v_mov_b32_e32 v131, v129
	v_pk_add_f32 v[128:129], v[132:133], v[130:131]
	v_pk_fma_f32 v[130:131], v[68:69], v[68:69], v[122:123] op_sel_hi:[1,1,0]
	v_mul_f32_e32 v122, v70, v70
	v_pk_fma_f32 v[132:133], v[70:71], v[70:71], v[122:123] op_sel_hi:[1,1,0]
	v_mul_f32_e32 v122, v72, v72
	v_pk_fma_f32 v[134:135], v[72:73], v[72:73], v[122:123] op_sel_hi:[1,1,0]
	v_mul_f32_e32 v122, v74, v74
	v_pk_add_f32 v[126:127], v[126:127], v[126:127] op_sel_hi:[0,1]
	v_pk_add_f32 v[128:129], v[128:129], v[128:129] op_sel_hi:[0,1]
	v_pk_fma_f32 v[136:137], v[74:75], v[74:75], v[122:123] op_sel_hi:[1,1,0]
	v_mul_f32_e32 v130, v76, v76
	v_mul_f32_e32 v132, v77, v77
	v_mul_f32_e32 v122, v78, v78
	v_mul_f32_e32 v126, v79, v79
	v_mul_f32_e32 v134, v80, v80
	v_mul_f32_e32 v136, v81, v81
	v_mul_f32_e32 v124, v82, v82
	v_mul_f32_e32 v128, v83, v83
	v_pk_add_f32 v[130:131], v[130:131], v[132:133]
	v_pk_add_f32 v[122:123], v[122:123], v[126:127]
	v_pk_add_f32 v[126:127], v[134:135], v[136:137]
	v_pk_add_f32 v[124:125], v[124:125], v[128:129]
	v_pk_add_f32 v[122:123], v[130:131], v[122:123]
	v_pk_add_f32 v[124:125], v[126:127], v[124:125]
	v_mov_b32_e32 v127, v122
	v_mov_b32_e32 v126, v124
	v_mov_b32_e32 v122, v125
	v_pk_add_f32 v[122:123], v[126:127], v[122:123]
	ds_bpermute_b32 v125, v1, v123
	ds_bpermute_b32 v124, v1, v122
	v_readfirstlane_b32 s9, v0
	v_readfirstlane_b32 s31, v0
	v_readfirstlane_b32 s34, v0
	s_waitcnt lgkmcnt(0)
; __device__ __forceinline__ unsigned pk2(float lo, float hi) { f32x2 v = {lo, hi}; bf16x2_t b = __builtin_convertvector(v, bf16x2_t); return __builtin_bit_cast(unsigned, b); }
; __device__ __forceinline__ void norm_pair_store(const NormPair& P, f32x4 (&sh)[4], f32x4 (&g)[4], const float*& md_cur, unsigned char* ws, int lane) {
;     ...
;   float ss0 = 0.f, ss1 = 0.f;
; #pragma unroll
;   for (int j = 0; j < 4; ++j) { ss0 += (P.v0[j][0] * P.v0[j][0] + P.v0[j][1] * P.v0[j][1]) + (P.v0[j][2] * P.v0[j][2] + P.v0[j][3] * P.v0[j][3]); ss1 += (P.v1[j][0] * P.v1[j][0] + P.v1[j][1] * P.v1[j][1]) + (P.v1[j][2] * P.v1[j][2] + P.v1[j][3] * P.v1[j][3]); }
;   const float rs0 = rsqrtf(wave_sum64(ss0) * (1.f / 1024.f) + EPS_N), rs1 = rsqrtf(wave_sum64(ss1) * (1.f / 1024.f) + EPS_N);
; #pragma unroll
;   for (int j = 0; j < 4; ++j) {
;     const f32x4 o0 = P.v0[j] * rs0 * g[j] + sh[j], o1 = P.v1[j] * rs1 * g[j] + sh[j]; u32x2 w, w2; w.x = pk2(o0[0], o0[1]); w.y = pk2(o0[2], o0[3]); w2.x = pk2(o1[0], o1[1]); w2.y = pk2(o1[2], o1[3]);
;     *(u32x2*)(XN + (size_t)P.row * 1024 + lane * 4 + 256 * j) = w; *(u32x2*)(XN + (size_t)(P.row + 1) * 1024 + lane * 4 + 256 * j) = w2; }
; __device__ __forceinline__ void norm_rows(unsigned char* ws, const float* x, const float* ctx, bool first, int l, int which, int sel, int w0, int wstride, int lane) {
;     ...
;     if (j + 2 < n) norm_pair_load(A, ws, x, ctx, first, l, which, sel, kb + wi + wpb * (j + 2), lane);
	v_pk_add_f32 v[122:123], v[122:123], v[124:125]
	ds_bpermute_b32 v125, v67, v123
	ds_bpermute_b32 v124, v67, v122
	s_waitcnt lgkmcnt(0)
	v_pk_add_f32 v[122:123], v[122:123], v[124:125]
	ds_bpermute_b32 v125, v118, v123
	ds_bpermute_b32 v124, v118, v122
	s_waitcnt lgkmcnt(0)
	v_pk_add_f32 v[122:123], v[122:123], v[124:125]
	ds_bpermute_b32 v125, v119, v123
	ds_bpermute_b32 v124, v119, v122
	s_waitcnt lgkmcnt(0)
	v_pk_add_f32 v[122:123], v[122:123], v[124:125]
	ds_bpermute_b32 v125, v120, v123
	ds_bpermute_b32 v124, v120, v122
	s_waitcnt lgkmcnt(0)
	v_pk_add_f32 v[122:123], v[122:123], v[124:125]
	ds_bpermute_b32 v125, v121, v123
	ds_bpermute_b32 v124, v121, v122
	s_waitcnt lgkmcnt(0)
	v_pk_add_f32 v[122:123], v[122:123], v[124:125]
	s_nop 0
	v_pk_fma_f32 v[122:123], v[122:123], s[6:7], v[66:67] op_sel_hi:[1,0,0]
	s_nop 0
	v_mul_f32_e32 v85, 0x4b800000, v123
	v_cmp_gt_f32_e32 vcc, s19, v123
	v_cmp_gt_f32_e64 s[0:1], s19, v122
	s_nop 0
	v_cndmask_b32_e32 v85, v123, v85, vcc
	v_mul_f32_e32 v123, 0x4b800000, v122
	v_rsq_f32_e32 v85, v85
	v_cndmask_b32_e64 v122, v122, v123, s[0:1]
	v_rsq_f32_e32 v123, v122
	v_mul_f32_e32 v122, 0x45800000, v85
	v_cndmask_b32_e32 v122, v85, v122, vcc
	v_mul_f32_e32 v85, 0x45800000, v123
	v_cndmask_b32_e64 v124, v123, v85, s[0:1]
	v_pk_mul_f32 v[126:127], v[122:123], v[50:51] op_sel_hi:[0,1]
	v_pk_mul_f32 v[128:129], v[122:123], v[52:53] op_sel_hi:[0,1]
	v_pk_mul_f32 v[130:131], v[124:125], v[54:55] op_sel_hi:[0,1]
	v_pk_fma_f32 v[128:129], v[20:21], v[128:129], v[4:5]
	v_pk_fma_f32 v[126:127], v[18:19], v[126:127], v[2:3]
	v_pk_mul_f32 v[132:133], v[124:125], v[56:57] op_sel_hi:[0,1]
	v_pk_fma_f32 v[130:131], v[18:19], v[130:131], v[2:3]
	v_ashrrev_i32_e32 v85, 31, v84
	v_pk_fma_f32 v[132:133], v[20:21], v[132:133], v[4:5]
	v_cvt_pk_bf16_f32 v126, v126, v127
	v_cvt_pk_bf16_f32 v127, v128, v129
	v_cvt_pk_bf16_f32 v128, v130, v131
	v_lshlrev_b64 v[130:131], 11, v[84:85]
	v_cvt_pk_bf16_f32 v129, v132, v133
	v_lshl_add_u64 v[130:131], v[36:37], 0, v[130:131]
	global_store_dwordx2 v[130:131], v[126:127], off
	global_store_dwordx2 v[130:131], v[128:129], off offset:2048
	v_pk_mul_f32 v[126:127], v[122:123], v[58:59] op_sel_hi:[0,1]
	v_pk_mul_f32 v[128:129], v[122:123], v[60:61] op_sel_hi:[0,1]
	v_pk_mul_f32 v[132:133], v[124:125], v[62:63] op_sel_hi:[0,1]
	v_pk_mul_f32 v[134:135], v[124:125], v[64:65] op_sel_hi:[0,1]
	v_pk_fma_f32 v[128:129], v[24:25], v[128:129], v[8:9]
	v_pk_fma_f32 v[126:127], v[22:23], v[126:127], v[6:7]
	v_pk_fma_f32 v[134:135], v[24:25], v[134:135], v[8:9]
	v_pk_fma_f32 v[132:133], v[22:23], v[132:133], v[6:7]
	v_cvt_pk_bf16_f32 v126, v126, v127
	v_cvt_pk_bf16_f32 v127, v128, v129
	v_cvt_pk_bf16_f32 v128, v132, v133
	v_cvt_pk_bf16_f32 v129, v134, v135
	global_store_dwordx2 v[130:131], v[126:127], off offset:512
	global_store_dwordx2 v[130:131], v[128:129], off offset:2560
	v_pk_mul_f32 v[126:127], v[122:123], v[68:69] op_sel_hi:[0,1]
	v_pk_mul_f32 v[128:129], v[122:123], v[70:71] op_sel_hi:[0,1]
	s_waitcnt vmcnt(5)
	v_pk_fma_f32 v[128:129], v[28:29], v[128:129], v[16:17]
	v_pk_fma_f32 v[126:127], v[26:27], v[126:127], v[14:15]
	v_pk_mul_f32 v[132:133], v[124:125], v[72:73] op_sel_hi:[0,1]
	v_pk_mul_f32 v[134:135], v[124:125], v[74:75] op_sel_hi:[0,1]
	v_pk_fma_f32 v[134:135], v[28:29], v[134:135], v[16:17]
	v_pk_fma_f32 v[132:133], v[26:27], v[132:133], v[14:15]
	v_cvt_pk_bf16_f32 v126, v126, v127
	v_cvt_pk_bf16_f32 v127, v128, v129
	v_cvt_pk_bf16_f32 v128, v132, v133
	v_cvt_pk_bf16_f32 v129, v134, v135
	global_store_dwordx2 v[130:131], v[126:127], off offset:1024
	global_store_dwordx2 v[130:131], v[128:129], off offset:3072
	v_pk_mul_f32 v[126:127], v[122:123], v[76:77] op_sel_hi:[0,1]
	v_pk_mul_f32 v[122:123], v[122:123], v[78:79] op_sel_hi:[0,1]
	s_waitcnt vmcnt(6)
	v_pk_fma_f32 v[122:123], v[32:33], v[122:123], v[12:13]
	v_pk_fma_f32 v[126:127], v[30:31], v[126:127], v[10:11]
	v_pk_mul_f32 v[128:129], v[124:125], v[80:81] op_sel_hi:[0,1]
	v_pk_mul_f32 v[124:125], v[124:125], v[82:83] op_sel_hi:[0,1]
	v_pk_fma_f32 v[124:125], v[32:33], v[124:125], v[12:13]
	v_pk_fma_f32 v[128:129], v[30:31], v[128:129], v[10:11]
	v_cvt_pk_bf16_f32 v126, v126, v127
	v_cvt_pk_bf16_f32 v127, v122, v123
	s_andn2_b64 vcc, exec, s[12:13]
	v_readfirstlane_b32 s12, v0
	v_cvt_pk_bf16_f32 v122, v128, v129
	v_cvt_pk_bf16_f32 v123, v124, v125
	global_store_dwordx2 v[130:131], v[126:127], off offset:1536
	global_store_dwordx2 v[130:131], v[122:123], off offset:3584
	s_cbranch_vccnz .LBB0_1176
	s_cmp_ge_i32 s7, s14
	s_cselect_b64 s[10:11], -1, 0
	s_and_b64 vcc, exec, s[10:11]
	s_cbranch_vccnz .LBB0_1184
	s_add_i32 s0, s3, s28
	s_add_i32 s1, s16, s29
	s_lshr_b32 s0, s0, 7
	s_and_b32 s1, s1, 0xfe
	s_mulk_i32 s0, 0x900
	s_or_b32 s0, s0, s1
	s_ashr_i32 s1, s0, 31
	s_lshl_b64 s[12:13], s[0:1], 11
	v_lshl_add_u64 v[50:51], v[48:49], 0, s[12:13]
	global_load_dwordx2 v[52:53], v[50:51], off nt
	global_load_dwordx2 v[56:57], v[50:51], off offset:2048 nt
	global_load_dwordx2 v[60:61], v[50:51], off offset:512 nt
	global_load_dwordx2 v[64:65], v[50:51], off offset:2560 nt
	global_load_dwordx2 v[70:71], v[50:51], off offset:1024 nt
	global_load_dwordx2 v[74:75], v[50:51], off offset:3072 nt
	global_load_dwordx2 v[78:79], v[50:51], off offset:1536 nt
	global_load_dwordx2 v[82:83], v[50:51], off offset:3584 nt
	v_mov_b32_e32 v84, s0
	s_waitcnt vmcnt(7)
	v_lshlrev_b32_e32 v50, 16, v52
	v_and_b32_e32 v51, 0xffff0000, v52
	v_lshlrev_b32_e32 v52, 16, v53
	v_and_b32_e32 v53, 0xffff0000, v53
	s_waitcnt vmcnt(6)
	v_lshlrev_b32_e32 v54, 16, v56
	v_and_b32_e32 v55, 0xffff0000, v56
	v_lshlrev_b32_e32 v56, 16, v57
	v_and_b32_e32 v57, 0xffff0000, v57
	s_waitcnt vmcnt(5)
	v_lshlrev_b32_e32 v58, 16, v60
	v_and_b32_e32 v59, 0xffff0000, v60
	v_lshlrev_b32_e32 v60, 16, v61
	v_and_b32_e32 v61, 0xffff0000, v61
	s_waitcnt vmcnt(4)
	v_lshlrev_b32_e32 v62, 16, v64
	v_and_b32_e32 v63, 0xffff0000, v64
	v_lshlrev_b32_e32 v64, 16, v65
	v_and_b32_e32 v65, 0xffff0000, v65
	s_waitcnt vmcnt(3)
	v_lshlrev_b32_e32 v68, 16, v70
	v_and_b32_e32 v69, 0xffff0000, v70
	v_lshlrev_b32_e32 v70, 16, v71
	v_and_b32_e32 v71, 0xffff0000, v71
	s_waitcnt vmcnt(2)
	v_lshlrev_b32_e32 v72, 16, v74
	v_and_b32_e32 v73, 0xffff0000, v74
	v_lshlrev_b32_e32 v74, 16, v75
	v_and_b32_e32 v75, 0xffff0000, v75
	s_waitcnt vmcnt(1)
	v_lshlrev_b32_e32 v76, 16, v78
	v_and_b32_e32 v77, 0xffff0000, v78
	v_lshlrev_b32_e32 v78, 16, v79
	v_and_b32_e32 v79, 0xffff0000, v79
	s_waitcnt vmcnt(0)
	v_lshlrev_b32_e32 v80, 16, v82
	v_and_b32_e32 v81, 0xffff0000, v82
	v_lshlrev_b32_e32 v82, 16, v83
	v_and_b32_e32 v83, 0xffff0000, v83
; __device__ __forceinline__ void norm_pair_store(const NormPair& P, f32x4 (&sh)[4], f32x4 (&g)[4], const float*& md_cur, unsigned char* ws, int lane) {
;     ...
; #pragma unroll
.LBB0_1184:
	s_cmp_eq_u64 s[4:5], s[4:5]
	s_cbranch_scc1 .LBB0_1175
	v_lshl_add_u64 v[2:3], s[4:5], 0, v[34:35]
	v_add_co_u32_e32 v10, vcc, 0x1000, v2
	s_nop 1
	v_addc_co_u32_e32 v11, vcc, 0, v3, vcc
	global_load_dwordx4 v[18:21], v[10:11], off nt
	global_load_dwordx4 v[22:25], v[10:11], off offset:1024 nt
	global_load_dwordx4 v[26:29], v[10:11], off offset:2048 nt
	global_load_dwordx4 v[2:5], v34, s[4:5] nt
	global_load_dwordx4 v[6:9], v34, s[4:5] offset:1024 nt
	global_load_dwordx4 v[30:33], v[10:11], off offset:3072 nt
	global_load_dwordx4 v[14:17], v34, s[4:5] offset:2048 nt
	s_nop 0
	global_load_dwordx4 v[10:13], v34, s[4:5] offset:3072 nt
	s_waitcnt vmcnt(7)
	v_pk_add_f32 v[20:21], v[20:21], 1.0 op_sel_hi:[1,0]
	v_pk_add_f32 v[18:19], v[18:19], 1.0 op_sel_hi:[1,0]
	s_waitcnt vmcnt(6)
	v_pk_add_f32 v[24:25], v[24:25], 1.0 op_sel_hi:[1,0]
	v_pk_add_f32 v[22:23], v[22:23], 1.0 op_sel_hi:[1,0]
	s_waitcnt vmcnt(5)
	v_pk_add_f32 v[28:29], v[28:29], 1.0 op_sel_hi:[1,0]
	v_pk_add_f32 v[26:27], v[26:27], 1.0 op_sel_hi:[1,0]
	s_waitcnt vmcnt(2)
	v_pk_add_f32 v[32:33], v[32:33], 1.0 op_sel_hi:[1,0]
	v_pk_add_f32 v[30:31], v[30:31], 1.0 op_sel_hi:[1,0]
	s_branch .LBB0_1175

; __device__ __forceinline__ void norm_pair_load(NormPair& P, unsigned char* ws, const float* x, const float* ctx, bool first, int l, int which, int sel, int k, int lane) {
;   const float* MODS = (const float*)(ws + WS_MODS); const bf16_t* HB = (const bf16_t*)(ws + WS_HB);
;   const int i = 2 * k;
;   int b, pos; if (sel == 0) { b = i / RB; pos = i - b * RB; } else if (sel == 1) { b = i >> 11; pos = NCTX + (i & 2047); } else { b = i >> 8; pos = i & 255; }
;   const int row = b * RB + pos; P.row = row;
;     ...
;   if (first) { const float* hr = hrow_ptr(ctx, x, row);
; #pragma unroll
;     for (int j = 0; j < 4; ++j) { P.v0[j] = *(const f32x4*)(hr + lane * 4 + 256 * j); P.v1[j] = *(const f32x4*)(hr + DMODEL + lane * 4 + 256 * j); } }
;   else { const bf16_t* hr = HB + (size_t)row * 1024;
; #pragma unroll
;     for (int j = 0; j < 4; ++j) { const u32x2 w = *(const u32x2*)(hr + lane * 4 + 256 * j), w2 = *(const u32x2*)(hr + 1024 + lane * 4 + 256 * j);
;       P.v0[j] = (f32x4){bflo(w.x), bfhi(w.x), bflo(w.y), bfhi(w.y)}; P.v1[j] = (f32x4){bflo(w2.x), bfhi(w2.x), bflo(w2.y), bfhi(w2.y)}; } }
; }
; __device__ __forceinline__ void norm_rows(unsigned char* ws, const float* x, const float* ctx, bool first, int l, int which, int sel, int w0, int wstride, int lane) {
;   const int ppb = (sel == 0 ? RB : sel == 1 ? NLAT : NCTX) >> 1, wpb = wstride >> 4, b = w0 / wpb, wi = w0 - b * wpb, kb = b * ppb, n = (ppb - wi + wpb - 1) / wpb;
;   if (b >= 16 || n <= 0) return;
;   f32x4 sh[4], g[4]; const float* md_cur = nullptr;
;   NormPair A, B; norm_pair_load(A, ws, x, ctx, first, l, which, sel, kb + wi, lane);
;   for (int j = 0; j < n; j += 2) {
;     if (j + 1 < n) norm_pair_load(B, ws, x, ctx, first, l, which, sel, kb + wi + wpb * (j + 1), lane);
;     norm_pair_store(A, sh, g, md_cur, ws, lane);
;     if (j + 1 >= n) break;
;     if (j + 2 < n) norm_pair_load(A, ws, x, ctx, first, l, which, sel, kb + wi + wpb * (j + 2), lane);
;     norm_pair_store(B, sh, g, md_cur, ws, lane);
;   }
; }
; template <int ph> __device__ __forceinline__ void run_phase(const MArgs& a, unsigned char* lds, int tid, int lane, int wave, int G, int bx, int vcu) {
;     ...
;       const int gw2 = (bx - nctx) * NWAVES + wave, NGW2 = (G - nctx) * NWAVES;
;       { XcdBarrier b2; b2.bar = (unsigned*)(ws + WS_CTL) + 4096; b2.x = 0; b2.st = (volatile LAS unsigned*)(L + MISC_OFF) + 8; xcd_wait(b2); }
.LBB0_1460:
	s_or_b64 exec, exec, s[0:1]
	s_lshl_b32 s3, s33, 3
	s_addk_i32 s3, 0xfc00
	s_waitcnt lgkmcnt(0)
	s_ashr_i32 s8, s3, 4
	s_abs_i32 s4, s8
	v_cvt_f32_u32_e32 v1, s4
	s_lshl_b32 s17, s2, 3
	s_sub_i32 s1, 0, s4
	s_add_i32 s16, s17, s93
	v_rcp_iflag_f32_e32 v1, v1
	s_addk_i32 s16, 0xfc00
	s_abs_i32 s0, s16
	s_ashr_i32 s18, s16, 31
	v_mul_f32_e32 v1, 0x4f7ffffe, v1
	v_cvt_u32_f32_e32 v1, v1
	s_ashr_i32 s5, s3, 31
	s_xor_b32 s9, s18, s5
	s_waitcnt vmcnt(0)
	v_readfirstlane_b32 s6, v1
	s_mul_i32 s1, s1, s6
	s_mul_hi_u32 s1, s6, s1
	s_add_i32 s6, s6, s1
	s_mul_hi_u32 s1, s0, s6
	s_mul_i32 s7, s1, s4
	s_sub_i32 s0, s0, s7
	s_add_i32 s7, s1, 1
	s_sub_i32 s10, s0, s4
	s_cmp_ge_u32 s0, s4
	s_cselect_b32 s1, s7, s1
	s_cselect_b32 s0, s10, s0
	s_add_i32 s7, s1, 1
	s_cmp_ge_u32 s0, s4
	s_cselect_b32 s0, s7, s1
	s_xor_b32 s10, s0, s9
	s_sub_i32 s0, s10, s9
	s_mul_i32 s1, s0, s8
	s_sub_i32 s1, s16, s1
	s_sub_i32 s7, s8, s1
	s_addk_i32 s7, 0x3ff
	s_ashr_i32 s11, s7, 31
	s_abs_i32 s7, s7
	s_mul_hi_u32 s6, s7, s6
	s_xor_b32 s5, s11, s5
	s_mul_i32 s11, s6, s4
	s_sub_i32 s7, s7, s11
	s_add_i32 s11, s6, 1
	s_sub_i32 s12, s7, s4
	s_cmp_ge_u32 s7, s4
	s_cselect_b32 s6, s11, s6
	s_cselect_b32 s7, s12, s7
	s_add_i32 s11, s6, 1
	s_cmp_ge_u32 s7, s4
	s_cselect_b32 s4, s11, s6
	s_xor_b32 s4, s4, s5
	s_sub_i32 s19, s4, s5
	s_cmp_gt_i32 s0, 15
	s_cselect_b64 s[4:5], -1, 0
	s_cmp_lt_i32 s19, 1
	s_cselect_b64 s[6:7], -1, 0
	s_or_b64 s[4:5], s[4:5], s[6:7]
	s_and_b64 vcc, exec, s[4:5]
	s_barrier
	s_cbranch_vccnz .LBB0_1473
	s_lshl_b32 s0, s0, 10
	s_add_i32 s4, s1, s0
	s_add_u32 s28, s26, 0x100000
	s_addc_u32 s29, s27, 0
	s_add_u32 s0, s26, 0x4f00000
	s_addc_u32 s1, s27, 0
	s_lshl_b32 s5, s4, 1
	s_ashr_i32 s4, s4, 10
	s_and_b32 s5, s5, 0x7fe
	s_mul_i32 s6, s4, 0x900
	s_add_i32 s5, s5, s6
	s_add_i32 s4, s4, 17
	s_add_i32 s6, s5, 0x100
	s_mul_hi_i32 s5, s4, 0x6000
	s_mulk_i32 s4, 0x6000
	s_add_u32 s4, s28, s4
	s_addc_u32 s5, s29, s5
	s_ashr_i32 s7, s6, 31
	s_lshl_b64 s[12:13], s[6:7], 11
	s_add_u32 s12, s0, s12
	s_addc_u32 s13, s1, s13
	v_lshlrev_b32_e32 v34, 3, v254
	global_load_dwordx2 v[2:3], v34, s[12:13] nt
	global_load_dwordx2 v[4:5], v34, s[12:13] offset:2048 nt
	global_load_dwordx2 v[6:7], v34, s[12:13] offset:512 nt
	global_load_dwordx2 v[8:9], v34, s[12:13] offset:2560 nt
	global_load_dwordx2 v[10:11], v34, s[12:13] offset:1024 nt
	global_load_dwordx2 v[12:13], v34, s[12:13] offset:3072 nt
	global_load_dwordx2 v[14:15], v34, s[12:13] offset:1536 nt
	global_load_dwordx2 v[16:17], v34, s[12:13] offset:3584 nt
	v_mbcnt_lo_u32_b32 v1, -1, 0
	v_mbcnt_hi_u32_b32 v1, -1, v1
	v_and_b32_e32 v20, 64, v1
	v_mov_b32_e32 v35, 0
	v_xor_b32_e32 v21, 1, v1
	v_add_u32_e32 v20, 64, v20
	v_xor_b32_e32 v22, 2, v1
	v_cmp_lt_i32_e32 vcc, v21, v20
	v_lshl_add_u64 v[40:41], s[0:1], 0, v[34:35]
	s_sub_i32 s0, s9, s10
	v_xor_b32_e32 v23, 4, v1
	v_cndmask_b32_e32 v21, v1, v21, vcc
	v_cmp_lt_i32_e32 vcc, v22, v20
	s_add_i32 s1, s0, 2
	v_lshl_add_u64 v[18:19], s[26:27], 0, v[34:35]
	v_xor_b32_e32 v24, 8, v1
	v_cndmask_b32_e32 v22, v1, v22, vcc
	v_cmp_lt_i32_e32 vcc, v23, v20
	s_mov_b64 s[12:13], 0x9700000
	s_mul_i32 s1, s8, s1
	s_add_i32 s0, s0, 1
	v_xor_b32_e32 v25, 16, v1
	v_cndmask_b32_e32 v23, v1, v23, vcc
	v_cmp_lt_i32_e32 vcc, v24, v20
	v_lshl_add_u64 v[38:39], v[18:19], 0, s[12:13]
	s_add_i32 s11, s93, s1
	s_lshl_b32 s12, s10, 10
	s_lshl_b32 s30, s8, 1
	s_lshl_b32 s31, s1, 1
	s_lshl_b32 s1, s10, 11
	s_lshl_b32 s10, s2, 4
	s_lshl_b32 s34, s8, 2
	s_mul_i32 s8, s8, s0
	v_xor_b32_e32 v26, 32, v1
	v_cndmask_b32_e32 v24, v1, v24, vcc
	v_cmp_lt_i32_e32 vcc, v25, v20
	s_add_i32 s1, s1, s10
	s_lshl_b32 s10, s93, 1
	s_add_i32 s0, s93, s8
	v_cndmask_b32_e32 v25, v1, v25, vcc
	v_cmp_lt_i32_e32 vcc, v26, v20
	s_add_i32 s11, s11, s12
	s_lshl_b32 s13, s9, 10
	s_add_i32 s1, s1, s10
	s_lshl_b32 s9, s9, 11
	s_add_i32 s0, s0, s12
	v_cndmask_b32_e32 v20, v1, v26, vcc
	s_sub_i32 s11, s11, s13
	s_sub_i32 s1, s1, s9
	s_sub_i32 s0, s0, s13
	s_mov_b32 s7, 2
	v_lshlrev_b32_e32 v36, 2, v254
	v_lshlrev_b32_e32 v1, 2, v21
	v_lshlrev_b32_e32 v37, 2, v22
	v_lshlrev_b32_e32 v51, 2, v23
	v_lshlrev_b32_e32 v110, 2, v24
	v_lshlrev_b32_e32 v111, 2, v25
	v_lshlrev_b32_e32 v112, 2, v20
	s_add_i32 s37, s11, 0xfffffc00
	s_add_i32 s38, s1, 0xfffff800
	s_add_i32 s39, s0, 0xfffffc00
	s_lshl_b32 s35, s8, 1
	s_mov_b64 s[0:1], 0
	v_mov_b32_e32 v76, s6
	s_mov_b32 s6, 0x3a800000
	s_mov_b32 s36, 0x800000
	v_mov_b32_e32 v50, 0x358637bd
	s_waitcnt vmcnt(7)
	v_lshlrev_b32_e32 v42, 16, v2
	v_and_b32_e32 v43, 0xffff0000, v2
	v_lshlrev_b32_e32 v44, 16, v3
	v_and_b32_e32 v45, 0xffff0000, v3
	s_waitcnt vmcnt(6)
	v_lshlrev_b32_e32 v46, 16, v4
	v_and_b32_e32 v47, 0xffff0000, v4
	v_lshlrev_b32_e32 v48, 16, v5
	v_and_b32_e32 v49, 0xffff0000, v5
	s_waitcnt vmcnt(5)
	v_lshlrev_b32_e32 v52, 16, v6
	v_and_b32_e32 v53, 0xffff0000, v6
	v_lshlrev_b32_e32 v54, 16, v7
	v_and_b32_e32 v55, 0xffff0000, v7
	s_waitcnt vmcnt(4)
	v_lshlrev_b32_e32 v56, 16, v8
	v_and_b32_e32 v57, 0xffff0000, v8
	v_lshlrev_b32_e32 v58, 16, v9
	v_and_b32_e32 v59, 0xffff0000, v9
	s_waitcnt vmcnt(3)
	v_lshlrev_b32_e32 v60, 16, v10
	v_and_b32_e32 v61, 0xffff0000, v10
	v_lshlrev_b32_e32 v62, 16, v11
	v_and_b32_e32 v63, 0xffff0000, v11
	s_waitcnt vmcnt(2)
	v_lshlrev_b32_e32 v64, 16, v12
	v_and_b32_e32 v65, 0xffff0000, v12
	v_lshlrev_b32_e32 v66, 16, v13
	v_and_b32_e32 v67, 0xffff0000, v13
	s_waitcnt vmcnt(1)
	v_lshlrev_b32_e32 v68, 16, v14
	v_and_b32_e32 v69, 0xffff0000, v14
	v_lshlrev_b32_e32 v70, 16, v15
	v_and_b32_e32 v71, 0xffff0000, v15
	s_waitcnt vmcnt(0)
	v_lshlrev_b32_e32 v72, 16, v16
	v_and_b32_e32 v73, 0xffff0000, v16
	v_lshlrev_b32_e32 v74, 16, v17
	v_and_b32_e32 v75, 0xffff0000, v17
	s_branch .LBB0_1464

; __device__ __forceinline__ float bflo(unsigned u) { return __uint_as_float(u << 16); }
; __device__ __forceinline__ float bfhi(unsigned u) { return __uint_as_float(u & 0xffff0000u); }
; __device__ __forceinline__ void norm_pair_load(NormPair& P, unsigned char* ws, const float* x, const float* ctx, bool first, int l, int which, int sel, int k, int lane) {
;     ...
;   else { const bf16_t* hr = HB + (size_t)row * 1024;
; #pragma unroll
;     for (int j = 0; j < 4; ++j) { const u32x2 w = *(const u32x2*)(hr + lane * 4 + 256 * j), w2 = *(const u32x2*)(hr + 1024 + lane * 4 + 256 * j);
;       P.v0[j] = (f32x4){bflo(w.x), bfhi(w.x), bflo(w.y), bfhi(w.y)}; P.v1[j] = (f32x4){bflo(w2.x), bfhi(w2.x), bflo(w2.y), bfhi(w2.y)}; } }
; __device__ __forceinline__ void norm_rows(unsigned char* ws, const float* x, const float* ctx, bool first, int l, int which, int sel, int w0, int wstride, int lane) {
;     ...
;     if (j + 1 < n) norm_pair_load(B, ws, x, ctx, first, l, which, sel, kb + wi + wpb * (j + 1), lane);
.LBB0_1464:
	s_add_i32 s9, s7, -1
	s_cmp_lt_i32 s9, s19
	s_cselect_b64 s[14:15], -1, 0
	s_cmp_ge_i32 s9, s19
	s_cbranch_scc1 .LBB0_1466
	s_add_i32 s8, s17, s39
	s_add_i32 s9, s35, s38
	s_ashr_i32 s10, s8, 10
	s_and_b32 s8, s9, 0x7fe
	s_mul_i32 s9, s10, 0x900
	s_add_i32 s8, s8, s9
	s_add_i32 s9, s10, 17
	s_addk_i32 s8, 0x100
	s_mul_hi_i32 s11, s9, 0x6000
	s_mulk_i32 s9, 0x6000
	s_add_u32 s10, s28, s9
	s_addc_u32 s11, s29, s11
	s_ashr_i32 s9, s8, 31
	s_lshl_b64 s[12:13], s[8:9], 11
	v_lshl_add_u64 v[78:79], v[40:41], 0, s[12:13]
	global_load_dwordx2 v[80:81], v[78:79], off nt
	global_load_dwordx2 v[84:85], v[78:79], off offset:2048 nt
	global_load_dwordx2 v[88:89], v[78:79], off offset:512 nt
	global_load_dwordx2 v[90:91], v[78:79], off offset:2560 nt
	global_load_dwordx2 v[96:97], v[78:79], off offset:1024 nt
	global_load_dwordx2 v[102:103], v[78:79], off offset:3072 nt
	global_load_dwordx2 v[104:105], v[78:79], off offset:1536 nt
	global_load_dwordx2 v[108:109], v[78:79], off offset:3584 nt
	s_waitcnt vmcnt(7)
	v_lshlrev_b32_e32 v78, 16, v80
	v_and_b32_e32 v79, 0xffff0000, v80
	v_lshlrev_b32_e32 v86, 16, v81
	v_and_b32_e32 v87, 0xffff0000, v81
	s_waitcnt vmcnt(6)
	v_lshlrev_b32_e32 v82, 16, v84
	v_and_b32_e32 v83, 0xffff0000, v84
	v_lshlrev_b32_e32 v92, 16, v85
	v_and_b32_e32 v93, 0xffff0000, v85
	s_waitcnt vmcnt(5)
	v_lshlrev_b32_e32 v80, 16, v88
	v_and_b32_e32 v81, 0xffff0000, v88
	v_lshlrev_b32_e32 v94, 16, v89
	v_and_b32_e32 v95, 0xffff0000, v89
	s_waitcnt vmcnt(4)
	v_lshlrev_b32_e32 v88, 16, v90
	v_and_b32_e32 v89, 0xffff0000, v90
	v_lshlrev_b32_e32 v98, 16, v91
	v_and_b32_e32 v99, 0xffff0000, v91
	s_waitcnt vmcnt(3)
	v_lshlrev_b32_e32 v84, 16, v96
	v_and_b32_e32 v85, 0xffff0000, v96
	v_lshlrev_b32_e32 v100, 16, v97
	v_and_b32_e32 v101, 0xffff0000, v97
	s_waitcnt vmcnt(2)
	v_lshlrev_b32_e32 v96, 16, v102
	v_and_b32_e32 v97, 0xffff0000, v102
	v_lshlrev_b32_e32 v102, 16, v103
	v_and_b32_e32 v103, 0xffff0000, v103
	s_waitcnt vmcnt(1)
	v_lshlrev_b32_e32 v90, 16, v104
	v_and_b32_e32 v91, 0xffff0000, v104
	v_lshlrev_b32_e32 v104, 16, v105
	v_and_b32_e32 v105, 0xffff0000, v105
	s_waitcnt vmcnt(0)
	v_lshlrev_b32_e32 v106, 16, v108
	v_and_b32_e32 v107, 0xffff0000, v108
	v_lshlrev_b32_e32 v108, 16, v109
	v_and_b32_e32 v109, 0xffff0000, v109

; __device__ __forceinline__ unsigned pk2(float lo, float hi) { f32x2 v = {lo, hi}; bf16x2_t b = __builtin_convertvector(v, bf16x2_t); return __builtin_bit_cast(unsigned, b); }
; __device__ __forceinline__ void norm_pair_store(const NormPair& P, f32x4 (&sh)[4], f32x4 (&g)[4], const float*& md_cur, unsigned char* ws, int lane) {
;     ...
;   float ss0 = 0.f, ss1 = 0.f;
; #pragma unroll
;   for (int j = 0; j < 4; ++j) { ss0 += (P.v0[j][0] * P.v0[j][0] + P.v0[j][1] * P.v0[j][1]) + (P.v0[j][2] * P.v0[j][2] + P.v0[j][3] * P.v0[j][3]); ss1 += (P.v1[j][0] * P.v1[j][0] + P.v1[j][1] * P.v1[j][1]) + (P.v1[j][2] * P.v1[j][2] + P.v1[j][3] * P.v1[j][3]); }
;   const float rs0 = rsqrtf(wave_sum64(ss0) * (1.f / 1024.f) + EPS_N), rs1 = rsqrtf(wave_sum64(ss1) * (1.f / 1024.f) + EPS_N);
; #pragma unroll
;   for (int j = 0; j < 4; ++j) {
;     const f32x4 o0 = P.v0[j] * rs0 * g[j] + sh[j], o1 = P.v1[j] * rs1 * g[j] + sh[j]; u32x2 w, w2; w.x = pk2(o0[0], o0[1]); w.y = pk2(o0[2], o0[3]); w2.x = pk2(o1[0], o1[1]); w2.y = pk2(o1[2], o1[3]);
;     *(u32x2*)(XN + (size_t)P.row * 1024 + lane * 4 + 256 * j) = w; *(u32x2*)(XN + (size_t)(P.row + 1) * 1024 + lane * 4 + 256 * j) = w2; }
.LBB0_1468:
	v_pk_mul_f32 v[114:115], v[44:45], v[44:45]
	v_pk_mul_f32 v[116:117], v[42:43], v[42:43]
	v_mul_f32_e32 v34, v60, v60
	v_pk_mov_b32 v[118:119], v[116:117], v[114:115] op_sel:[1,0]
	v_mov_b32_e32 v117, v115
	v_pk_add_f32 v[114:115], v[118:119], v[116:117]
	v_pk_mul_f32 v[116:117], v[48:49], v[48:49]
	v_pk_mul_f32 v[118:119], v[46:47], v[46:47]
	v_pk_add_f32 v[114:115], v[114:115], v[114:115] op_sel_hi:[0,1]
	v_pk_mov_b32 v[120:121], v[118:119], v[116:117] op_sel:[1,0]
	v_mov_b32_e32 v119, v117
	v_pk_add_f32 v[116:117], v[120:121], v[118:119]
	v_pk_mul_f32 v[118:119], v[54:55], v[54:55]
	v_pk_mul_f32 v[120:121], v[52:53], v[52:53]
	v_pk_add_f32 v[116:117], v[116:117], v[116:117] op_sel_hi:[0,1]
	v_pk_mov_b32 v[122:123], v[120:121], v[118:119] op_sel:[1,0]
	v_mov_b32_e32 v121, v119
	v_pk_add_f32 v[118:119], v[122:123], v[120:121]
	v_pk_mul_f32 v[120:121], v[58:59], v[58:59]
	v_pk_mul_f32 v[122:123], v[56:57], v[56:57]
	v_pk_add_f32 v[118:119], v[118:119], v[118:119] op_sel_hi:[0,1]
	v_pk_mov_b32 v[124:125], v[122:123], v[120:121] op_sel:[1,0]
	v_mov_b32_e32 v123, v121
	v_pk_add_f32 v[120:121], v[124:125], v[122:123]
	v_pk_fma_f32 v[122:123], v[60:61], v[60:61], v[34:35] op_sel_hi:[1,1,0]
	v_mul_f32_e32 v34, v62, v62
	v_pk_fma_f32 v[124:125], v[62:63], v[62:63], v[34:35] op_sel_hi:[1,1,0]
	v_mul_f32_e32 v34, v64, v64
	v_pk_fma_f32 v[126:127], v[64:65], v[64:65], v[34:35] op_sel_hi:[1,1,0]
	v_mul_f32_e32 v34, v66, v66
	v_pk_add_f32 v[120:121], v[120:121], v[120:121] op_sel_hi:[0,1]
	v_pk_fma_f32 v[128:129], v[66:67], v[66:67], v[34:35] op_sel_hi:[1,1,0]
	v_mul_f32_e32 v122, v68, v68
	v_mul_f32_e32 v124, v69, v69
	v_mul_f32_e32 v114, v70, v70
	v_mul_f32_e32 v118, v71, v71
	v_mul_f32_e32 v126, v72, v72
	v_mul_f32_e32 v128, v73, v73
	v_mul_f32_e32 v116, v74, v74
	v_mul_f32_e32 v120, v75, v75
	v_pk_add_f32 v[122:123], v[122:123], v[124:125]
	v_pk_add_f32 v[114:115], v[114:115], v[118:119]
	v_pk_add_f32 v[118:119], v[126:127], v[128:129]
	v_pk_add_f32 v[116:117], v[116:117], v[120:121]
	v_pk_add_f32 v[114:115], v[122:123], v[114:115]
	v_pk_add_f32 v[116:117], v[118:119], v[116:117]
	v_mov_b32_e32 v119, v114
	v_mov_b32_e32 v118, v116
	v_mov_b32_e32 v114, v117
	v_pk_add_f32 v[114:115], v[118:119], v[114:115]
	ds_bpermute_b32 v117, v1, v115
	ds_bpermute_b32 v116, v1, v114
	s_mov_b64 s[12:13], -1
	v_readfirstlane_b32 s9, v0
	v_readfirstlane_b32 s40, v0
	v_readfirstlane_b32 s41, v0
	s_waitcnt lgkmcnt(0)
	v_pk_add_f32 v[114:115], v[114:115], v[116:117]
	ds_bpermute_b32 v117, v37, v115
	ds_bpermute_b32 v116, v37, v114
	v_readfirstlane_b32 s42, v0
	s_waitcnt lgkmcnt(0)
	v_pk_add_f32 v[114:115], v[114:115], v[116:117]
	ds_bpermute_b32 v117, v51, v115
	ds_bpermute_b32 v116, v51, v114
	s_waitcnt lgkmcnt(0)
	v_pk_add_f32 v[114:115], v[114:115], v[116:117]
	ds_bpermute_b32 v117, v110, v115
	ds_bpermute_b32 v116, v110, v114
	s_waitcnt lgkmcnt(0)
	v_pk_add_f32 v[114:115], v[114:115], v[116:117]
	ds_bpermute_b32 v117, v111, v115
	ds_bpermute_b32 v116, v111, v114
	s_waitcnt lgkmcnt(0)
	v_pk_add_f32 v[114:115], v[114:115], v[116:117]
	ds_bpermute_b32 v117, v112, v115
	ds_bpermute_b32 v116, v112, v114
	s_waitcnt lgkmcnt(0)
	v_pk_add_f32 v[114:115], v[114:115], v[116:117]
	s_nop 0
	v_pk_fma_f32 v[114:115], v[114:115], s[6:7], v[50:51] op_sel_hi:[1,0,0]
	s_nop 0
	v_mul_f32_e32 v34, 0x4b800000, v115
	v_cmp_gt_f32_e32 vcc, s36, v115
	v_mul_f32_e32 v77, 0x4b800000, v114
	v_cmp_gt_f32_e64 s[0:1], s36, v114
	v_cndmask_b32_e32 v34, v115, v34, vcc
	v_rsq_f32_e32 v34, v34
	v_cndmask_b32_e64 v77, v114, v77, s[0:1]
	v_rsq_f32_e32 v77, v77
	v_mul_f32_e32 v113, 0x45800000, v34
	v_cndmask_b32_e32 v34, v34, v113, vcc
	v_mul_f32_e32 v113, 0x45800000, v77
	v_cndmask_b32_e64 v114, v77, v113, s[0:1]
	v_pk_mul_f32 v[116:117], v[34:35], v[42:43] op_sel_hi:[0,1]
	v_pk_mul_f32 v[118:119], v[34:35], v[44:45] op_sel_hi:[0,1]
	v_pk_mul_f32 v[120:121], v[114:115], v[46:47] op_sel_hi:[0,1]
	v_pk_fma_f32 v[118:119], v[20:21], v[118:119], v[4:5]
	v_pk_fma_f32 v[116:117], v[18:19], v[116:117], v[2:3]
	v_pk_mul_f32 v[122:123], v[114:115], v[48:49] op_sel_hi:[0,1]
	v_pk_fma_f32 v[120:121], v[18:19], v[120:121], v[2:3]
	v_ashrrev_i32_e32 v77, 31, v76
	v_pk_fma_f32 v[122:123], v[20:21], v[122:123], v[4:5]
	v_cvt_pk_bf16_f32 v116, v116, v117
	v_cvt_pk_bf16_f32 v117, v118, v119
	v_cvt_pk_bf16_f32 v118, v120, v121
	v_lshlrev_b64 v[120:121], 11, v[76:77]
	v_cvt_pk_bf16_f32 v119, v122, v123
	v_lshl_add_u64 v[120:121], v[38:39], 0, v[120:121]
	global_store_dwordx2 v[120:121], v[116:117], off
	global_store_dwordx2 v[120:121], v[118:119], off offset:2048
	v_pk_mul_f32 v[116:117], v[34:35], v[52:53] op_sel_hi:[0,1]
	v_pk_mul_f32 v[118:119], v[34:35], v[54:55] op_sel_hi:[0,1]
	v_pk_mul_f32 v[122:123], v[114:115], v[56:57] op_sel_hi:[0,1]
	v_pk_mul_f32 v[124:125], v[114:115], v[58:59] op_sel_hi:[0,1]
	v_pk_fma_f32 v[118:119], v[24:25], v[118:119], v[8:9]
	v_pk_fma_f32 v[116:117], v[22:23], v[116:117], v[6:7]
	v_pk_fma_f32 v[124:125], v[24:25], v[124:125], v[8:9]
	v_pk_fma_f32 v[122:123], v[22:23], v[122:123], v[6:7]
	v_cvt_pk_bf16_f32 v116, v116, v117
	v_cvt_pk_bf16_f32 v117, v118, v119
	v_cvt_pk_bf16_f32 v118, v122, v123
	v_cvt_pk_bf16_f32 v119, v124, v125
	global_store_dwordx2 v[120:121], v[116:117], off offset:512
	global_store_dwordx2 v[120:121], v[118:119], off offset:2560
	v_pk_mul_f32 v[116:117], v[34:35], v[60:61] op_sel_hi:[0,1]
	v_pk_mul_f32 v[118:119], v[34:35], v[62:63] op_sel_hi:[0,1]
	v_pk_mul_f32 v[122:123], v[114:115], v[64:65] op_sel_hi:[0,1]
	v_pk_mul_f32 v[124:125], v[114:115], v[66:67] op_sel_hi:[0,1]
	s_waitcnt vmcnt(5)
	v_pk_fma_f32 v[118:119], v[28:29], v[118:119], v[16:17]
	v_pk_fma_f32 v[116:117], v[26:27], v[116:117], v[14:15]
	v_pk_fma_f32 v[124:125], v[28:29], v[124:125], v[16:17]
	v_pk_fma_f32 v[122:123], v[26:27], v[122:123], v[14:15]
	v_cvt_pk_bf16_f32 v116, v116, v117
	v_cvt_pk_bf16_f32 v117, v118, v119
	v_cvt_pk_bf16_f32 v118, v122, v123
	v_cvt_pk_bf16_f32 v119, v124, v125
	global_store_dwordx2 v[120:121], v[116:117], off offset:1024
	global_store_dwordx2 v[120:121], v[118:119], off offset:3072
	v_pk_mul_f32 v[116:117], v[34:35], v[68:69] op_sel_hi:[0,1]
	v_pk_mul_f32 v[118:119], v[34:35], v[70:71] op_sel_hi:[0,1]
	s_waitcnt vmcnt(6)
	v_pk_fma_f32 v[118:119], v[32:33], v[118:119], v[12:13]
	v_pk_fma_f32 v[116:117], v[30:31], v[116:117], v[10:11]
	v_pk_mul_f32 v[122:123], v[114:115], v[72:73] op_sel_hi:[0,1]
	v_pk_mul_f32 v[114:115], v[114:115], v[74:75] op_sel_hi:[0,1]
	v_pk_fma_f32 v[114:115], v[32:33], v[114:115], v[12:13]
	v_pk_fma_f32 v[122:123], v[30:31], v[122:123], v[10:11]
	v_cvt_pk_bf16_f32 v116, v116, v117
	v_cvt_pk_bf16_f32 v117, v118, v119
	s_andn2_b64 vcc, exec, s[14:15]
	v_cvt_pk_bf16_f32 v118, v122, v123
	v_cvt_pk_bf16_f32 v119, v114, v115
	global_store_dwordx2 v[120:121], v[116:117], off offset:1536
	global_store_dwordx2 v[120:121], v[118:119], off offset:3584
	s_cbranch_vccnz .LBB0_1463
; __device__ __forceinline__ float bflo(unsigned u) { return __uint_as_float(u << 16); }
; __device__ __forceinline__ float bfhi(unsigned u) { return __uint_as_float(u & 0xffff0000u); }
; __device__ __forceinline__ void norm_pair_load(NormPair& P, unsigned char* ws, const float* x, const float* ctx, bool first, int l, int which, int sel, int k, int lane) {
;     ...
;   else { const bf16_t* hr = HB + (size_t)row * 1024;
; #pragma unroll
;     for (int j = 0; j < 4; ++j) { const u32x2 w = *(const u32x2*)(hr + lane * 4 + 256 * j), w2 = *(const u32x2*)(hr + 1024 + lane * 4 + 256 * j);
;       P.v0[j] = (f32x4){bflo(w.x), bfhi(w.x), bflo(w.y), bfhi(w.y)}; P.v1[j] = (f32x4){bflo(w2.x), bfhi(w2.x), bflo(w2.y), bfhi(w2.y)}; } }
; __device__ __forceinline__ void norm_rows(unsigned char* ws, const float* x, const float* ctx, bool first, int l, int which, int sel, int w0, int wstride, int lane) {
;     ...
;     if (j + 2 < n) norm_pair_load(A, ws, x, ctx, first, l, which, sel, kb + wi + wpb * (j + 2), lane);
	s_cmp_ge_i32 s7, s19
	s_cselect_b64 s[12:13], -1, 0
	s_and_b64 vcc, exec, s[12:13]
	s_mov_b64 s[14:15], s[4:5]
	s_cbranch_vccnz .LBB0_1471
	s_add_i32 s0, s17, s37
	s_add_i32 s1, s31, s38
	s_ashr_i32 s9, s0, 10
	s_and_b32 s0, s1, 0x7fe
	s_mul_i32 s1, s9, 0x900
	s_add_i32 s0, s0, s1
	s_add_i32 s1, s9, 17
	s_addk_i32 s0, 0x100
	s_mul_hi_i32 s9, s1, 0x6000
	s_mulk_i32 s1, 0x6000
	s_add_u32 s14, s28, s1
	s_addc_u32 s15, s29, s9
	s_ashr_i32 s1, s0, 31
	s_lshl_b64 s[40:41], s[0:1], 11
	v_lshl_add_u64 v[42:43], v[40:41], 0, s[40:41]
	global_load_dwordx2 v[44:45], v[42:43], off nt
	global_load_dwordx2 v[48:49], v[42:43], off offset:2048 nt
	global_load_dwordx2 v[54:55], v[42:43], off offset:512 nt
	global_load_dwordx2 v[58:59], v[42:43], off offset:2560 nt
	global_load_dwordx2 v[62:63], v[42:43], off offset:1024 nt
	global_load_dwordx2 v[66:67], v[42:43], off offset:3072 nt
	global_load_dwordx2 v[70:71], v[42:43], off offset:1536 nt
	global_load_dwordx2 v[74:75], v[42:43], off offset:3584 nt
	v_mov_b32_e32 v76, s0
	s_waitcnt vmcnt(7)
	v_lshlrev_b32_e32 v42, 16, v44
	v_and_b32_e32 v43, 0xffff0000, v44
	v_lshlrev_b32_e32 v44, 16, v45
	v_and_b32_e32 v45, 0xffff0000, v45
	s_waitcnt vmcnt(6)
	v_lshlrev_b32_e32 v46, 16, v48
	v_and_b32_e32 v47, 0xffff0000, v48
	v_lshlrev_b32_e32 v48, 16, v49
	v_and_b32_e32 v49, 0xffff0000, v49
	s_waitcnt vmcnt(5)
	v_lshlrev_b32_e32 v52, 16, v54
	v_and_b32_e32 v53, 0xffff0000, v54
	v_lshlrev_b32_e32 v54, 16, v55
	v_and_b32_e32 v55, 0xffff0000, v55
	s_waitcnt vmcnt(4)
	v_lshlrev_b32_e32 v56, 16, v58
	v_and_b32_e32 v57, 0xffff0000, v58
	v_lshlrev_b32_e32 v58, 16, v59
	v_and_b32_e32 v59, 0xffff0000, v59
	s_waitcnt vmcnt(3)
	v_lshlrev_b32_e32 v60, 16, v62
	v_and_b32_e32 v61, 0xffff0000, v62
	v_lshlrev_b32_e32 v62, 16, v63
	v_and_b32_e32 v63, 0xffff0000, v63
	s_waitcnt vmcnt(2)
	v_lshlrev_b32_e32 v64, 16, v66
	v_and_b32_e32 v65, 0xffff0000, v66
	v_lshlrev_b32_e32 v66, 16, v67
	v_and_b32_e32 v67, 0xffff0000, v67
	s_waitcnt vmcnt(1)
	v_lshlrev_b32_e32 v68, 16, v70
	v_and_b32_e32 v69, 0xffff0000, v70
	v_lshlrev_b32_e32 v70, 16, v71
	v_and_b32_e32 v71, 0xffff0000, v71
	s_waitcnt vmcnt(0)
	v_lshlrev_b32_e32 v72, 16, v74
	v_and_b32_e32 v73, 0xffff0000, v74
	v_lshlrev_b32_e32 v74, 16, v75
	v_and_b32_e32 v75, 0xffff0000, v75

; __device__ __forceinline__ float bflo(unsigned u) { return __uint_as_float(u << 16); }
; __device__ __forceinline__ float bfhi(unsigned u) { return __uint_as_float(u & 0xffff0000u); }
; __device__ __forceinline__ void store8(bf16_t* p, const f32x4& a, const f32x4& b) { u32x4 w; w.x = pk2(a[0], a[1]); w.y = pk2(a[2], a[3]); w.z = pk2(b[0], b[1]); w.w = pk2(b[2], b[3]); *(u32x4*)p = w; }
;     __device__ __forceinline__ void operator()(const f32x4 (&acc)[2][2][4][2], const pg8::Unit& u, int wr, int wc, int fr, int fq, int buf) const {
;     ...
;             const float* hi_ = lat ? hin_l + ((size_t)bb * NLAT + (jt - 1) * 256) * DMODEL : hin_c + (size_t)bb * NCTX * DMODEL;
;             bf16_t* HB = (bf16_t*)(ws + WS_HB) + (size_t)u.pm * 256 * DMODEL; const bool first = hin_l != nullptr;
;             const float* gt = gate + (size_t)(lat ? bb : 16) * 6144;
; #pragma unroll
;             for (int bj = 0; bj < 2; ++bj) {
;                 const int c0 = u.pn * 256 + bj * 128 + wc * 32 + 8 * fq; const f32x4 g0 = *(const f32x4*)(gt + c0), g1 = *(const f32x4*)(gt + c0 + 4);
;     ...
;                 } else { u32x4 hw[8];
; #pragma unroll
;                     for (int q = 0; q < 8; ++q) { const size_t off = (size_t)((q >> 2) * 128 + (q & 3) * 16 + rloc0) * DMODEL + c0; hw[q] = *(const u32x4*)(HB + off); }
;                     __builtin_amdgcn_sched_barrier(0);
; #pragma unroll
;                     for (int q = 0; q < 8; ++q) { const size_t off = (size_t)((q >> 2) * 128 + (q & 3) * 16 + rloc0) * DMODEL + c0;
;                         const f32x4 h0 = (f32x4){bflo(hw[q].x), bfhi(hw[q].x), bflo(hw[q].y), bfhi(hw[q].y)}, h1 = (f32x4){bflo(hw[q].z), bfhi(hw[q].z), bflo(hw[q].w), bfhi(hw[q].w)};
;                         store8(HB + off, h0 + g0 * acc[q >> 2][bj][q & 3][0], h1 + g1 * acc[q >> 2][bj][q & 3][1]); }
.LBB0_1498:
	s_lshl_b32 s10, s17, 5
	s_lshl_b32 s6, s16, 19
	s_add_u32 s6, s26, s6
	s_addc_u32 s7, s27, 0
	s_add_u32 s6, s6, 0x4f00000
	s_addc_u32 s7, s7, 0
	s_add_u32 s8, s26, 0x165000
	s_addc_u32 s9, s27, 0
	s_lshl_b32 s3, s3, 8
	v_add_u32_e32 v154, s18, v142
	s_or_b32 s3, s10, s3
	v_lshl_add_u32 v138, v1, 3, s3
	v_ashrrev_i32_e32 v155, 31, v154
	v_add_u32_e32 v144, 32, v154
	v_add_u32_e32 v148, 0x80, v154
	v_add_u32_e32 v152, 0xa0, v154
	v_ashrrev_i32_e32 v139, 31, v138
	v_lshlrev_b64 v[140:141], 11, v[154:155]
	v_add_u32_e32 v142, 16, v154
	v_ashrrev_i32_e32 v145, 31, v144
	v_add_u32_e32 v146, 48, v154
	v_ashrrev_i32_e32 v149, 31, v148
	v_add_u32_e32 v150, 0x90, v154
	v_ashrrev_i32_e32 v153, 31, v152
	v_add_u32_e32 v154, 0xb0, v154
	v_lshl_add_u64 v[156:157], v[138:139], 1, s[6:7]
	v_ashrrev_i32_e32 v143, 31, v142
	v_lshlrev_b64 v[144:145], 11, v[144:145]
	v_ashrrev_i32_e32 v147, 31, v146
	v_lshlrev_b64 v[148:149], 11, v[148:149]
	v_ashrrev_i32_e32 v151, 31, v150
	v_lshlrev_b64 v[152:153], 11, v[152:153]
	v_ashrrev_i32_e32 v155, 31, v154
	v_lshl_add_u64 v[134:135], v[138:139], 2, s[8:9]
	v_lshl_add_u64 v[192:193], v[156:157], 0, v[140:141]
	v_lshlrev_b64 v[142:143], 11, v[142:143]
	v_lshl_add_u64 v[196:197], v[156:157], 0, v[144:145]
	v_lshlrev_b64 v[146:147], 11, v[146:147]
	v_lshl_add_u64 v[200:201], v[156:157], 0, v[148:149]
	v_lshlrev_b64 v[150:151], 11, v[150:151]
	v_lshl_add_u64 v[204:205], v[156:157], 0, v[152:153]
	v_lshlrev_b64 v[154:155], 11, v[154:155]
	global_load_dwordx4 v[130:133], v[134:135], off offset:16 nt
	s_nop 0
	global_load_dwordx4 v[134:137], v[134:135], off nt
	v_lshl_add_u64 v[194:195], v[156:157], 0, v[142:143]
	global_load_dwordx4 v[158:161], v[192:193], off nt
	global_load_dwordx4 v[162:165], v[194:195], off nt
	v_lshl_add_u64 v[198:199], v[156:157], 0, v[146:147]
	global_load_dwordx4 v[166:169], v[196:197], off nt
	global_load_dwordx4 v[172:175], v[198:199], off nt
	v_lshl_add_u64 v[202:203], v[156:157], 0, v[150:151]
	global_load_dwordx4 v[176:179], v[200:201], off nt
	global_load_dwordx4 v[180:183], v[202:203], off nt
	v_lshl_add_u64 v[156:157], v[156:157], 0, v[154:155]
	global_load_dwordx4 v[184:187], v[204:205], off nt
	global_load_dwordx4 v[188:191], v[156:157], off nt
	s_waitcnt vmcnt(0)
	v_lshlrev_b32_e32 v206, 16, v158
	v_and_b32_e32 v207, 0xffff0000, v158
	v_lshlrev_b32_e32 v158, 16, v159
	v_and_b32_e32 v159, 0xffff0000, v159
	v_lshlrev_b32_e32 v208, 16, v160
	v_and_b32_e32 v209, 0xffff0000, v160
	v_lshlrev_b32_e32 v160, 16, v161
	v_and_b32_e32 v161, 0xffff0000, v161
	v_pk_fma_f32 v[128:129], v[128:129], v[136:137], v[158:159]
	v_pk_fma_f32 v[126:127], v[126:127], v[134:135], v[206:207]
	v_pk_fma_f32 v[158:159], v[124:125], v[132:133], v[160:161]
	v_pk_fma_f32 v[124:125], v[122:123], v[130:131], v[208:209]
	v_cvt_pk_bf16_f32 v122, v126, v127
	v_cvt_pk_bf16_f32 v123, v128, v129
	v_cvt_pk_bf16_f32 v124, v124, v125
	v_cvt_pk_bf16_f32 v125, v158, v159
	global_store_dwordx4 v[192:193], v[122:125], off
	v_lshlrev_b32_e32 v126, 16, v164
	v_and_b32_e32 v127, 0xffff0000, v164
	v_lshlrev_b32_e32 v122, 16, v162
	v_and_b32_e32 v123, 0xffff0000, v162
	v_lshlrev_b32_e32 v124, 16, v163
	v_and_b32_e32 v125, 0xffff0000, v163
	v_lshlrev_b32_e32 v128, 16, v165
	v_and_b32_e32 v129, 0xffff0000, v165
	v_pk_fma_f32 v[120:121], v[120:121], v[136:137], v[124:125]
	v_pk_fma_f32 v[118:119], v[118:119], v[134:135], v[122:123]
	v_pk_fma_f32 v[122:123], v[116:117], v[132:133], v[128:129]
	v_pk_fma_f32 v[116:117], v[114:115], v[130:131], v[126:127]
	v_cvt_pk_bf16_f32 v114, v118, v119
	v_cvt_pk_bf16_f32 v115, v120, v121
	v_cvt_pk_bf16_f32 v116, v116, v117
	v_cvt_pk_bf16_f32 v117, v122, v123
	global_store_dwordx4 v[194:195], v[114:117], off
	v_lshlrev_b32_e32 v118, 16, v168
	v_and_b32_e32 v119, 0xffff0000, v168
	v_lshlrev_b32_e32 v114, 16, v166
	v_and_b32_e32 v115, 0xffff0000, v166
	v_lshlrev_b32_e32 v116, 16, v167
	v_and_b32_e32 v117, 0xffff0000, v167
	v_lshlrev_b32_e32 v120, 16, v169
	v_and_b32_e32 v121, 0xffff0000, v169
	v_pk_fma_f32 v[112:113], v[112:113], v[136:137], v[116:117]
	v_pk_fma_f32 v[110:111], v[110:111], v[134:135], v[114:115]
	v_pk_fma_f32 v[114:115], v[108:109], v[132:133], v[120:121]
	v_pk_fma_f32 v[108:109], v[106:107], v[130:131], v[118:119]
	v_cvt_pk_bf16_f32 v106, v110, v111
	v_cvt_pk_bf16_f32 v107, v112, v113
	v_cvt_pk_bf16_f32 v108, v108, v109
	v_cvt_pk_bf16_f32 v109, v114, v115
	global_store_dwordx4 v[196:197], v[106:109], off
	v_lshlrev_b32_e32 v110, 16, v174
	v_and_b32_e32 v111, 0xffff0000, v174
	v_lshlrev_b32_e32 v106, 16, v172
	v_and_b32_e32 v107, 0xffff0000, v172
	v_lshlrev_b32_e32 v108, 16, v173
	v_and_b32_e32 v109, 0xffff0000, v173
	v_lshlrev_b32_e32 v112, 16, v175
	v_and_b32_e32 v113, 0xffff0000, v175
	v_pk_fma_f32 v[104:105], v[104:105], v[136:137], v[108:109]
	v_pk_fma_f32 v[102:103], v[102:103], v[134:135], v[106:107]
	v_pk_fma_f32 v[106:107], v[100:101], v[132:133], v[112:113]
	v_pk_fma_f32 v[100:101], v[98:99], v[130:131], v[110:111]
	v_cvt_pk_bf16_f32 v98, v102, v103
	v_cvt_pk_bf16_f32 v99, v104, v105
	v_cvt_pk_bf16_f32 v100, v100, v101
	v_cvt_pk_bf16_f32 v101, v106, v107
	global_store_dwordx4 v[198:199], v[98:101], off
	v_lshlrev_b32_e32 v102, 16, v178
	v_and_b32_e32 v103, 0xffff0000, v178
	v_lshlrev_b32_e32 v98, 16, v176
	v_and_b32_e32 v99, 0xffff0000, v176
	v_lshlrev_b32_e32 v100, 16, v177
	v_and_b32_e32 v101, 0xffff0000, v177
	v_lshlrev_b32_e32 v104, 16, v179
	v_and_b32_e32 v105, 0xffff0000, v179
	v_pk_fma_f32 v[96:97], v[96:97], v[136:137], v[100:101]
	v_pk_fma_f32 v[94:95], v[94:95], v[134:135], v[98:99]
	v_pk_fma_f32 v[98:99], v[92:93], v[132:133], v[104:105]
; __device__ __forceinline__ float bflo(unsigned u) { return __uint_as_float(u << 16); }
; __device__ __forceinline__ float bfhi(unsigned u) { return __uint_as_float(u & 0xffff0000u); }
; __device__ __forceinline__ void store8(bf16_t* p, const f32x4& a, const f32x4& b) { u32x4 w; w.x = pk2(a[0], a[1]); w.y = pk2(a[2], a[3]); w.z = pk2(b[0], b[1]); w.w = pk2(b[2], b[3]); *(u32x4*)p = w; }
;     __device__ __forceinline__ void operator()(const f32x4 (&acc)[2][2][4][2], const pg8::Unit& u, int wr, int wc, int fr, int fq, int buf) const {
;     ...
;             for (int bj = 0; bj < 2; ++bj) {
;                 const int c0 = u.pn * 256 + bj * 128 + wc * 32 + 8 * fq; const f32x4 g0 = *(const f32x4*)(gt + c0), g1 = *(const f32x4*)(gt + c0 + 4);
;                 if (first) { f32x4 h0[8], h1[8];
; #pragma unroll
;                     for (int q = 0; q < 8; ++q) { const size_t off = (size_t)((q >> 2) * 128 + (q & 3) * 16 + rloc0) * DMODEL + c0; h0[q] = *(const f32x4*)(hi_ + off); h1[q] = *(const f32x4*)(hi_ + off + 4); }
;                     __builtin_amdgcn_sched_barrier(0);
; #pragma unroll
;                     for (int q = 0; q < 8; ++q) { const size_t off = (size_t)((q >> 2) * 128 + (q & 3) * 16 + rloc0) * DMODEL + c0;
;                         store8(HB + off, h0[q] + g0 * acc[q >> 2][bj][q & 3][0], h1[q] + g1 * acc[q >> 2][bj][q & 3][1]); }
;                 } else { u32x4 hw[8];
; #pragma unroll
;                     for (int q = 0; q < 8; ++q) { const size_t off = (size_t)((q >> 2) * 128 + (q & 3) * 16 + rloc0) * DMODEL + c0; hw[q] = *(const u32x4*)(HB + off); }
;                     __builtin_amdgcn_sched_barrier(0);
; #pragma unroll
;                     for (int q = 0; q < 8; ++q) { const size_t off = (size_t)((q >> 2) * 128 + (q & 3) * 16 + rloc0) * DMODEL + c0;
;                         const f32x4 h0 = (f32x4){bflo(hw[q].x), bfhi(hw[q].x), bflo(hw[q].y), bfhi(hw[q].y)}, h1 = (f32x4){bflo(hw[q].z), bfhi(hw[q].z), bflo(hw[q].w), bfhi(hw[q].w)};
;                         store8(HB + off, h0 + g0 * acc[q >> 2][bj][q & 3][0], h1 + g1 * acc[q >> 2][bj][q & 3][1]); }
	v_pk_fma_f32 v[92:93], v[90:91], v[130:131], v[102:103]
	v_cvt_pk_bf16_f32 v90, v94, v95
	v_cvt_pk_bf16_f32 v91, v96, v97
	v_cvt_pk_bf16_f32 v92, v92, v93
	v_cvt_pk_bf16_f32 v93, v98, v99
	global_store_dwordx4 v[200:201], v[90:93], off
	v_lshlrev_b32_e32 v94, 16, v182
	v_and_b32_e32 v95, 0xffff0000, v182
	v_lshlrev_b32_e32 v90, 16, v180
	v_and_b32_e32 v91, 0xffff0000, v180
	v_lshlrev_b32_e32 v92, 16, v181
	v_and_b32_e32 v93, 0xffff0000, v181
	v_lshlrev_b32_e32 v96, 16, v183
	v_and_b32_e32 v97, 0xffff0000, v183
	v_pk_fma_f32 v[88:89], v[88:89], v[136:137], v[92:93]
	v_pk_fma_f32 v[86:87], v[86:87], v[134:135], v[90:91]
	v_pk_fma_f32 v[90:91], v[84:85], v[132:133], v[96:97]
	v_pk_fma_f32 v[84:85], v[82:83], v[130:131], v[94:95]
	v_cvt_pk_bf16_f32 v82, v86, v87
	v_cvt_pk_bf16_f32 v83, v88, v89
	v_cvt_pk_bf16_f32 v84, v84, v85
	v_cvt_pk_bf16_f32 v85, v90, v91
	global_store_dwordx4 v[202:203], v[82:85], off
	v_lshlrev_b32_e32 v86, 16, v186
	v_and_b32_e32 v87, 0xffff0000, v186
	v_lshlrev_b32_e32 v82, 16, v184
	v_and_b32_e32 v83, 0xffff0000, v184
	v_lshlrev_b32_e32 v84, 16, v185
	v_and_b32_e32 v85, 0xffff0000, v185
	v_lshlrev_b32_e32 v88, 16, v187
	v_and_b32_e32 v89, 0xffff0000, v187
	v_pk_fma_f32 v[80:81], v[80:81], v[136:137], v[84:85]
	v_pk_fma_f32 v[78:79], v[78:79], v[134:135], v[82:83]
	v_pk_fma_f32 v[82:83], v[76:77], v[132:133], v[88:89]
	v_pk_fma_f32 v[76:77], v[74:75], v[130:131], v[86:87]
	v_cvt_pk_bf16_f32 v74, v78, v79
	v_cvt_pk_bf16_f32 v75, v80, v81
	v_cvt_pk_bf16_f32 v76, v76, v77
	v_cvt_pk_bf16_f32 v77, v82, v83
	global_store_dwordx4 v[204:205], v[74:77], off
	v_lshlrev_b32_e32 v78, 16, v190
	v_and_b32_e32 v79, 0xffff0000, v190
	v_lshlrev_b32_e32 v74, 16, v188
	v_and_b32_e32 v75, 0xffff0000, v188
	v_lshlrev_b32_e32 v76, 16, v189
	v_and_b32_e32 v77, 0xffff0000, v189
	v_lshlrev_b32_e32 v80, 16, v191
	v_and_b32_e32 v81, 0xffff0000, v191
	v_pk_fma_f32 v[72:73], v[72:73], v[136:137], v[76:77]
	v_pk_fma_f32 v[70:71], v[70:71], v[134:135], v[74:75]
	v_pk_fma_f32 v[74:75], v[64:65], v[132:133], v[80:81]
	v_pk_fma_f32 v[64:65], v[62:63], v[130:131], v[78:79]
	v_cvt_pk_bf16_f32 v62, v70, v71
	v_cvt_pk_bf16_f32 v63, v72, v73
	v_cvt_pk_bf16_f32 v64, v64, v65
	v_cvt_pk_bf16_f32 v65, v74, v75
	global_store_dwordx4 v[156:157], v[62:65], off
	v_add_u32_e32 v74, 0x80, v138
	v_ashrrev_i32_e32 v75, 31, v74
	v_lshl_add_u64 v[70:71], v[74:75], 2, s[8:9]
	v_lshl_add_u64 v[74:75], v[74:75], 1, s[6:7]
	v_lshl_add_u64 v[108:109], v[74:75], 0, v[140:141]
	v_lshl_add_u64 v[112:113], v[74:75], 0, v[144:145]
	v_lshl_add_u64 v[116:117], v[74:75], 0, v[148:149]
	v_lshl_add_u64 v[120:121], v[74:75], 0, v[152:153]
	global_load_dwordx4 v[62:65], v[70:71], off offset:16 nt
	s_nop 0
	global_load_dwordx4 v[70:73], v[70:71], off nt
	v_lshl_add_u64 v[110:111], v[74:75], 0, v[142:143]
	global_load_dwordx4 v[76:79], v[108:109], off nt
	global_load_dwordx4 v[80:83], v[110:111], off nt
	v_lshl_add_u64 v[114:115], v[74:75], 0, v[146:147]
	global_load_dwordx4 v[84:87], v[112:113], off nt
	global_load_dwordx4 v[88:91], v[114:115], off nt
	v_lshl_add_u64 v[118:119], v[74:75], 0, v[150:151]
	global_load_dwordx4 v[92:95], v[116:117], off nt
	global_load_dwordx4 v[96:99], v[118:119], off nt
	v_lshl_add_u64 v[74:75], v[74:75], 0, v[154:155]
	global_load_dwordx4 v[100:103], v[120:121], off nt
	global_load_dwordx4 v[104:107], v[74:75], off nt
	s_waitcnt vmcnt(7)
	v_lshlrev_b32_e32 v122, 16, v76
	v_and_b32_e32 v123, 0xffff0000, v76
	v_lshlrev_b32_e32 v76, 16, v77
	v_and_b32_e32 v77, 0xffff0000, v77
	v_lshlrev_b32_e32 v124, 16, v78
	v_and_b32_e32 v125, 0xffff0000, v78
	v_lshlrev_b32_e32 v78, 16, v79
	v_and_b32_e32 v79, 0xffff0000, v79
	v_pk_fma_f32 v[68:69], v[68:69], v[72:73], v[76:77]
	v_pk_fma_f32 v[66:67], v[66:67], v[70:71], v[122:123]
	v_pk_fma_f32 v[76:77], v[60:61], v[64:65], v[78:79]
	v_pk_fma_f32 v[60:61], v[58:59], v[62:63], v[124:125]
	v_cvt_pk_bf16_f32 v58, v66, v67
	v_cvt_pk_bf16_f32 v59, v68, v69
	v_cvt_pk_bf16_f32 v60, v60, v61
	v_cvt_pk_bf16_f32 v61, v76, v77
	global_store_dwordx4 v[108:109], v[58:61], off
	s_waitcnt vmcnt(7)
	v_lshlrev_b32_e32 v66, 16, v82
	v_and_b32_e32 v67, 0xffff0000, v82
	v_lshlrev_b32_e32 v58, 16, v80
	v_and_b32_e32 v59, 0xffff0000, v80
	v_lshlrev_b32_e32 v60, 16, v81
	v_and_b32_e32 v61, 0xffff0000, v81
	v_lshlrev_b32_e32 v68, 16, v83
	v_and_b32_e32 v69, 0xffff0000, v83
	v_pk_fma_f32 v[56:57], v[56:57], v[72:73], v[60:61]
	v_pk_fma_f32 v[54:55], v[54:55], v[70:71], v[58:59]
	v_pk_fma_f32 v[58:59], v[52:53], v[64:65], v[68:69]
	v_pk_fma_f32 v[52:53], v[50:51], v[62:63], v[66:67]
	v_cvt_pk_bf16_f32 v50, v54, v55
	v_cvt_pk_bf16_f32 v51, v56, v57
	v_cvt_pk_bf16_f32 v52, v52, v53
	v_cvt_pk_bf16_f32 v53, v58, v59
	global_store_dwordx4 v[110:111], v[50:53], off
	s_waitcnt vmcnt(7)
; __device__ __forceinline__ float bflo(unsigned u) { return __uint_as_float(u << 16); }
; __device__ __forceinline__ float bfhi(unsigned u) { return __uint_as_float(u & 0xffff0000u); }
; __device__ __forceinline__ void store8(bf16_t* p, const f32x4& a, const f32x4& b) { u32x4 w; w.x = pk2(a[0], a[1]); w.y = pk2(a[2], a[3]); w.z = pk2(b[0], b[1]); w.w = pk2(b[2], b[3]); *(u32x4*)p = w; }
; #define PG8_WAIT_V(n) asm volatile("s_waitcnt vmcnt(" #n ")" ::: "memory")
; #define PG8_BAR __builtin_amdgcn_s_barrier()
; template <class Epi, class Sched, bool APERM, bool ABLK = false, bool RELAX = true>
; __device__ __forceinline__ void gemm_phase(LAS unsigned char* lds, const Gemm g, const Sched& S, const Epi& E) {
;     ...
;     PG8_WAIT_V(0);
;     PG8_BAR;
;     __device__ __forceinline__ void operator()(const f32x4 (&acc)[2][2][4][2], const pg8::Unit& u, int wr, int wc, int fr, int fq, int buf) const {
;     ...
;                     for (int q = 0; q < 8; ++q) { const size_t off = (size_t)((q >> 2) * 128 + (q & 3) * 16 + rloc0) * DMODEL + c0;
;                         const f32x4 h0 = (f32x4){bflo(hw[q].x), bfhi(hw[q].x), bflo(hw[q].y), bfhi(hw[q].y)}, h1 = (f32x4){bflo(hw[q].z), bfhi(hw[q].z), bflo(hw[q].w), bfhi(hw[q].w)};
;                         store8(HB + off, h0 + g0 * acc[q >> 2][bj][q & 3][0], h1 + g1 * acc[q >> 2][bj][q & 3][1]); }
	v_lshlrev_b32_e32 v54, 16, v86
	v_and_b32_e32 v55, 0xffff0000, v86
	v_lshlrev_b32_e32 v50, 16, v84
	v_and_b32_e32 v51, 0xffff0000, v84
	v_lshlrev_b32_e32 v52, 16, v85
	v_and_b32_e32 v53, 0xffff0000, v85
	v_lshlrev_b32_e32 v56, 16, v87
	v_and_b32_e32 v57, 0xffff0000, v87
	v_pk_fma_f32 v[48:49], v[48:49], v[72:73], v[52:53]
	v_pk_fma_f32 v[46:47], v[46:47], v[70:71], v[50:51]
	v_pk_fma_f32 v[50:51], v[44:45], v[64:65], v[56:57]
	v_pk_fma_f32 v[44:45], v[42:43], v[62:63], v[54:55]
	v_cvt_pk_bf16_f32 v42, v46, v47
	v_cvt_pk_bf16_f32 v43, v48, v49
	v_cvt_pk_bf16_f32 v44, v44, v45
	v_cvt_pk_bf16_f32 v45, v50, v51
	global_store_dwordx4 v[112:113], v[42:45], off
	s_waitcnt vmcnt(7)
	v_lshlrev_b32_e32 v46, 16, v90
	v_and_b32_e32 v47, 0xffff0000, v90
	v_lshlrev_b32_e32 v42, 16, v88
	v_and_b32_e32 v43, 0xffff0000, v88
	v_lshlrev_b32_e32 v44, 16, v89
	v_and_b32_e32 v45, 0xffff0000, v89
	v_lshlrev_b32_e32 v48, 16, v91
	v_and_b32_e32 v49, 0xffff0000, v91
	v_pk_fma_f32 v[40:41], v[40:41], v[72:73], v[44:45]
	v_pk_fma_f32 v[38:39], v[38:39], v[70:71], v[42:43]
	v_pk_fma_f32 v[42:43], v[36:37], v[64:65], v[48:49]
	v_pk_fma_f32 v[36:37], v[34:35], v[62:63], v[46:47]
	v_cvt_pk_bf16_f32 v34, v38, v39
	v_cvt_pk_bf16_f32 v35, v40, v41
	v_cvt_pk_bf16_f32 v36, v36, v37
	v_cvt_pk_bf16_f32 v37, v42, v43
	global_store_dwordx4 v[114:115], v[34:37], off
	s_waitcnt vmcnt(7)
	v_lshlrev_b32_e32 v38, 16, v94
	v_and_b32_e32 v39, 0xffff0000, v94
	v_lshlrev_b32_e32 v34, 16, v92
	v_and_b32_e32 v35, 0xffff0000, v92
	v_lshlrev_b32_e32 v36, 16, v93
	v_and_b32_e32 v37, 0xffff0000, v93
	v_lshlrev_b32_e32 v40, 16, v95
	v_and_b32_e32 v41, 0xffff0000, v95
	v_pk_fma_f32 v[32:33], v[32:33], v[72:73], v[36:37]
	v_pk_fma_f32 v[30:31], v[30:31], v[70:71], v[34:35]
	v_pk_fma_f32 v[34:35], v[28:29], v[64:65], v[40:41]
	v_pk_fma_f32 v[28:29], v[26:27], v[62:63], v[38:39]
	v_cvt_pk_bf16_f32 v26, v30, v31
	v_cvt_pk_bf16_f32 v27, v32, v33
	v_cvt_pk_bf16_f32 v28, v28, v29
	v_cvt_pk_bf16_f32 v29, v34, v35
	global_store_dwordx4 v[116:117], v[26:29], off
	s_waitcnt vmcnt(7)
	v_lshlrev_b32_e32 v30, 16, v98
	v_and_b32_e32 v31, 0xffff0000, v98
	v_lshlrev_b32_e32 v26, 16, v96
	v_and_b32_e32 v27, 0xffff0000, v96
	v_lshlrev_b32_e32 v28, 16, v97
	v_and_b32_e32 v29, 0xffff0000, v97
	v_lshlrev_b32_e32 v32, 16, v99
	v_and_b32_e32 v33, 0xffff0000, v99
	v_pk_fma_f32 v[24:25], v[24:25], v[72:73], v[28:29]
	v_pk_fma_f32 v[22:23], v[22:23], v[70:71], v[26:27]
	v_pk_fma_f32 v[26:27], v[20:21], v[64:65], v[32:33]
	v_pk_fma_f32 v[20:21], v[18:19], v[62:63], v[30:31]
	v_cvt_pk_bf16_f32 v18, v22, v23
	v_cvt_pk_bf16_f32 v19, v24, v25
	v_cvt_pk_bf16_f32 v20, v20, v21
	v_cvt_pk_bf16_f32 v21, v26, v27
	global_store_dwordx4 v[118:119], v[18:21], off
	s_waitcnt vmcnt(7)
	v_lshlrev_b32_e32 v22, 16, v102
	v_and_b32_e32 v23, 0xffff0000, v102
	v_lshlrev_b32_e32 v18, 16, v100
	v_and_b32_e32 v19, 0xffff0000, v100
	v_lshlrev_b32_e32 v20, 16, v101
	v_and_b32_e32 v21, 0xffff0000, v101
	v_lshlrev_b32_e32 v24, 16, v103
	v_and_b32_e32 v25, 0xffff0000, v103
	v_pk_fma_f32 v[16:17], v[16:17], v[72:73], v[20:21]
	v_pk_fma_f32 v[14:15], v[14:15], v[70:71], v[18:19]
	v_pk_fma_f32 v[18:19], v[12:13], v[64:65], v[24:25]
	v_pk_fma_f32 v[12:13], v[10:11], v[62:63], v[22:23]
	v_cvt_pk_bf16_f32 v10, v14, v15
	v_cvt_pk_bf16_f32 v11, v16, v17
	v_cvt_pk_bf16_f32 v12, v12, v13
	v_cvt_pk_bf16_f32 v13, v18, v19
	global_store_dwordx4 v[120:121], v[10:13], off
	s_waitcnt vmcnt(7)
	v_lshlrev_b32_e32 v14, 16, v106
	v_and_b32_e32 v15, 0xffff0000, v106
	v_lshlrev_b32_e32 v10, 16, v104
	v_and_b32_e32 v11, 0xffff0000, v104
	v_lshlrev_b32_e32 v12, 16, v105
	v_and_b32_e32 v13, 0xffff0000, v105
	v_lshlrev_b32_e32 v16, 16, v107
	v_and_b32_e32 v17, 0xffff0000, v107
	v_pk_fma_f32 v[8:9], v[8:9], v[72:73], v[12:13]
	v_pk_fma_f32 v[6:7], v[6:7], v[70:71], v[10:11]
	v_pk_fma_f32 v[10:11], v[4:5], v[64:65], v[16:17]
	v_pk_fma_f32 v[4:5], v[2:3], v[62:63], v[14:15]
	v_cvt_pk_bf16_f32 v2, v6, v7
	v_cvt_pk_bf16_f32 v3, v8, v9
	v_cvt_pk_bf16_f32 v4, v4, v5
	v_cvt_pk_bf16_f32 v5, v10, v11
	global_store_dwordx4 v[74:75], v[2:5], off
	s_waitcnt vmcnt(0)
	v_cmp_eq_u32_e32 vcc, 0, v0
	s_and_b64 s[0:1], vcc, s[0:1]
	s_barrier
	s_and_saveexec_b64 s[6:7], s[0:1]
	s_cbranch_execz .LBB0_1501
	s_mov_b64 s[8:9], exec
	v_mbcnt_lo_u32_b32 v1, s8, 0
	v_mbcnt_hi_u32_b32 v1, s9, v1
	v_cmp_eq_u32_e64 s[0:1], 0, v1
	s_and_b64 s[0:1], exec, s[0:1]
	buffer_wbl2 sc1
	s_waitcnt vmcnt(0)
	s_mov_b64 exec, s[0:1]
	s_cbranch_execz .LBB0_1501
	s_bcnt1_i32_b64 s0, s[8:9]
	v_mov_b32_e32 v1, 0
	v_mov_b32_e32 v2, s0
	global_atomic_add v1, v2, s[4:5]

; #define FN_LOAD(W, k) do { const int row_ = 2 * (k); const bf16_t* hr_ = HB + ((size_t)(row_ >> 11) * RB + NCTX + (row_ & 2047)) * 1024; \
;       _Pragma("unroll") for (int j = 0; j < 4; ++j) { W[j] = *(const u32x2*)(hr_ + lane * 4 + 256 * j); W[4 + j] = *(const u32x2*)(hr_ + 1024 + lane * 4 + 256 * j); } } while (0)
; template <int ph> __device__ __forceinline__ void run_phase(const MArgs& a, unsigned char* lds, int tid, int lane, int wave, int G, int bx, int vcu) {
;     ...
;   } else if (ph == 20) {
;     const float* gf = a.in[31]; f32x4 gfv[4];
; #pragma unroll
;     for (int j = 0; j < 4; ++j) gfv[j] = *(const f32x4*)(gf + lane * 4 + 256 * j);
;     constexpr int NP = 16 * NLAT / 2;
;     ...
;     if (gw < NP) { u32x2 WA[8], WB[8]; FN_LOAD(WA, gw);
.LBB0_2398:
	s_cmp_gt_i32 s94, 20
	s_cselect_b64 s[0:1], -1, 0
	s_cmp_lt_i32 s95, 21
	s_cselect_b64 s[2:3], -1, 0
	s_or_b64 s[0:1], s[0:1], s[2:3]
	s_and_b64 vcc, exec, s[0:1]
	s_cbranch_vccnz .LBB0_2410
	s_lshl_b32 s0, s92, 3
	s_waitcnt lgkmcnt(0)
	s_add_i32 s19, s0, s93
	s_cmpk_gt_i32 s19, 0x3fff
	s_cbranch_scc1 .LBB0_2410
	s_add_u32 s0, s26, 0x4f00000
	s_addc_u32 s1, s27, 0
	s_ashr_i32 s2, s19, 10
	s_lshl_b32 s4, s19, 1
	s_lshl_b32 s5, s33, 3
	s_mul_hi_i32 s3, s2, 0x900
	s_mulk_i32 s2, 0x900
	s_and_b32 s4, s4, 0x7fe
	s_add_u32 s2, s2, s4
	s_addc_u32 s3, s3, 0
	s_lshl_b64 s[2:3], s[2:3], 11
	v_lshlrev_b32_e32 v16, 4, v254
	s_add_u32 s2, s0, s2
	s_waitcnt vmcnt(0)
	v_mov_b32_e32 v17, 0
	global_load_dwordx4 v[0:3], v16, s[90:91] nt
	global_load_dwordx4 v[4:7], v16, s[90:91] offset:1024 nt
	global_load_dwordx4 v[8:11], v16, s[90:91] offset:2048 nt
	global_load_dwordx4 v[12:15], v16, s[90:91] offset:3072 nt
	s_addc_u32 s3, s1, s3
	v_lshlrev_b32_e32 v16, 3, v254
	v_lshl_add_u64 v[18:19], s[2:3], 0, v[16:17]
	s_mov_b64 s[2:3], 0x80000
	s_mov_b32 s4, 0x80000
	v_lshl_add_u64 v[36:37], v[18:19], 0, s[2:3]
	v_add_co_u32_e32 v18, vcc, s4, v18
	s_lshl_b32 s14, s33, 5
	s_nop 0
	v_addc_co_u32_e32 v19, vcc, 0, v19, vcc
	global_load_dwordx2 v[20:21], v[36:37], off offset:512 nt
	global_load_dwordx2 v[24:25], v[36:37], off offset:1024 nt
	global_load_dwordx2 v[26:27], v[36:37], off offset:1536 nt
	global_load_dwordx2 v[22:23], v[36:37], off offset:2048 nt
	global_load_dwordx2 v[28:29], v[18:19], off nt
	global_load_dwordx2 v[30:31], v[36:37], off offset:2560 nt
	global_load_dwordx2 v[32:33], v[36:37], off offset:3072 nt
	global_load_dwordx2 v[34:35], v[36:37], off offset:3584 nt
	v_mbcnt_lo_u32_b32 v19, -1, 0
	v_mbcnt_hi_u32_b32 v36, -1, v19
	v_and_b32_e32 v19, 64, v36
	v_add_u32_e32 v37, 64, v19
	v_xor_b32_e32 v19, 1, v36
	v_cmp_lt_i32_e32 vcc, v19, v37
	v_xor_b32_e32 v38, 2, v36
	v_lshlrev_b32_e32 v18, 2, v254
	v_cndmask_b32_e32 v19, v36, v19, vcc
	v_cmp_lt_i32_e32 vcc, v38, v37
	v_lshlrev_b32_e32 v19, 2, v19
	s_lshl_b32 s15, s33, 4
	v_cndmask_b32_e32 v38, v36, v38, vcc
	v_lshlrev_b32_e32 v39, 2, v38
	v_xor_b32_e32 v38, 4, v36
	v_cmp_lt_i32_e32 vcc, v38, v37
	s_mov_b32 s4, 0x3a800000
	s_mov_b32 s16, 0x800000
	v_cndmask_b32_e32 v38, v36, v38, vcc
	v_lshlrev_b32_e32 v56, 2, v38
	v_xor_b32_e32 v38, 8, v36
	v_cmp_lt_i32_e32 vcc, v38, v37
	s_mov_b64 s[6:7], 0x1000
	s_movk_i32 s17, 0x1000
	v_cndmask_b32_e32 v38, v36, v38, vcc
	v_lshlrev_b32_e32 v57, 2, v38
	v_xor_b32_e32 v38, 16, v36
	v_cmp_lt_i32_e32 vcc, v38, v37
	v_mov_b32_e32 v42, v17
	v_mov_b32_e32 v43, v17
	v_cndmask_b32_e32 v38, v36, v38, vcc
	v_lshlrev_b32_e32 v58, 2, v38
	v_xor_b32_e32 v38, 32, v36
	v_cmp_lt_i32_e32 vcc, v38, v37
	v_mov_b32_e32 v40, v17
	v_mov_b32_e32 v41, v17
	v_cndmask_b32_e32 v36, v36, v38, vcc
	v_lshlrev_b32_e32 v59, 2, v36
	v_lshl_add_u64 v[36:37], s[0:1], 0, v[16:17]
	s_lshl_b32 s0, s92, 4
	s_lshl_b32 s1, s93, 1
	s_add_i32 s8, s0, s1
	v_mov_b32_e32 v38, 0x358637bd
	v_mov_b32_e32 v44, v17
	v_mov_b32_e32 v45, v17
	v_mov_b32_e32 v48, v17
	v_mov_b32_e32 v49, v17
	v_mov_b32_e32 v46, v17
	v_mov_b32_e32 v47, v17
	v_mov_b32_e32 v50, v17
	v_mov_b32_e32 v51, v17
	v_mov_b32_e32 v52, v17
	v_mov_b32_e32 v53, v17
	v_mov_b32_e32 v54, v17
	v_mov_b32_e32 v55, v17
	s_branch .LBB0_2403

; #define FN_LOAD(W, k) do { const int row_ = 2 * (k); const bf16_t* hr_ = HB + ((size_t)(row_ >> 11) * RB + NCTX + (row_ & 2047)) * 1024; \
;       _Pragma("unroll") for (int j = 0; j < 4; ++j) { W[j] = *(const u32x2*)(hr_ + lane * 4 + 256 * j); W[4 + j] = *(const u32x2*)(hr_ + 1024 + lane * 4 + 256 * j); } } while (0)
; template <int ph> __device__ __forceinline__ void run_phase(const MArgs& a, unsigned char* lds, int tid, int lane, int wave, int G, int bx, int vcu) {
;     ...
;       for (int k = gw; k < NP; k += 2 * NGW) { const int k1 = k + NGW, k2 = k + 2 * NGW;
;         if (k1 < NP) FN_LOAD(WB, k1);
.LBB0_2403:
	s_add_i32 s18, s19, s5
	s_cmpk_lt_i32 s18, 0x4000
	s_cselect_b64 s[10:11], -1, 0
	s_cmpk_gt_i32 s18, 0x3fff
	s_cbranch_scc1 .LBB0_2405
	s_add_i32 s0, s15, s8
	s_ashr_i32 s1, s18, 10
	s_mul_hi_i32 s9, s1, 0x900
	s_mulk_i32 s1, 0x900
	s_and_b32 s0, s0, 0x7fe
	s_add_u32 s0, s1, s0
	s_addc_u32 s1, s9, 0
	s_lshl_b64 s[0:1], s[0:1], 11
	v_lshl_add_u64 v[40:41], v[36:37], 0, s[0:1]
	v_lshl_add_u64 v[60:61], v[40:41], 0, s[2:3]
	v_add_co_u32_e32 v62, vcc, 0x80000, v40
	s_nop 1
	v_addc_co_u32_e32 v63, vcc, 0, v41, vcc
	global_load_dwordx2 v[46:47], v[60:61], off offset:2048 nt
	global_load_dwordx2 v[40:41], v[60:61], off offset:512 nt
	global_load_dwordx2 v[44:45], v[60:61], off offset:1024 nt
	global_load_dwordx2 v[48:49], v[60:61], off offset:1536 nt
	global_load_dwordx2 v[42:43], v[62:63], off nt
	global_load_dwordx2 v[50:51], v[60:61], off offset:2560 nt
	global_load_dwordx2 v[52:53], v[60:61], off offset:3072 nt
	global_load_dwordx2 v[54:55], v[60:61], off offset:3584 nt

; #define FN_LOAD(W, k) do { const int row_ = 2 * (k); const bf16_t* hr_ = HB + ((size_t)(row_ >> 11) * RB + NCTX + (row_ & 2047)) * 1024; \
;       _Pragma("unroll") for (int j = 0; j < 4; ++j) { W[j] = *(const u32x2*)(hr_ + lane * 4 + 256 * j); W[4 + j] = *(const u32x2*)(hr_ + 1024 + lane * 4 + 256 * j); } } while (0)
; template <int ph> __device__ __forceinline__ void run_phase(const MArgs& a, unsigned char* lds, int tid, int lane, int wave, int G, int bx, int vcu) {
;     ...
;         if (k2 < NP) FN_LOAD(WA, k2);
.LBB0_2408:
	s_andn2_b64 vcc, exec, s[0:1]
	s_cbranch_vccnz .LBB0_2401
	s_add_i32 s10, s14, s8
	s_ashr_i32 s0, s9, 10
	s_mul_hi_i32 s1, s0, 0x900
	s_mulk_i32 s0, 0x900
	s_and_b32 s9, s10, 0x7fe
	s_add_u32 s0, s0, s9
	s_addc_u32 s1, s1, 0
	s_lshl_b64 s[0:1], s[0:1], 11
	v_lshl_add_u64 v[20:21], v[36:37], 0, s[0:1]
	v_lshl_add_u64 v[60:61], v[20:21], 0, s[2:3]
	v_add_co_u32_e32 v62, vcc, 0x80000, v20
	s_nop 1
	v_addc_co_u32_e32 v63, vcc, 0, v21, vcc
	global_load_dwordx2 v[22:23], v[60:61], off offset:2048 nt
	global_load_dwordx2 v[20:21], v[60:61], off offset:512 nt
	global_load_dwordx2 v[24:25], v[60:61], off offset:1024 nt
	global_load_dwordx2 v[26:27], v[60:61], off offset:1536 nt
	global_load_dwordx2 v[28:29], v[62:63], off nt
	global_load_dwordx2 v[30:31], v[60:61], off offset:2560 nt
	global_load_dwordx2 v[32:33], v[60:61], off offset:3072 nt
	global_load_dwordx2 v[34:35], v[60:61], off offset:3584 nt
	s_branch .LBB0_2401
